# S5 chunk-scan phases rewritten by hand: 4 tasks x 4 steps as the 16 MFMA rows, complex recurrence in registers (no LDS transposition), C x via permuted-K LDS tile
# speedup vs baseline: 1.0235x; 1.0183x over previous
; __device__ __forceinline__ bf16x8 pack8(const float (&f)[8]) { u32x4 h; h.x = pk2(f[0], f[1]); h.y = pk2(f[2], f[3]); h.z = pk2(f[4], f[5]); h.w = pk2(f[6], f[7]); return __builtin_bit_cast(bf16x8, h); }
;     __device__ __forceinline__ bf16* R(int i) const { return (bf16*)(ws + OFF_R0 + (size_t)i * RSZ); }
; template <bool FINAL> __device__ __forceinline__ void phase_s5_scan(const Fr& F) {
;     const bf16* U = F.R(1); float* E = (float*)F.R(6);
;     float* BUl = (float*)(F.lds + F.wave * 16384);
;     const int lane = F.lane, l15 = lane & 15, lq = lane >> 4;
;     const float* BBf = (const float*)(F.ws + OFF_BB);
;     const int sg = F.gw >> 4, g = sg & 63, s = sg >> 6;
;     const f32x4 av = *(const f32x4*)((const float*)(F.ws + OFF_S5A) + (sg * 64 + lane) * 4);
;     const float ar = av.x, ai = av.y;
;     bf16x8 B1[8];
; #pragma unroll
;     for (int nt = 0; nt < 8; ++nt) {
;         const int n = 16 * nt + l15; const float* bp = BBf + (size_t)(sg * 64 + (n & 63)) * 32 + 16 * (n >> 6) + 8 * (lq & 1);
;         const f32x4 t0 = *(const f32x4*)bp, t1 = *(const f32x4*)(bp + 4); const float f[8] = {t0.x, t0.y, t0.z, t0.w, t1.x, t1.y, t1.z, t1.w};
;         B1[nt] = lq < 2 ? pack8(f) : (bf16x8){0, 0, 0, 0, 0, 0, 0, 0};
;     }
;     bf16x8 Chi[4];
;     if (FINAL) {
; #pragma unroll
;         for (int ks = 0; ks < 4; ++ks) {
;             const int k = 32 * ks + 8 * lq; const float* cp = (k < 64 ? F.a->in[32] : F.a->in[33]) + (size_t)g * 1024 + l15 * 64 + (k & 63); const float sg_ = k < 64 ? 1.f : -1.f;
;             const f32x4 t0 = *(const f32x4*)cp, t1 = *(const f32x4*)(cp + 4); const float f[8] = {sg_ * t0.x, sg_ * t0.y, sg_ * t0.z, sg_ * t0.w, sg_ * t1.x, sg_ * t1.y, sg_ * t1.z, sg_ * t1.w};
;             Chi[ks] = pack8(f);
;         }
;     }
;     u32x4 ua[4]; float e0 = 0.f, e1 = 0.f;
;     {   const int ti = F.gw & 15, b = ti / 68, chunk = ti - b * 68;
; #pragma unroll
;         for (int sb = 0; sb < 4; ++sb) ua[sb] = lq < 2 ? *(const u32x4*)(U + ((size_t)b * TB + tokof(s, chunk * 64 + sb * 16 + l15)) * D + g * 16 + 8 * lq) : (u32x4){0u, 0u, 0u, 0u};
;         if (FINAL) { const float* e = E + ((size_t)(((s * 4 + b) * 64 + g) * 68 + chunk) * 64 + lane) * 2; e0 = e[0]; e1 = e[1]; } }
.LBB0_1558:
	s_cmp_lt_i32 s34, 16
	s_cselect_b64 s[10:11], -1, 0
	s_cmp_gt_i32 s35, 15
	s_cselect_b64 s[6:7], -1, 0
	s_and_b64 s[6:7], s[10:11], s[6:7]
	s_andn2_b64 vcc, exec, s[6:7]
	v_cmp_gt_u32_e64 s[6:7], 32, v130
	s_cbranch_vccnz .LBB0_1604
	s_lshr_b32 s3, s36, 4
	s_and_b32 s8, s3, 63
	s_lshr_b32 s9, s3, 6
	s_and_b32 s55, s36, 15
	s_cmp_lt_u32 s55, 4
	s_cselect_b32 s56, 5, 4
	v_and_b32_e32 v236, 15, v130
	v_lshrrev_b32_e32 v237, 4, v130
	s_add_u32 s42, s26, 0x100000
	s_addc_u32 s43, s27, 0
	s_add_u32 s44, s26, 0x40000
	s_addc_u32 s45, s27, 0
	s_add_u32 s20, s26, 0x3400000
	s_addc_u32 s21, s27, 0
	s_add_u32 s22, s26, 0xde00000
	s_addc_u32 s23, s27, 0
	s_lshl_b32 s15, s3, 6
	v_add_u32_e32 v216, s15, v236
	v_and_b32_e32 v217, 1, v237
	v_lshlrev_b32_e32 v217, 5, v217
	v_lshl_add_u32 v218, v216, 7, v217
	v_add_u32_e32 v219, 0x1000, v218
	global_load_dwordx4 v[56:59], v218, s[42:43] offset:0
	global_load_dwordx4 v[60:63], v218, s[42:43] offset:16
	global_load_dwordx4 v[64:67], v218, s[42:43] offset:2048
	global_load_dwordx4 v[68:71], v218, s[42:43] offset:2064
	global_load_dwordx4 v[72:75], v219, s[42:43] offset:0
	global_load_dwordx4 v[76:79], v219, s[42:43] offset:16
	global_load_dwordx4 v[80:83], v219, s[42:43] offset:2048
	global_load_dwordx4 v[84:87], v219, s[42:43] offset:2064
	global_load_dwordx4 v[88:91], v218, s[42:43] offset:64
	global_load_dwordx4 v[92:95], v218, s[42:43] offset:80
	global_load_dwordx4 v[96:99], v218, s[42:43] offset:2112
	global_load_dwordx4 v[100:103], v218, s[42:43] offset:2128
	global_load_dwordx4 v[104:107], v219, s[42:43] offset:64
	global_load_dwordx4 v[108:111], v219, s[42:43] offset:80
	global_load_dwordx4 v[112:115], v219, s[42:43] offset:2112
	global_load_dwordx4 v[116:119], v219, s[42:43] offset:2128
	v_lshlrev_b32_e32 v220, 4, v216
	global_load_dwordx2 v[32:33], v220, s[44:45] offset:0
	global_load_dwordx2 v[34:35], v220, s[44:45] offset:256
	global_load_dwordx2 v[36:37], v220, s[44:45] offset:512
	global_load_dwordx2 v[38:39], v220, s[44:45] offset:768
	s_waitcnt vmcnt(0)
	v_cmp_gt_u32_e32 vcc, 2, v237
	v_cvt_pk_bf16_f32 v0, v56, v57
	v_cvt_pk_bf16_f32 v1, v58, v59
	v_cvt_pk_bf16_f32 v2, v60, v61
	v_cvt_pk_bf16_f32 v3, v62, v63
	v_cvt_pk_bf16_f32 v4, v64, v65
	v_cvt_pk_bf16_f32 v5, v66, v67
	v_cvt_pk_bf16_f32 v6, v68, v69
	v_cvt_pk_bf16_f32 v7, v70, v71
	v_cvt_pk_bf16_f32 v8, v72, v73
	v_cvt_pk_bf16_f32 v9, v74, v75
	v_cvt_pk_bf16_f32 v10, v76, v77
	v_cvt_pk_bf16_f32 v11, v78, v79
	v_cvt_pk_bf16_f32 v12, v80, v81
	v_cvt_pk_bf16_f32 v13, v82, v83
	v_cvt_pk_bf16_f32 v14, v84, v85
	v_cvt_pk_bf16_f32 v15, v86, v87
	v_cvt_pk_bf16_f32 v16, v88, v89
	v_cvt_pk_bf16_f32 v17, v90, v91
	v_cvt_pk_bf16_f32 v18, v92, v93
	v_cvt_pk_bf16_f32 v19, v94, v95
	v_cvt_pk_bf16_f32 v20, v96, v97
	v_cvt_pk_bf16_f32 v21, v98, v99
	v_cvt_pk_bf16_f32 v22, v100, v101
	v_cvt_pk_bf16_f32 v23, v102, v103
	v_cvt_pk_bf16_f32 v24, v104, v105
	v_cvt_pk_bf16_f32 v25, v106, v107
	v_cvt_pk_bf16_f32 v26, v108, v109
	v_cvt_pk_bf16_f32 v27, v110, v111
	v_cvt_pk_bf16_f32 v28, v112, v113
	v_cvt_pk_bf16_f32 v29, v114, v115
	v_cvt_pk_bf16_f32 v30, v116, v117
	v_cvt_pk_bf16_f32 v31, v118, v119
	v_cndmask_b32_e32 v0, 0, v0, vcc
	v_cndmask_b32_e32 v1, 0, v1, vcc
	v_cndmask_b32_e32 v2, 0, v2, vcc
	v_cndmask_b32_e32 v3, 0, v3, vcc
	v_cndmask_b32_e32 v4, 0, v4, vcc
	v_cndmask_b32_e32 v5, 0, v5, vcc
	v_cndmask_b32_e32 v6, 0, v6, vcc
	v_cndmask_b32_e32 v7, 0, v7, vcc
	v_cndmask_b32_e32 v8, 0, v8, vcc
	v_cndmask_b32_e32 v9, 0, v9, vcc
	v_cndmask_b32_e32 v10, 0, v10, vcc
	v_cndmask_b32_e32 v11, 0, v11, vcc
	v_cndmask_b32_e32 v12, 0, v12, vcc
	v_cndmask_b32_e32 v13, 0, v13, vcc
	v_cndmask_b32_e32 v14, 0, v14, vcc
	v_cndmask_b32_e32 v15, 0, v15, vcc
	v_cndmask_b32_e32 v16, 0, v16, vcc
	v_cndmask_b32_e32 v17, 0, v17, vcc
	v_cndmask_b32_e32 v18, 0, v18, vcc
	v_cndmask_b32_e32 v19, 0, v19, vcc
	v_cndmask_b32_e32 v20, 0, v20, vcc
	v_cndmask_b32_e32 v21, 0, v21, vcc
	v_cndmask_b32_e32 v22, 0, v22, vcc
	v_cndmask_b32_e32 v23, 0, v23, vcc
	v_cndmask_b32_e32 v24, 0, v24, vcc
	v_cndmask_b32_e32 v25, 0, v25, vcc
	v_cndmask_b32_e32 v26, 0, v26, vcc
	v_cndmask_b32_e32 v27, 0, v27, vcc
	v_cndmask_b32_e32 v28, 0, v28, vcc
	v_cndmask_b32_e32 v29, 0, v29, vcc
	v_cndmask_b32_e32 v30, 0, v30, vcc
	v_cndmask_b32_e32 v31, 0, v31, vcc
	s_cmp_eq_u32 s9, 0
	s_mov_b32 s18, 0xffffe000
	s_cselect_b32 s18, 0x2000, s18
	v_mov_b32_e32 v243, s18
	s_mov_b32 s14, s55
	s_lshl_b32 s15, s14, 2
	v_lshrrev_b32_e32 v244, 2, v236
	v_add_u32_e32 v244, s15, v244
	v_mul_u32_u24_e32 v245, 0xf1, v244
	v_lshrrev_b32_e32 v245, 14, v245
	v_mul_u32_u24_e32 v232, 68, v245
	v_sub_u32_e32 v244, v244, v232
	v_and_b32_e32 v232, 3, v236
	v_lshl_add_u32 v232, v244, 6, v232
	v_mov_b32_e32 v233, 0x11ff
	v_mov_b32_e32 v234, 0xff
	v_cmp_gt_u32_e32 vcc, 4, v244
	s_nop 1
	v_cndmask_b32_e32 v233, v233, v234, vcc
	v_sub_u32_e32 v233, v233, v232
	s_cmp_eq_u32 s9, 0
	s_cselect_b64 vcc, -1, 0
	s_nop 1
	v_cndmask_b32_e32 v232, v233, v232, vcc
	v_mul_u32_u24_e32 v245, 0x1100, v245
	v_add_u32_e32 v232, v232, v245
	s_lshl_b32 s16, s8, 5
	v_and_b32_e32 v233, 1, v237
	v_lshl_add_u32 v233, v233, 4, s16
	v_lshl_add_u32 v238, v232, 11, v233
	global_load_dwordx4 v[56:59], v238, s[20:21]
	v_add_u32_e32 v238, v238, v243
	global_load_dwordx4 v[60:63], v238, s[20:21]
	v_add_u32_e32 v238, v238, v243
	global_load_dwordx4 v[64:67], v238, s[20:21]
	v_add_u32_e32 v238, v238, v243
	global_load_dwordx4 v[68:71], v238, s[20:21]
	v_add_u32_e32 v238, v238, v243
	global_load_dwordx4 v[72:75], v238, s[20:21]
	v_add_u32_e32 v238, v238, v243
	global_load_dwordx4 v[76:79], v238, s[20:21]
	v_add_u32_e32 v238, v238, v243
	global_load_dwordx4 v[80:83], v238, s[20:21]
	v_add_u32_e32 v238, v238, v243
	global_load_dwordx4 v[84:87], v238, s[20:21]
	v_add_u32_e32 v238, v238, v243
	global_load_dwordx4 v[88:91], v238, s[20:21]
	v_add_u32_e32 v238, v238, v243
	global_load_dwordx4 v[92:95], v238, s[20:21]
	v_add_u32_e32 v238, v238, v243
	global_load_dwordx4 v[96:99], v238, s[20:21]
	v_add_u32_e32 v238, v238, v243
	global_load_dwordx4 v[100:103], v238, s[20:21]
	v_add_u32_e32 v238, v238, v243
	global_load_dwordx4 v[104:107], v238, s[20:21]
	v_add_u32_e32 v238, v238, v243
	global_load_dwordx4 v[108:111], v238, s[20:21]
	v_add_u32_e32 v238, v238, v243
	global_load_dwordx4 v[112:115], v238, s[20:21]
	v_add_u32_e32 v238, v238, v243
	global_load_dwordx4 v[116:119], v238, s[20:21]
	v_add_u32_e32 v238, v238, v243
	s_mov_b32 s19, 0
;     __device__ __forceinline__ bf16* R(int i) const { return (bf16*)(ws + OFF_R0 + (size_t)i * RSZ); }
; template <bool FINAL> __device__ __forceinline__ void phase_s5_scan(const Fr& F) {
;     ...
;     for (int ti = (F.gw & 15); ti < NB * 68; ti += 16) {
;         const int b = ti / 68, chunk = ti - b * 68, sbg = (s * 4 + b) * 64 + g, task = sbg * 68 + chunk;
;         float xr = FINAL ? e0 : 0.f, xi = FINAL ? e1 : 0.f;
;         bf16* Yb = F.R(4 + s);
;         u32x4 uc[4];
; #pragma unroll
;         for (int sb = 0; sb < 4; ++sb) uc[sb] = ua[sb];
;         if (ti + 16 < NB * 68) {
;             const int tn = ti + 16, bn = tn / 68, cn = tn - bn * 68;
; #pragma unroll
;             for (int sb = 0; sb < 4; ++sb) ua[sb] = lq < 2 ? *(const u32x4*)(U + ((size_t)bn * TB + tokof(s, cn * 64 + sb * 16 + l15)) * D + g * 16 + 8 * lq) : (u32x4){0u, 0u, 0u, 0u};
;             if (FINAL) { const float* e = E + ((size_t)(((s * 4 + bn) * 64 + g) * 68 + cn) * 64 + lane) * 2; e0 = e[0]; e1 = e[1]; }
;         }
; #pragma unroll
;         for (int sub = 0; sub < 4; ++sub) {
;             const bf16x8 A1 = __builtin_bit_cast(bf16x8, uc[sub]);
; #pragma unroll
;             for (int nt = 0; nt < 8; ++nt) {
;                 f32x4 acc = {0.f, 0.f, 0.f, 0.f};
;                 acc = __builtin_amdgcn_mfma_f32_16x16x32_bf16(A1, B1[nt], acc, 0, 0, 0);
; #pragma unroll
;                 for (int reg = 0; reg < 4; ++reg) BUl[(4 * lq + reg) * 132 + 16 * nt + l15] = acc[reg];
;             }
;             asm volatile("s_waitcnt lgkmcnt(0)" ::: "memory");
; #pragma unroll 4
;             for (int jj = 0; jj < 16; ++jj) {
;                 const float br_ = BUl[jj * 132 + lane], bi_ = BUl[jj * 132 + 64 + lane];
;                 const float nr = ar * xr - ai * xi + br_, ni = ar * xi + ai * xr + bi_; xr = nr; xi = ni;
;                 if (FINAL) { BUl[jj * 132 + lane] = xr; BUl[jj * 132 + 64 + lane] = xi; }
.Ls5a_grp:
	s_lshl_b32 s15, s14, 2
	v_lshrrev_b32_e32 v244, 2, v236
	v_add_u32_e32 v244, s15, v244
	v_mul_u32_u24_e32 v245, 0xf1, v244
	v_lshrrev_b32_e32 v245, 14, v245
	v_mul_u32_u24_e32 v232, 68, v245
	v_sub_u32_e32 v244, v244, v232
	v_and_b32_e32 v232, 3, v236
	v_lshl_add_u32 v232, v244, 6, v232
	v_mov_b32_e32 v233, 0x11ff
	v_mov_b32_e32 v234, 0xff
	v_cmp_gt_u32_e32 vcc, 4, v244
	s_nop 1
	v_cndmask_b32_e32 v233, v233, v234, vcc
	v_sub_u32_e32 v233, v233, v232
	s_cmp_eq_u32 s9, 0
	s_cselect_b64 vcc, -1, 0
	s_nop 1
	v_cndmask_b32_e32 v232, v233, v232, vcc
	v_mul_u32_u24_e32 v245, 0x1100, v245
	v_add_u32_e32 v232, v232, v245
	s_lshl_b32 s16, s8, 5
	v_and_b32_e32 v233, 1, v237
	v_lshl_add_u32 v233, v233, 4, s16
	v_lshl_add_u32 v235, v232, 11, v233
	v_add_u32_e32 v244, s15, v237
	v_mul_u32_u24_e32 v245, 0xf1, v244
	v_lshrrev_b32_e32 v245, 14, v245
	v_mul_u32_u24_e32 v232, 68, v245
	v_sub_u32_e32 v244, v244, v232
	s_lshl_b32 s17, s9, 2
	v_add_u32_e32 v245, s17, v245
	v_lshl_add_u32 v245, v245, 6, s8
	v_mul_u32_u24_e32 v245, 68, v245
	v_add_u32_e32 v245, v245, v244
	v_lshl_add_u32 v245, v245, 6, v236
	v_lshlrev_b32_e32 v240, 3, v245
	s_add_i32 s54, s14, 16
	s_lshl_b32 s15, s54, 2
	v_lshrrev_b32_e32 v244, 2, v236
	v_add_u32_e32 v244, s15, v244
	v_mul_u32_u24_e32 v245, 0xf1, v244
	v_lshrrev_b32_e32 v245, 14, v245
	v_mul_u32_u24_e32 v232, 68, v245
	v_sub_u32_e32 v244, v244, v232
	v_and_b32_e32 v232, 3, v236
	v_lshl_add_u32 v232, v244, 6, v232
	v_mov_b32_e32 v233, 0x11ff
	v_mov_b32_e32 v234, 0xff
	v_cmp_gt_u32_e32 vcc, 4, v244
	s_nop 1
	v_cndmask_b32_e32 v233, v233, v234, vcc
	v_sub_u32_e32 v233, v233, v232
	s_cmp_eq_u32 s9, 0
	s_cselect_b64 vcc, -1, 0
	s_nop 1
	v_cndmask_b32_e32 v232, v233, v232, vcc
	v_mul_u32_u24_e32 v245, 0x1100, v245
	v_add_u32_e32 v232, v232, v245
	s_lshl_b32 s16, s8, 5
	v_and_b32_e32 v233, 1, v237
	v_lshl_add_u32 v233, v233, 4, s16
	v_lshl_add_u32 v238, v232, 11, v233
	v_mov_b32_e32 v200, 0
	v_mov_b32_e32 v201, 0
	v_mov_b32_e32 v202, 0
	v_mov_b32_e32 v203, 0
	v_mov_b32_e32 v204, 0
	v_mov_b32_e32 v205, 0
	v_mov_b32_e32 v206, 0
	v_mov_b32_e32 v207, 0
	s_waitcnt vmcnt(0)
	v_mfma_f32_16x16x32_bf16 v[136:139], v[56:59], v[0:3], 0
	v_mfma_f32_16x16x32_bf16 v[140:143], v[56:59], v[4:7], 0
	v_mfma_f32_16x16x32_bf16 v[144:147], v[56:59], v[8:11], 0
	v_mfma_f32_16x16x32_bf16 v[148:151], v[56:59], v[12:15], 0
	v_mfma_f32_16x16x32_bf16 v[152:155], v[56:59], v[16:19], 0
	v_mfma_f32_16x16x32_bf16 v[156:159], v[56:59], v[20:23], 0
	v_mfma_f32_16x16x32_bf16 v[160:163], v[56:59], v[24:27], 0
	v_mfma_f32_16x16x32_bf16 v[164:167], v[56:59], v[28:31], 0
	v_mfma_f32_16x16x32_bf16 v[168:171], v[60:63], v[0:3], 0
	v_mfma_f32_16x16x32_bf16 v[172:175], v[60:63], v[4:7], 0
	v_mfma_f32_16x16x32_bf16 v[176:179], v[60:63], v[8:11], 0
	v_mfma_f32_16x16x32_bf16 v[180:183], v[60:63], v[12:15], 0
	v_mfma_f32_16x16x32_bf16 v[184:187], v[60:63], v[16:19], 0
	v_mfma_f32_16x16x32_bf16 v[188:191], v[60:63], v[20:23], 0
	v_mfma_f32_16x16x32_bf16 v[192:195], v[60:63], v[24:27], 0
	v_mfma_f32_16x16x32_bf16 v[196:199], v[60:63], v[28:31], 0
	v_fma_f32 v208, v32, v200, v136
	v_fma_f32 v209, v32, v201, v152
	v_fma_f32 v210, v34, v202, v140
	v_fma_f32 v211, v34, v203, v156
	v_fma_f32 v212, v36, v204, v144
	v_fma_f32 v213, v36, v205, v160
	v_fma_f32 v214, v38, v206, v148
	v_fma_f32 v215, v38, v207, v164
	v_fma_f32 v208, -v33, v201, v208
	v_fma_f32 v209, v33, v200, v209
	v_fma_f32 v210, -v35, v203, v210
	v_fma_f32 v211, v35, v202, v211
	v_fma_f32 v212, -v37, v205, v212
	v_fma_f32 v213, v37, v204, v213
	v_fma_f32 v214, -v39, v207, v214
	v_fma_f32 v215, v39, v206, v215
	v_fma_f32 v200, v32, v208, v137
	v_fma_f32 v201, v32, v209, v153
	v_fma_f32 v202, v34, v210, v141
	v_fma_f32 v203, v34, v211, v157
	v_fma_f32 v204, v36, v212, v145
	v_fma_f32 v205, v36, v213, v161
	v_fma_f32 v206, v38, v214, v149
	v_fma_f32 v207, v38, v215, v165
	v_fma_f32 v200, -v33, v209, v200
	v_fma_f32 v201, v33, v208, v201
	v_fma_f32 v202, -v35, v211, v202
	v_fma_f32 v203, v35, v210, v203
	v_fma_f32 v204, -v37, v213, v204
	v_fma_f32 v205, v37, v212, v205
	v_fma_f32 v206, -v39, v215, v206
	v_fma_f32 v207, v39, v214, v207
	v_fma_f32 v208, v32, v200, v138
	v_fma_f32 v209, v32, v201, v154
	v_fma_f32 v210, v34, v202, v142
	v_fma_f32 v211, v34, v203, v158
	v_fma_f32 v212, v36, v204, v146
	v_fma_f32 v213, v36, v205, v162
	v_fma_f32 v214, v38, v206, v150
	v_fma_f32 v215, v38, v207, v166
	v_fma_f32 v208, -v33, v201, v208
	v_fma_f32 v209, v33, v200, v209
	v_fma_f32 v210, -v35, v203, v210
	v_fma_f32 v211, v35, v202, v211
	v_fma_f32 v212, -v37, v205, v212
	v_fma_f32 v213, v37, v204, v213
	v_fma_f32 v214, -v39, v207, v214
	v_fma_f32 v215, v39, v206, v215
	v_fma_f32 v200, v32, v208, v139
	v_fma_f32 v201, v32, v209, v155
	v_fma_f32 v202, v34, v210, v143
	v_fma_f32 v203, v34, v211, v159
	v_fma_f32 v204, v36, v212, v147
	v_fma_f32 v205, v36, v213, v163
	v_fma_f32 v206, v38, v214, v151
	v_fma_f32 v207, v38, v215, v167
	v_fma_f32 v200, -v33, v209, v200
	v_fma_f32 v201, v33, v208, v201
	v_fma_f32 v202, -v35, v211, v202
	v_fma_f32 v203, v35, v210, v203
	v_fma_f32 v204, -v37, v213, v204
	v_fma_f32 v205, v37, v212, v205
	v_fma_f32 v206, -v39, v215, v206
	v_fma_f32 v207, v39, v214, v207
	global_load_dwordx4 v[56:59], v238, s[20:21]
	v_add_u32_e32 v238, v238, v243
	v_mfma_f32_16x16x32_bf16 v[136:139], v[64:67], v[0:3], 0
	v_mfma_f32_16x16x32_bf16 v[140:143], v[64:67], v[4:7], 0
	v_mfma_f32_16x16x32_bf16 v[144:147], v[64:67], v[8:11], 0
	v_mfma_f32_16x16x32_bf16 v[148:151], v[64:67], v[12:15], 0
	v_mfma_f32_16x16x32_bf16 v[152:155], v[64:67], v[16:19], 0
	v_mfma_f32_16x16x32_bf16 v[156:159], v[64:67], v[20:23], 0
; template <bool FINAL> __device__ __forceinline__ void phase_s5_scan(const Fr& F) {
;     ...
;         for (int sub = 0; sub < 4; ++sub) {
;             const bf16x8 A1 = __builtin_bit_cast(bf16x8, uc[sub]);
; #pragma unroll
;             for (int nt = 0; nt < 8; ++nt) {
;                 f32x4 acc = {0.f, 0.f, 0.f, 0.f};
;                 acc = __builtin_amdgcn_mfma_f32_16x16x32_bf16(A1, B1[nt], acc, 0, 0, 0);
; #pragma unroll
;                 for (int reg = 0; reg < 4; ++reg) BUl[(4 * lq + reg) * 132 + 16 * nt + l15] = acc[reg];
;             }
;             asm volatile("s_waitcnt lgkmcnt(0)" ::: "memory");
; #pragma unroll 4
;             for (int jj = 0; jj < 16; ++jj) {
;                 const float br_ = BUl[jj * 132 + lane], bi_ = BUl[jj * 132 + 64 + lane];
;                 const float nr = ar * xr - ai * xi + br_, ni = ar * xi + ai * xr + bi_; xr = nr; xi = ni;
	v_mfma_f32_16x16x32_bf16 v[160:163], v[64:67], v[24:27], 0
	v_mfma_f32_16x16x32_bf16 v[164:167], v[64:67], v[28:31], 0
	v_fma_f32 v208, v32, v200, v168
	v_fma_f32 v209, v32, v201, v184
	v_fma_f32 v210, v34, v202, v172
	v_fma_f32 v211, v34, v203, v188
	v_fma_f32 v212, v36, v204, v176
	v_fma_f32 v213, v36, v205, v192
	v_fma_f32 v214, v38, v206, v180
	v_fma_f32 v215, v38, v207, v196
	v_fma_f32 v208, -v33, v201, v208
	v_fma_f32 v209, v33, v200, v209
	v_fma_f32 v210, -v35, v203, v210
	v_fma_f32 v211, v35, v202, v211
	v_fma_f32 v212, -v37, v205, v212
	v_fma_f32 v213, v37, v204, v213
	v_fma_f32 v214, -v39, v207, v214
	v_fma_f32 v215, v39, v206, v215
	v_fma_f32 v200, v32, v208, v169
	v_fma_f32 v201, v32, v209, v185
	v_fma_f32 v202, v34, v210, v173
	v_fma_f32 v203, v34, v211, v189
	v_fma_f32 v204, v36, v212, v177
	v_fma_f32 v205, v36, v213, v193
	v_fma_f32 v206, v38, v214, v181
	v_fma_f32 v207, v38, v215, v197
	v_fma_f32 v200, -v33, v209, v200
	v_fma_f32 v201, v33, v208, v201
	v_fma_f32 v202, -v35, v211, v202
	v_fma_f32 v203, v35, v210, v203
	v_fma_f32 v204, -v37, v213, v204
	v_fma_f32 v205, v37, v212, v205
	v_fma_f32 v206, -v39, v215, v206
	v_fma_f32 v207, v39, v214, v207
	v_fma_f32 v208, v32, v200, v170
	v_fma_f32 v209, v32, v201, v186
	v_fma_f32 v210, v34, v202, v174
	v_fma_f32 v211, v34, v203, v190
	v_fma_f32 v212, v36, v204, v178
	v_fma_f32 v213, v36, v205, v194
	v_fma_f32 v214, v38, v206, v182
	v_fma_f32 v215, v38, v207, v198
	v_fma_f32 v208, -v33, v201, v208
	v_fma_f32 v209, v33, v200, v209
	v_fma_f32 v210, -v35, v203, v210
	v_fma_f32 v211, v35, v202, v211
	v_fma_f32 v212, -v37, v205, v212
	v_fma_f32 v213, v37, v204, v213
	v_fma_f32 v214, -v39, v207, v214
	v_fma_f32 v215, v39, v206, v215
	v_fma_f32 v200, v32, v208, v171
	v_fma_f32 v201, v32, v209, v187
	v_fma_f32 v202, v34, v210, v175
	v_fma_f32 v203, v34, v211, v191
	v_fma_f32 v204, v36, v212, v179
	v_fma_f32 v205, v36, v213, v195
	v_fma_f32 v206, v38, v214, v183
	v_fma_f32 v207, v38, v215, v199
	v_fma_f32 v200, -v33, v209, v200
	v_fma_f32 v201, v33, v208, v201
	v_fma_f32 v202, -v35, v211, v202
	v_fma_f32 v203, v35, v210, v203
	v_fma_f32 v204, -v37, v213, v204
	v_fma_f32 v205, v37, v212, v205
	v_fma_f32 v206, -v39, v215, v206
	v_fma_f32 v207, v39, v214, v207
	global_load_dwordx4 v[60:63], v238, s[20:21]
	v_add_u32_e32 v238, v238, v243
	v_mfma_f32_16x16x32_bf16 v[168:171], v[68:71], v[0:3], 0
	v_mfma_f32_16x16x32_bf16 v[172:175], v[68:71], v[4:7], 0
	v_mfma_f32_16x16x32_bf16 v[176:179], v[68:71], v[8:11], 0
	v_mfma_f32_16x16x32_bf16 v[180:183], v[68:71], v[12:15], 0
	v_mfma_f32_16x16x32_bf16 v[184:187], v[68:71], v[16:19], 0
	v_mfma_f32_16x16x32_bf16 v[188:191], v[68:71], v[20:23], 0
	v_mfma_f32_16x16x32_bf16 v[192:195], v[68:71], v[24:27], 0
	v_mfma_f32_16x16x32_bf16 v[196:199], v[68:71], v[28:31], 0
	v_fma_f32 v208, v32, v200, v136
	v_fma_f32 v209, v32, v201, v152
	v_fma_f32 v210, v34, v202, v140
	v_fma_f32 v211, v34, v203, v156
	v_fma_f32 v212, v36, v204, v144
	v_fma_f32 v213, v36, v205, v160
	v_fma_f32 v214, v38, v206, v148
	v_fma_f32 v215, v38, v207, v164
	v_fma_f32 v208, -v33, v201, v208
	v_fma_f32 v209, v33, v200, v209
	v_fma_f32 v210, -v35, v203, v210
	v_fma_f32 v211, v35, v202, v211
	v_fma_f32 v212, -v37, v205, v212
	v_fma_f32 v213, v37, v204, v213
	v_fma_f32 v214, -v39, v207, v214
	v_fma_f32 v215, v39, v206, v215
	v_fma_f32 v200, v32, v208, v137
	v_fma_f32 v201, v32, v209, v153
	v_fma_f32 v202, v34, v210, v141
	v_fma_f32 v203, v34, v211, v157
	v_fma_f32 v204, v36, v212, v145
	v_fma_f32 v205, v36, v213, v161
	v_fma_f32 v206, v38, v214, v149
	v_fma_f32 v207, v38, v215, v165
	v_fma_f32 v200, -v33, v209, v200
	v_fma_f32 v201, v33, v208, v201
	v_fma_f32 v202, -v35, v211, v202
	v_fma_f32 v203, v35, v210, v203
	v_fma_f32 v204, -v37, v213, v204
	v_fma_f32 v205, v37, v212, v205
	v_fma_f32 v206, -v39, v215, v206
	v_fma_f32 v207, v39, v214, v207
	v_fma_f32 v208, v32, v200, v138
	v_fma_f32 v209, v32, v201, v154
	v_fma_f32 v210, v34, v202, v142
	v_fma_f32 v211, v34, v203, v158
	v_fma_f32 v212, v36, v204, v146
	v_fma_f32 v213, v36, v205, v162
	v_fma_f32 v214, v38, v206, v150
	v_fma_f32 v215, v38, v207, v166
	v_fma_f32 v208, -v33, v201, v208
	v_fma_f32 v209, v33, v200, v209
	v_fma_f32 v210, -v35, v203, v210
	v_fma_f32 v211, v35, v202, v211
	v_fma_f32 v212, -v37, v205, v212
	v_fma_f32 v213, v37, v204, v213
	v_fma_f32 v214, -v39, v207, v214
	v_fma_f32 v215, v39, v206, v215
	v_fma_f32 v200, v32, v208, v139
	v_fma_f32 v201, v32, v209, v155
	v_fma_f32 v202, v34, v210, v143
	v_fma_f32 v203, v34, v211, v159
	v_fma_f32 v204, v36, v212, v147
	v_fma_f32 v205, v36, v213, v163
	v_fma_f32 v206, v38, v214, v151
	v_fma_f32 v207, v38, v215, v167
	v_fma_f32 v200, -v33, v209, v200
	v_fma_f32 v201, v33, v208, v201
	v_fma_f32 v202, -v35, v211, v202
	v_fma_f32 v203, v35, v210, v203
	v_fma_f32 v204, -v37, v213, v204
	v_fma_f32 v205, v37, v212, v205
	v_fma_f32 v206, -v39, v215, v206
	v_fma_f32 v207, v39, v214, v207
	global_load_dwordx4 v[64:67], v238, s[20:21]
	v_add_u32_e32 v238, v238, v243
	v_mfma_f32_16x16x32_bf16 v[136:139], v[72:75], v[0:3], 0
	v_mfma_f32_16x16x32_bf16 v[140:143], v[72:75], v[4:7], 0
	v_mfma_f32_16x16x32_bf16 v[144:147], v[72:75], v[8:11], 0
	v_mfma_f32_16x16x32_bf16 v[148:151], v[72:75], v[12:15], 0
	v_mfma_f32_16x16x32_bf16 v[152:155], v[72:75], v[16:19], 0
	v_mfma_f32_16x16x32_bf16 v[156:159], v[72:75], v[20:23], 0
	v_mfma_f32_16x16x32_bf16 v[160:163], v[72:75], v[24:27], 0
	v_mfma_f32_16x16x32_bf16 v[164:167], v[72:75], v[28:31], 0
	v_fma_f32 v208, v32, v200, v168
	v_fma_f32 v209, v32, v201, v184
	v_fma_f32 v210, v34, v202, v172
	v_fma_f32 v211, v34, v203, v188
	v_fma_f32 v212, v36, v204, v176
; template <bool FINAL> __device__ __forceinline__ void phase_s5_scan(const Fr& F) {
;     ...
;         for (int sub = 0; sub < 4; ++sub) {
;             const bf16x8 A1 = __builtin_bit_cast(bf16x8, uc[sub]);
; #pragma unroll
;             for (int nt = 0; nt < 8; ++nt) {
;                 f32x4 acc = {0.f, 0.f, 0.f, 0.f};
;                 acc = __builtin_amdgcn_mfma_f32_16x16x32_bf16(A1, B1[nt], acc, 0, 0, 0);
; #pragma unroll
;                 for (int reg = 0; reg < 4; ++reg) BUl[(4 * lq + reg) * 132 + 16 * nt + l15] = acc[reg];
;             }
;             asm volatile("s_waitcnt lgkmcnt(0)" ::: "memory");
; #pragma unroll 4
;             for (int jj = 0; jj < 16; ++jj) {
;                 const float br_ = BUl[jj * 132 + lane], bi_ = BUl[jj * 132 + 64 + lane];
;                 const float nr = ar * xr - ai * xi + br_, ni = ar * xi + ai * xr + bi_; xr = nr; xi = ni;
	v_fma_f32 v213, v36, v205, v192
	v_fma_f32 v214, v38, v206, v180
	v_fma_f32 v215, v38, v207, v196
	v_fma_f32 v208, -v33, v201, v208
	v_fma_f32 v209, v33, v200, v209
	v_fma_f32 v210, -v35, v203, v210
	v_fma_f32 v211, v35, v202, v211
	v_fma_f32 v212, -v37, v205, v212
	v_fma_f32 v213, v37, v204, v213
	v_fma_f32 v214, -v39, v207, v214
	v_fma_f32 v215, v39, v206, v215
	v_fma_f32 v200, v32, v208, v169
	v_fma_f32 v201, v32, v209, v185
	v_fma_f32 v202, v34, v210, v173
	v_fma_f32 v203, v34, v211, v189
	v_fma_f32 v204, v36, v212, v177
	v_fma_f32 v205, v36, v213, v193
	v_fma_f32 v206, v38, v214, v181
	v_fma_f32 v207, v38, v215, v197
	v_fma_f32 v200, -v33, v209, v200
	v_fma_f32 v201, v33, v208, v201
	v_fma_f32 v202, -v35, v211, v202
	v_fma_f32 v203, v35, v210, v203
	v_fma_f32 v204, -v37, v213, v204
	v_fma_f32 v205, v37, v212, v205
	v_fma_f32 v206, -v39, v215, v206
	v_fma_f32 v207, v39, v214, v207
	v_fma_f32 v208, v32, v200, v170
	v_fma_f32 v209, v32, v201, v186
	v_fma_f32 v210, v34, v202, v174
	v_fma_f32 v211, v34, v203, v190
	v_fma_f32 v212, v36, v204, v178
	v_fma_f32 v213, v36, v205, v194
	v_fma_f32 v214, v38, v206, v182
	v_fma_f32 v215, v38, v207, v198
	v_fma_f32 v208, -v33, v201, v208
	v_fma_f32 v209, v33, v200, v209
	v_fma_f32 v210, -v35, v203, v210
	v_fma_f32 v211, v35, v202, v211
	v_fma_f32 v212, -v37, v205, v212
	v_fma_f32 v213, v37, v204, v213
	v_fma_f32 v214, -v39, v207, v214
	v_fma_f32 v215, v39, v206, v215
	v_fma_f32 v200, v32, v208, v171
	v_fma_f32 v201, v32, v209, v187
	v_fma_f32 v202, v34, v210, v175
	v_fma_f32 v203, v34, v211, v191
	v_fma_f32 v204, v36, v212, v179
	v_fma_f32 v205, v36, v213, v195
	v_fma_f32 v206, v38, v214, v183
	v_fma_f32 v207, v38, v215, v199
	v_fma_f32 v200, -v33, v209, v200
	v_fma_f32 v201, v33, v208, v201
	v_fma_f32 v202, -v35, v211, v202
	v_fma_f32 v203, v35, v210, v203
	v_fma_f32 v204, -v37, v213, v204
	v_fma_f32 v205, v37, v212, v205
	v_fma_f32 v206, -v39, v215, v206
	v_fma_f32 v207, v39, v214, v207
	global_load_dwordx4 v[68:71], v238, s[20:21]
	v_add_u32_e32 v238, v238, v243
	v_mfma_f32_16x16x32_bf16 v[168:171], v[76:79], v[0:3], 0
	v_mfma_f32_16x16x32_bf16 v[172:175], v[76:79], v[4:7], 0
	v_mfma_f32_16x16x32_bf16 v[176:179], v[76:79], v[8:11], 0
	v_mfma_f32_16x16x32_bf16 v[180:183], v[76:79], v[12:15], 0
	v_mfma_f32_16x16x32_bf16 v[184:187], v[76:79], v[16:19], 0
	v_mfma_f32_16x16x32_bf16 v[188:191], v[76:79], v[20:23], 0
	v_mfma_f32_16x16x32_bf16 v[192:195], v[76:79], v[24:27], 0
	v_mfma_f32_16x16x32_bf16 v[196:199], v[76:79], v[28:31], 0
	v_fma_f32 v208, v32, v200, v136
	v_fma_f32 v209, v32, v201, v152
	v_fma_f32 v210, v34, v202, v140
	v_fma_f32 v211, v34, v203, v156
	v_fma_f32 v212, v36, v204, v144
	v_fma_f32 v213, v36, v205, v160
	v_fma_f32 v214, v38, v206, v148
	v_fma_f32 v215, v38, v207, v164
	v_fma_f32 v208, -v33, v201, v208
	v_fma_f32 v209, v33, v200, v209
	v_fma_f32 v210, -v35, v203, v210
	v_fma_f32 v211, v35, v202, v211
	v_fma_f32 v212, -v37, v205, v212
	v_fma_f32 v213, v37, v204, v213
	v_fma_f32 v214, -v39, v207, v214
	v_fma_f32 v215, v39, v206, v215
	v_fma_f32 v200, v32, v208, v137
	v_fma_f32 v201, v32, v209, v153
	v_fma_f32 v202, v34, v210, v141
	v_fma_f32 v203, v34, v211, v157
	v_fma_f32 v204, v36, v212, v145
	v_fma_f32 v205, v36, v213, v161
	v_fma_f32 v206, v38, v214, v149
	v_fma_f32 v207, v38, v215, v165
	v_fma_f32 v200, -v33, v209, v200
	v_fma_f32 v201, v33, v208, v201
	v_fma_f32 v202, -v35, v211, v202
	v_fma_f32 v203, v35, v210, v203
	v_fma_f32 v204, -v37, v213, v204
	v_fma_f32 v205, v37, v212, v205
	v_fma_f32 v206, -v39, v215, v206
	v_fma_f32 v207, v39, v214, v207
	v_fma_f32 v208, v32, v200, v138
	v_fma_f32 v209, v32, v201, v154
	v_fma_f32 v210, v34, v202, v142
	v_fma_f32 v211, v34, v203, v158
	v_fma_f32 v212, v36, v204, v146
	v_fma_f32 v213, v36, v205, v162
	v_fma_f32 v214, v38, v206, v150
	v_fma_f32 v215, v38, v207, v166
	v_fma_f32 v208, -v33, v201, v208
	v_fma_f32 v209, v33, v200, v209
	v_fma_f32 v210, -v35, v203, v210
	v_fma_f32 v211, v35, v202, v211
	v_fma_f32 v212, -v37, v205, v212
	v_fma_f32 v213, v37, v204, v213
	v_fma_f32 v214, -v39, v207, v214
	v_fma_f32 v215, v39, v206, v215
	v_fma_f32 v200, v32, v208, v139
	v_fma_f32 v201, v32, v209, v155
	v_fma_f32 v202, v34, v210, v143
	v_fma_f32 v203, v34, v211, v159
	v_fma_f32 v204, v36, v212, v147
	v_fma_f32 v205, v36, v213, v163
	v_fma_f32 v206, v38, v214, v151
	v_fma_f32 v207, v38, v215, v167
	v_fma_f32 v200, -v33, v209, v200
	v_fma_f32 v201, v33, v208, v201
	v_fma_f32 v202, -v35, v211, v202
	v_fma_f32 v203, v35, v210, v203
	v_fma_f32 v204, -v37, v213, v204
	v_fma_f32 v205, v37, v212, v205
	v_fma_f32 v206, -v39, v215, v206
	v_fma_f32 v207, v39, v214, v207
	global_load_dwordx4 v[72:75], v238, s[20:21]
	v_add_u32_e32 v238, v238, v243
	v_mfma_f32_16x16x32_bf16 v[136:139], v[80:83], v[0:3], 0
	v_mfma_f32_16x16x32_bf16 v[140:143], v[80:83], v[4:7], 0
	v_mfma_f32_16x16x32_bf16 v[144:147], v[80:83], v[8:11], 0
	v_mfma_f32_16x16x32_bf16 v[148:151], v[80:83], v[12:15], 0
	v_mfma_f32_16x16x32_bf16 v[152:155], v[80:83], v[16:19], 0
	v_mfma_f32_16x16x32_bf16 v[156:159], v[80:83], v[20:23], 0
	v_mfma_f32_16x16x32_bf16 v[160:163], v[80:83], v[24:27], 0
	v_mfma_f32_16x16x32_bf16 v[164:167], v[80:83], v[28:31], 0
	v_fma_f32 v208, v32, v200, v168
	v_fma_f32 v209, v32, v201, v184
	v_fma_f32 v210, v34, v202, v172
	v_fma_f32 v211, v34, v203, v188
	v_fma_f32 v212, v36, v204, v176
	v_fma_f32 v213, v36, v205, v192
	v_fma_f32 v214, v38, v206, v180
	v_fma_f32 v215, v38, v207, v196
	v_fma_f32 v208, -v33, v201, v208
	v_fma_f32 v209, v33, v200, v209
	v_fma_f32 v210, -v35, v203, v210
	v_fma_f32 v211, v35, v202, v211
	v_fma_f32 v212, -v37, v205, v212
; template <bool FINAL> __device__ __forceinline__ void phase_s5_scan(const Fr& F) {
;     ...
;         for (int sub = 0; sub < 4; ++sub) {
;             const bf16x8 A1 = __builtin_bit_cast(bf16x8, uc[sub]);
; #pragma unroll
;             for (int nt = 0; nt < 8; ++nt) {
;                 f32x4 acc = {0.f, 0.f, 0.f, 0.f};
;                 acc = __builtin_amdgcn_mfma_f32_16x16x32_bf16(A1, B1[nt], acc, 0, 0, 0);
; #pragma unroll
;                 for (int reg = 0; reg < 4; ++reg) BUl[(4 * lq + reg) * 132 + 16 * nt + l15] = acc[reg];
;             }
;             asm volatile("s_waitcnt lgkmcnt(0)" ::: "memory");
; #pragma unroll 4
;             for (int jj = 0; jj < 16; ++jj) {
;                 const float br_ = BUl[jj * 132 + lane], bi_ = BUl[jj * 132 + 64 + lane];
;                 const float nr = ar * xr - ai * xi + br_, ni = ar * xi + ai * xr + bi_; xr = nr; xi = ni;
	v_fma_f32 v213, v37, v204, v213
	v_fma_f32 v214, -v39, v207, v214
	v_fma_f32 v215, v39, v206, v215
	v_fma_f32 v200, v32, v208, v169
	v_fma_f32 v201, v32, v209, v185
	v_fma_f32 v202, v34, v210, v173
	v_fma_f32 v203, v34, v211, v189
	v_fma_f32 v204, v36, v212, v177
	v_fma_f32 v205, v36, v213, v193
	v_fma_f32 v206, v38, v214, v181
	v_fma_f32 v207, v38, v215, v197
	v_fma_f32 v200, -v33, v209, v200
	v_fma_f32 v201, v33, v208, v201
	v_fma_f32 v202, -v35, v211, v202
	v_fma_f32 v203, v35, v210, v203
	v_fma_f32 v204, -v37, v213, v204
	v_fma_f32 v205, v37, v212, v205
	v_fma_f32 v206, -v39, v215, v206
	v_fma_f32 v207, v39, v214, v207
	v_fma_f32 v208, v32, v200, v170
	v_fma_f32 v209, v32, v201, v186
	v_fma_f32 v210, v34, v202, v174
	v_fma_f32 v211, v34, v203, v190
	v_fma_f32 v212, v36, v204, v178
	v_fma_f32 v213, v36, v205, v194
	v_fma_f32 v214, v38, v206, v182
	v_fma_f32 v215, v38, v207, v198
	v_fma_f32 v208, -v33, v201, v208
	v_fma_f32 v209, v33, v200, v209
	v_fma_f32 v210, -v35, v203, v210
	v_fma_f32 v211, v35, v202, v211
	v_fma_f32 v212, -v37, v205, v212
	v_fma_f32 v213, v37, v204, v213
	v_fma_f32 v214, -v39, v207, v214
	v_fma_f32 v215, v39, v206, v215
	v_fma_f32 v200, v32, v208, v171
	v_fma_f32 v201, v32, v209, v187
	v_fma_f32 v202, v34, v210, v175
	v_fma_f32 v203, v34, v211, v191
	v_fma_f32 v204, v36, v212, v179
	v_fma_f32 v205, v36, v213, v195
	v_fma_f32 v206, v38, v214, v183
	v_fma_f32 v207, v38, v215, v199
	v_fma_f32 v200, -v33, v209, v200
	v_fma_f32 v201, v33, v208, v201
	v_fma_f32 v202, -v35, v211, v202
	v_fma_f32 v203, v35, v210, v203
	v_fma_f32 v204, -v37, v213, v204
	v_fma_f32 v205, v37, v212, v205
	v_fma_f32 v206, -v39, v215, v206
	v_fma_f32 v207, v39, v214, v207
	global_load_dwordx4 v[76:79], v238, s[20:21]
	v_add_u32_e32 v238, v238, v243
	v_mfma_f32_16x16x32_bf16 v[168:171], v[84:87], v[0:3], 0
	v_mfma_f32_16x16x32_bf16 v[172:175], v[84:87], v[4:7], 0
	v_mfma_f32_16x16x32_bf16 v[176:179], v[84:87], v[8:11], 0
	v_mfma_f32_16x16x32_bf16 v[180:183], v[84:87], v[12:15], 0
	v_mfma_f32_16x16x32_bf16 v[184:187], v[84:87], v[16:19], 0
	v_mfma_f32_16x16x32_bf16 v[188:191], v[84:87], v[20:23], 0
	v_mfma_f32_16x16x32_bf16 v[192:195], v[84:87], v[24:27], 0
	v_mfma_f32_16x16x32_bf16 v[196:199], v[84:87], v[28:31], 0
	v_fma_f32 v208, v32, v200, v136
	v_fma_f32 v209, v32, v201, v152
	v_fma_f32 v210, v34, v202, v140
	v_fma_f32 v211, v34, v203, v156
	v_fma_f32 v212, v36, v204, v144
	v_fma_f32 v213, v36, v205, v160
	v_fma_f32 v214, v38, v206, v148
	v_fma_f32 v215, v38, v207, v164
	v_fma_f32 v208, -v33, v201, v208
	v_fma_f32 v209, v33, v200, v209
	v_fma_f32 v210, -v35, v203, v210
	v_fma_f32 v211, v35, v202, v211
	v_fma_f32 v212, -v37, v205, v212
	v_fma_f32 v213, v37, v204, v213
	v_fma_f32 v214, -v39, v207, v214
	v_fma_f32 v215, v39, v206, v215
	v_fma_f32 v200, v32, v208, v137
	v_fma_f32 v201, v32, v209, v153
	v_fma_f32 v202, v34, v210, v141
	v_fma_f32 v203, v34, v211, v157
	v_fma_f32 v204, v36, v212, v145
	v_fma_f32 v205, v36, v213, v161
	v_fma_f32 v206, v38, v214, v149
	v_fma_f32 v207, v38, v215, v165
	v_fma_f32 v200, -v33, v209, v200
	v_fma_f32 v201, v33, v208, v201
	v_fma_f32 v202, -v35, v211, v202
	v_fma_f32 v203, v35, v210, v203
	v_fma_f32 v204, -v37, v213, v204
	v_fma_f32 v205, v37, v212, v205
	v_fma_f32 v206, -v39, v215, v206
	v_fma_f32 v207, v39, v214, v207
	v_fma_f32 v208, v32, v200, v138
	v_fma_f32 v209, v32, v201, v154
	v_fma_f32 v210, v34, v202, v142
	v_fma_f32 v211, v34, v203, v158
	v_fma_f32 v212, v36, v204, v146
	v_fma_f32 v213, v36, v205, v162
	v_fma_f32 v214, v38, v206, v150
	v_fma_f32 v215, v38, v207, v166
	v_fma_f32 v208, -v33, v201, v208
	v_fma_f32 v209, v33, v200, v209
	v_fma_f32 v210, -v35, v203, v210
	v_fma_f32 v211, v35, v202, v211
	v_fma_f32 v212, -v37, v205, v212
	v_fma_f32 v213, v37, v204, v213
	v_fma_f32 v214, -v39, v207, v214
	v_fma_f32 v215, v39, v206, v215
	v_fma_f32 v200, v32, v208, v139
	v_fma_f32 v201, v32, v209, v155
	v_fma_f32 v202, v34, v210, v143
	v_fma_f32 v203, v34, v211, v159
	v_fma_f32 v204, v36, v212, v147
	v_fma_f32 v205, v36, v213, v163
	v_fma_f32 v206, v38, v214, v151
	v_fma_f32 v207, v38, v215, v167
	v_fma_f32 v200, -v33, v209, v200
	v_fma_f32 v201, v33, v208, v201
	v_fma_f32 v202, -v35, v211, v202
	v_fma_f32 v203, v35, v210, v203
	v_fma_f32 v204, -v37, v213, v204
	v_fma_f32 v205, v37, v212, v205
	v_fma_f32 v206, -v39, v215, v206
	v_fma_f32 v207, v39, v214, v207
	global_load_dwordx4 v[80:83], v238, s[20:21]
	v_add_u32_e32 v238, v238, v243
	v_mfma_f32_16x16x32_bf16 v[136:139], v[88:91], v[0:3], 0
	v_mfma_f32_16x16x32_bf16 v[140:143], v[88:91], v[4:7], 0
	v_mfma_f32_16x16x32_bf16 v[144:147], v[88:91], v[8:11], 0
	v_mfma_f32_16x16x32_bf16 v[148:151], v[88:91], v[12:15], 0
	v_mfma_f32_16x16x32_bf16 v[152:155], v[88:91], v[16:19], 0
	v_mfma_f32_16x16x32_bf16 v[156:159], v[88:91], v[20:23], 0
	v_mfma_f32_16x16x32_bf16 v[160:163], v[88:91], v[24:27], 0
	v_mfma_f32_16x16x32_bf16 v[164:167], v[88:91], v[28:31], 0
	v_fma_f32 v208, v32, v200, v168
	v_fma_f32 v209, v32, v201, v184
	v_fma_f32 v210, v34, v202, v172
	v_fma_f32 v211, v34, v203, v188
	v_fma_f32 v212, v36, v204, v176
	v_fma_f32 v213, v36, v205, v192
	v_fma_f32 v214, v38, v206, v180
	v_fma_f32 v215, v38, v207, v196
	v_fma_f32 v208, -v33, v201, v208
	v_fma_f32 v209, v33, v200, v209
	v_fma_f32 v210, -v35, v203, v210
	v_fma_f32 v211, v35, v202, v211
	v_fma_f32 v212, -v37, v205, v212
	v_fma_f32 v213, v37, v204, v213
	v_fma_f32 v214, -v39, v207, v214
	v_fma_f32 v215, v39, v206, v215
	v_fma_f32 v200, v32, v208, v169
	v_fma_f32 v201, v32, v209, v185
	v_fma_f32 v202, v34, v210, v173
	v_fma_f32 v203, v34, v211, v189
	v_fma_f32 v204, v36, v212, v177
; template <bool FINAL> __device__ __forceinline__ void phase_s5_scan(const Fr& F) {
;     ...
;         for (int sub = 0; sub < 4; ++sub) {
;             const bf16x8 A1 = __builtin_bit_cast(bf16x8, uc[sub]);
; #pragma unroll
;             for (int nt = 0; nt < 8; ++nt) {
;                 f32x4 acc = {0.f, 0.f, 0.f, 0.f};
;                 acc = __builtin_amdgcn_mfma_f32_16x16x32_bf16(A1, B1[nt], acc, 0, 0, 0);
; #pragma unroll
;                 for (int reg = 0; reg < 4; ++reg) BUl[(4 * lq + reg) * 132 + 16 * nt + l15] = acc[reg];
;             }
;             asm volatile("s_waitcnt lgkmcnt(0)" ::: "memory");
; #pragma unroll 4
;             for (int jj = 0; jj < 16; ++jj) {
;                 const float br_ = BUl[jj * 132 + lane], bi_ = BUl[jj * 132 + 64 + lane];
;                 const float nr = ar * xr - ai * xi + br_, ni = ar * xi + ai * xr + bi_; xr = nr; xi = ni;
	v_fma_f32 v205, v36, v213, v193
	v_fma_f32 v206, v38, v214, v181
	v_fma_f32 v207, v38, v215, v197
	v_fma_f32 v200, -v33, v209, v200
	v_fma_f32 v201, v33, v208, v201
	v_fma_f32 v202, -v35, v211, v202
	v_fma_f32 v203, v35, v210, v203
	v_fma_f32 v204, -v37, v213, v204
	v_fma_f32 v205, v37, v212, v205
	v_fma_f32 v206, -v39, v215, v206
	v_fma_f32 v207, v39, v214, v207
	v_fma_f32 v208, v32, v200, v170
	v_fma_f32 v209, v32, v201, v186
	v_fma_f32 v210, v34, v202, v174
	v_fma_f32 v211, v34, v203, v190
	v_fma_f32 v212, v36, v204, v178
	v_fma_f32 v213, v36, v205, v194
	v_fma_f32 v214, v38, v206, v182
	v_fma_f32 v215, v38, v207, v198
	v_fma_f32 v208, -v33, v201, v208
	v_fma_f32 v209, v33, v200, v209
	v_fma_f32 v210, -v35, v203, v210
	v_fma_f32 v211, v35, v202, v211
	v_fma_f32 v212, -v37, v205, v212
	v_fma_f32 v213, v37, v204, v213
	v_fma_f32 v214, -v39, v207, v214
	v_fma_f32 v215, v39, v206, v215
	v_fma_f32 v200, v32, v208, v171
	v_fma_f32 v201, v32, v209, v187
	v_fma_f32 v202, v34, v210, v175
	v_fma_f32 v203, v34, v211, v191
	v_fma_f32 v204, v36, v212, v179
	v_fma_f32 v205, v36, v213, v195
	v_fma_f32 v206, v38, v214, v183
	v_fma_f32 v207, v38, v215, v199
	v_fma_f32 v200, -v33, v209, v200
	v_fma_f32 v201, v33, v208, v201
	v_fma_f32 v202, -v35, v211, v202
	v_fma_f32 v203, v35, v210, v203
	v_fma_f32 v204, -v37, v213, v204
	v_fma_f32 v205, v37, v212, v205
	v_fma_f32 v206, -v39, v215, v206
	v_fma_f32 v207, v39, v214, v207
	global_load_dwordx4 v[84:87], v238, s[20:21]
	v_add_u32_e32 v238, v238, v243
	v_mfma_f32_16x16x32_bf16 v[168:171], v[92:95], v[0:3], 0
	v_mfma_f32_16x16x32_bf16 v[172:175], v[92:95], v[4:7], 0
	v_mfma_f32_16x16x32_bf16 v[176:179], v[92:95], v[8:11], 0
	v_mfma_f32_16x16x32_bf16 v[180:183], v[92:95], v[12:15], 0
	v_mfma_f32_16x16x32_bf16 v[184:187], v[92:95], v[16:19], 0
	v_mfma_f32_16x16x32_bf16 v[188:191], v[92:95], v[20:23], 0
	v_mfma_f32_16x16x32_bf16 v[192:195], v[92:95], v[24:27], 0
	v_mfma_f32_16x16x32_bf16 v[196:199], v[92:95], v[28:31], 0
	v_fma_f32 v208, v32, v200, v136
	v_fma_f32 v209, v32, v201, v152
	v_fma_f32 v210, v34, v202, v140
	v_fma_f32 v211, v34, v203, v156
	v_fma_f32 v212, v36, v204, v144
	v_fma_f32 v213, v36, v205, v160
	v_fma_f32 v214, v38, v206, v148
	v_fma_f32 v215, v38, v207, v164
	v_fma_f32 v208, -v33, v201, v208
	v_fma_f32 v209, v33, v200, v209
	v_fma_f32 v210, -v35, v203, v210
	v_fma_f32 v211, v35, v202, v211
	v_fma_f32 v212, -v37, v205, v212
	v_fma_f32 v213, v37, v204, v213
	v_fma_f32 v214, -v39, v207, v214
	v_fma_f32 v215, v39, v206, v215
	v_fma_f32 v200, v32, v208, v137
	v_fma_f32 v201, v32, v209, v153
	v_fma_f32 v202, v34, v210, v141
	v_fma_f32 v203, v34, v211, v157
	v_fma_f32 v204, v36, v212, v145
	v_fma_f32 v205, v36, v213, v161
	v_fma_f32 v206, v38, v214, v149
	v_fma_f32 v207, v38, v215, v165
	v_fma_f32 v200, -v33, v209, v200
	v_fma_f32 v201, v33, v208, v201
	v_fma_f32 v202, -v35, v211, v202
	v_fma_f32 v203, v35, v210, v203
	v_fma_f32 v204, -v37, v213, v204
	v_fma_f32 v205, v37, v212, v205
	v_fma_f32 v206, -v39, v215, v206
	v_fma_f32 v207, v39, v214, v207
	v_fma_f32 v208, v32, v200, v138
	v_fma_f32 v209, v32, v201, v154
	v_fma_f32 v210, v34, v202, v142
	v_fma_f32 v211, v34, v203, v158
	v_fma_f32 v212, v36, v204, v146
	v_fma_f32 v213, v36, v205, v162
	v_fma_f32 v214, v38, v206, v150
	v_fma_f32 v215, v38, v207, v166
	v_fma_f32 v208, -v33, v201, v208
	v_fma_f32 v209, v33, v200, v209
	v_fma_f32 v210, -v35, v203, v210
	v_fma_f32 v211, v35, v202, v211
	v_fma_f32 v212, -v37, v205, v212
	v_fma_f32 v213, v37, v204, v213
	v_fma_f32 v214, -v39, v207, v214
	v_fma_f32 v215, v39, v206, v215
	v_fma_f32 v200, v32, v208, v139
	v_fma_f32 v201, v32, v209, v155
	v_fma_f32 v202, v34, v210, v143
	v_fma_f32 v203, v34, v211, v159
	v_fma_f32 v204, v36, v212, v147
	v_fma_f32 v205, v36, v213, v163
	v_fma_f32 v206, v38, v214, v151
	v_fma_f32 v207, v38, v215, v167
	v_fma_f32 v200, -v33, v209, v200
	v_fma_f32 v201, v33, v208, v201
	v_fma_f32 v202, -v35, v211, v202
	v_fma_f32 v203, v35, v210, v203
	v_fma_f32 v204, -v37, v213, v204
	v_fma_f32 v205, v37, v212, v205
	v_fma_f32 v206, -v39, v215, v206
	v_fma_f32 v207, v39, v214, v207
	global_load_dwordx4 v[88:91], v238, s[20:21]
	v_add_u32_e32 v238, v238, v243
	v_mfma_f32_16x16x32_bf16 v[136:139], v[96:99], v[0:3], 0
	v_mfma_f32_16x16x32_bf16 v[140:143], v[96:99], v[4:7], 0
	v_mfma_f32_16x16x32_bf16 v[144:147], v[96:99], v[8:11], 0
	v_mfma_f32_16x16x32_bf16 v[148:151], v[96:99], v[12:15], 0
	v_mfma_f32_16x16x32_bf16 v[152:155], v[96:99], v[16:19], 0
	v_mfma_f32_16x16x32_bf16 v[156:159], v[96:99], v[20:23], 0
	v_mfma_f32_16x16x32_bf16 v[160:163], v[96:99], v[24:27], 0
	v_mfma_f32_16x16x32_bf16 v[164:167], v[96:99], v[28:31], 0
	v_fma_f32 v208, v32, v200, v168
	v_fma_f32 v209, v32, v201, v184
	v_fma_f32 v210, v34, v202, v172
	v_fma_f32 v211, v34, v203, v188
	v_fma_f32 v212, v36, v204, v176
	v_fma_f32 v213, v36, v205, v192
	v_fma_f32 v214, v38, v206, v180
	v_fma_f32 v215, v38, v207, v196
	v_fma_f32 v208, -v33, v201, v208
	v_fma_f32 v209, v33, v200, v209
	v_fma_f32 v210, -v35, v203, v210
	v_fma_f32 v211, v35, v202, v211
	v_fma_f32 v212, -v37, v205, v212
	v_fma_f32 v213, v37, v204, v213
	v_fma_f32 v214, -v39, v207, v214
	v_fma_f32 v215, v39, v206, v215
	v_fma_f32 v200, v32, v208, v169
	v_fma_f32 v201, v32, v209, v185
	v_fma_f32 v202, v34, v210, v173
	v_fma_f32 v203, v34, v211, v189
	v_fma_f32 v204, v36, v212, v177
	v_fma_f32 v205, v36, v213, v193
	v_fma_f32 v206, v38, v214, v181
	v_fma_f32 v207, v38, v215, v197
	v_fma_f32 v200, -v33, v209, v200
	v_fma_f32 v201, v33, v208, v201
	v_fma_f32 v202, -v35, v211, v202
	v_fma_f32 v203, v35, v210, v203
	v_fma_f32 v204, -v37, v213, v204
; template <bool FINAL> __device__ __forceinline__ void phase_s5_scan(const Fr& F) {
;     ...
;         for (int sub = 0; sub < 4; ++sub) {
;             const bf16x8 A1 = __builtin_bit_cast(bf16x8, uc[sub]);
; #pragma unroll
;             for (int nt = 0; nt < 8; ++nt) {
;                 f32x4 acc = {0.f, 0.f, 0.f, 0.f};
;                 acc = __builtin_amdgcn_mfma_f32_16x16x32_bf16(A1, B1[nt], acc, 0, 0, 0);
; #pragma unroll
;                 for (int reg = 0; reg < 4; ++reg) BUl[(4 * lq + reg) * 132 + 16 * nt + l15] = acc[reg];
;             }
;             asm volatile("s_waitcnt lgkmcnt(0)" ::: "memory");
; #pragma unroll 4
;             for (int jj = 0; jj < 16; ++jj) {
;                 const float br_ = BUl[jj * 132 + lane], bi_ = BUl[jj * 132 + 64 + lane];
;                 const float nr = ar * xr - ai * xi + br_, ni = ar * xi + ai * xr + bi_; xr = nr; xi = ni;
	v_fma_f32 v205, v37, v212, v205
	v_fma_f32 v206, -v39, v215, v206
	v_fma_f32 v207, v39, v214, v207
	v_fma_f32 v208, v32, v200, v170
	v_fma_f32 v209, v32, v201, v186
	v_fma_f32 v210, v34, v202, v174
	v_fma_f32 v211, v34, v203, v190
	v_fma_f32 v212, v36, v204, v178
	v_fma_f32 v213, v36, v205, v194
	v_fma_f32 v214, v38, v206, v182
	v_fma_f32 v215, v38, v207, v198
	v_fma_f32 v208, -v33, v201, v208
	v_fma_f32 v209, v33, v200, v209
	v_fma_f32 v210, -v35, v203, v210
	v_fma_f32 v211, v35, v202, v211
	v_fma_f32 v212, -v37, v205, v212
	v_fma_f32 v213, v37, v204, v213
	v_fma_f32 v214, -v39, v207, v214
	v_fma_f32 v215, v39, v206, v215
	v_fma_f32 v200, v32, v208, v171
	v_fma_f32 v201, v32, v209, v187
	v_fma_f32 v202, v34, v210, v175
	v_fma_f32 v203, v34, v211, v191
	v_fma_f32 v204, v36, v212, v179
	v_fma_f32 v205, v36, v213, v195
	v_fma_f32 v206, v38, v214, v183
	v_fma_f32 v207, v38, v215, v199
	v_fma_f32 v200, -v33, v209, v200
	v_fma_f32 v201, v33, v208, v201
	v_fma_f32 v202, -v35, v211, v202
	v_fma_f32 v203, v35, v210, v203
	v_fma_f32 v204, -v37, v213, v204
	v_fma_f32 v205, v37, v212, v205
	v_fma_f32 v206, -v39, v215, v206
	v_fma_f32 v207, v39, v214, v207
	global_load_dwordx4 v[92:95], v238, s[20:21]
	v_add_u32_e32 v238, v238, v243
	v_mfma_f32_16x16x32_bf16 v[168:171], v[100:103], v[0:3], 0
	v_mfma_f32_16x16x32_bf16 v[172:175], v[100:103], v[4:7], 0
	v_mfma_f32_16x16x32_bf16 v[176:179], v[100:103], v[8:11], 0
	v_mfma_f32_16x16x32_bf16 v[180:183], v[100:103], v[12:15], 0
	v_mfma_f32_16x16x32_bf16 v[184:187], v[100:103], v[16:19], 0
	v_mfma_f32_16x16x32_bf16 v[188:191], v[100:103], v[20:23], 0
	v_mfma_f32_16x16x32_bf16 v[192:195], v[100:103], v[24:27], 0
	v_mfma_f32_16x16x32_bf16 v[196:199], v[100:103], v[28:31], 0
	v_fma_f32 v208, v32, v200, v136
	v_fma_f32 v209, v32, v201, v152
	v_fma_f32 v210, v34, v202, v140
	v_fma_f32 v211, v34, v203, v156
	v_fma_f32 v212, v36, v204, v144
	v_fma_f32 v213, v36, v205, v160
	v_fma_f32 v214, v38, v206, v148
	v_fma_f32 v215, v38, v207, v164
	v_fma_f32 v208, -v33, v201, v208
	v_fma_f32 v209, v33, v200, v209
	v_fma_f32 v210, -v35, v203, v210
	v_fma_f32 v211, v35, v202, v211
	v_fma_f32 v212, -v37, v205, v212
	v_fma_f32 v213, v37, v204, v213
	v_fma_f32 v214, -v39, v207, v214
	v_fma_f32 v215, v39, v206, v215
	v_fma_f32 v200, v32, v208, v137
	v_fma_f32 v201, v32, v209, v153
	v_fma_f32 v202, v34, v210, v141
	v_fma_f32 v203, v34, v211, v157
	v_fma_f32 v204, v36, v212, v145
	v_fma_f32 v205, v36, v213, v161
	v_fma_f32 v206, v38, v214, v149
	v_fma_f32 v207, v38, v215, v165
	v_fma_f32 v200, -v33, v209, v200
	v_fma_f32 v201, v33, v208, v201
	v_fma_f32 v202, -v35, v211, v202
	v_fma_f32 v203, v35, v210, v203
	v_fma_f32 v204, -v37, v213, v204
	v_fma_f32 v205, v37, v212, v205
	v_fma_f32 v206, -v39, v215, v206
	v_fma_f32 v207, v39, v214, v207
	v_fma_f32 v208, v32, v200, v138
	v_fma_f32 v209, v32, v201, v154
	v_fma_f32 v210, v34, v202, v142
	v_fma_f32 v211, v34, v203, v158
	v_fma_f32 v212, v36, v204, v146
	v_fma_f32 v213, v36, v205, v162
	v_fma_f32 v214, v38, v206, v150
	v_fma_f32 v215, v38, v207, v166
	v_fma_f32 v208, -v33, v201, v208
	v_fma_f32 v209, v33, v200, v209
	v_fma_f32 v210, -v35, v203, v210
	v_fma_f32 v211, v35, v202, v211
	v_fma_f32 v212, -v37, v205, v212
	v_fma_f32 v213, v37, v204, v213
	v_fma_f32 v214, -v39, v207, v214
	v_fma_f32 v215, v39, v206, v215
	v_fma_f32 v200, v32, v208, v139
	v_fma_f32 v201, v32, v209, v155
	v_fma_f32 v202, v34, v210, v143
	v_fma_f32 v203, v34, v211, v159
	v_fma_f32 v204, v36, v212, v147
	v_fma_f32 v205, v36, v213, v163
	v_fma_f32 v206, v38, v214, v151
	v_fma_f32 v207, v38, v215, v167
	v_fma_f32 v200, -v33, v209, v200
	v_fma_f32 v201, v33, v208, v201
	v_fma_f32 v202, -v35, v211, v202
	v_fma_f32 v203, v35, v210, v203
	v_fma_f32 v204, -v37, v213, v204
	v_fma_f32 v205, v37, v212, v205
	v_fma_f32 v206, -v39, v215, v206
	v_fma_f32 v207, v39, v214, v207
	global_load_dwordx4 v[96:99], v238, s[20:21]
	v_add_u32_e32 v238, v238, v243
	v_mfma_f32_16x16x32_bf16 v[136:139], v[104:107], v[0:3], 0
	v_mfma_f32_16x16x32_bf16 v[140:143], v[104:107], v[4:7], 0
	v_mfma_f32_16x16x32_bf16 v[144:147], v[104:107], v[8:11], 0
	v_mfma_f32_16x16x32_bf16 v[148:151], v[104:107], v[12:15], 0
	v_mfma_f32_16x16x32_bf16 v[152:155], v[104:107], v[16:19], 0
	v_mfma_f32_16x16x32_bf16 v[156:159], v[104:107], v[20:23], 0
	v_mfma_f32_16x16x32_bf16 v[160:163], v[104:107], v[24:27], 0
	v_mfma_f32_16x16x32_bf16 v[164:167], v[104:107], v[28:31], 0
	v_fma_f32 v208, v32, v200, v168
	v_fma_f32 v209, v32, v201, v184
	v_fma_f32 v210, v34, v202, v172
	v_fma_f32 v211, v34, v203, v188
	v_fma_f32 v212, v36, v204, v176
	v_fma_f32 v213, v36, v205, v192
	v_fma_f32 v214, v38, v206, v180
	v_fma_f32 v215, v38, v207, v196
	v_fma_f32 v208, -v33, v201, v208
	v_fma_f32 v209, v33, v200, v209
	v_fma_f32 v210, -v35, v203, v210
	v_fma_f32 v211, v35, v202, v211
	v_fma_f32 v212, -v37, v205, v212
	v_fma_f32 v213, v37, v204, v213
	v_fma_f32 v214, -v39, v207, v214
	v_fma_f32 v215, v39, v206, v215
	v_fma_f32 v200, v32, v208, v169
	v_fma_f32 v201, v32, v209, v185
	v_fma_f32 v202, v34, v210, v173
	v_fma_f32 v203, v34, v211, v189
	v_fma_f32 v204, v36, v212, v177
	v_fma_f32 v205, v36, v213, v193
	v_fma_f32 v206, v38, v214, v181
	v_fma_f32 v207, v38, v215, v197
	v_fma_f32 v200, -v33, v209, v200
	v_fma_f32 v201, v33, v208, v201
	v_fma_f32 v202, -v35, v211, v202
	v_fma_f32 v203, v35, v210, v203
	v_fma_f32 v204, -v37, v213, v204
	v_fma_f32 v205, v37, v212, v205
	v_fma_f32 v206, -v39, v215, v206
	v_fma_f32 v207, v39, v214, v207
	v_fma_f32 v208, v32, v200, v170
	v_fma_f32 v209, v32, v201, v186
	v_fma_f32 v210, v34, v202, v174
	v_fma_f32 v211, v34, v203, v190
; template <bool FINAL> __device__ __forceinline__ void phase_s5_scan(const Fr& F) {
;     ...
;         for (int sub = 0; sub < 4; ++sub) {
;             const bf16x8 A1 = __builtin_bit_cast(bf16x8, uc[sub]);
; #pragma unroll
;             for (int nt = 0; nt < 8; ++nt) {
;                 f32x4 acc = {0.f, 0.f, 0.f, 0.f};
;                 acc = __builtin_amdgcn_mfma_f32_16x16x32_bf16(A1, B1[nt], acc, 0, 0, 0);
; #pragma unroll
;                 for (int reg = 0; reg < 4; ++reg) BUl[(4 * lq + reg) * 132 + 16 * nt + l15] = acc[reg];
;             }
;             asm volatile("s_waitcnt lgkmcnt(0)" ::: "memory");
; #pragma unroll 4
;             for (int jj = 0; jj < 16; ++jj) {
;                 const float br_ = BUl[jj * 132 + lane], bi_ = BUl[jj * 132 + 64 + lane];
;                 const float nr = ar * xr - ai * xi + br_, ni = ar * xi + ai * xr + bi_; xr = nr; xi = ni;
	v_fma_f32 v212, v36, v204, v178
	v_fma_f32 v213, v36, v205, v194
	v_fma_f32 v214, v38, v206, v182
	v_fma_f32 v215, v38, v207, v198
	v_fma_f32 v208, -v33, v201, v208
	v_fma_f32 v209, v33, v200, v209
	v_fma_f32 v210, -v35, v203, v210
	v_fma_f32 v211, v35, v202, v211
	v_fma_f32 v212, -v37, v205, v212
	v_fma_f32 v213, v37, v204, v213
	v_fma_f32 v214, -v39, v207, v214
	v_fma_f32 v215, v39, v206, v215
	v_fma_f32 v200, v32, v208, v171
	v_fma_f32 v201, v32, v209, v187
	v_fma_f32 v202, v34, v210, v175
	v_fma_f32 v203, v34, v211, v191
	v_fma_f32 v204, v36, v212, v179
	v_fma_f32 v205, v36, v213, v195
	v_fma_f32 v206, v38, v214, v183
	v_fma_f32 v207, v38, v215, v199
	v_fma_f32 v200, -v33, v209, v200
	v_fma_f32 v201, v33, v208, v201
	v_fma_f32 v202, -v35, v211, v202
	v_fma_f32 v203, v35, v210, v203
	v_fma_f32 v204, -v37, v213, v204
	v_fma_f32 v205, v37, v212, v205
	v_fma_f32 v206, -v39, v215, v206
	v_fma_f32 v207, v39, v214, v207
	global_load_dwordx4 v[100:103], v238, s[20:21]
	v_add_u32_e32 v238, v238, v243
	v_mfma_f32_16x16x32_bf16 v[168:171], v[108:111], v[0:3], 0
	v_mfma_f32_16x16x32_bf16 v[172:175], v[108:111], v[4:7], 0
	v_mfma_f32_16x16x32_bf16 v[176:179], v[108:111], v[8:11], 0
	v_mfma_f32_16x16x32_bf16 v[180:183], v[108:111], v[12:15], 0
	v_mfma_f32_16x16x32_bf16 v[184:187], v[108:111], v[16:19], 0
	v_mfma_f32_16x16x32_bf16 v[188:191], v[108:111], v[20:23], 0
	v_mfma_f32_16x16x32_bf16 v[192:195], v[108:111], v[24:27], 0
	v_mfma_f32_16x16x32_bf16 v[196:199], v[108:111], v[28:31], 0
	v_fma_f32 v208, v32, v200, v136
	v_fma_f32 v209, v32, v201, v152
	v_fma_f32 v210, v34, v202, v140
	v_fma_f32 v211, v34, v203, v156
	v_fma_f32 v212, v36, v204, v144
	v_fma_f32 v213, v36, v205, v160
	v_fma_f32 v214, v38, v206, v148
	v_fma_f32 v215, v38, v207, v164
	v_fma_f32 v208, -v33, v201, v208
	v_fma_f32 v209, v33, v200, v209
	v_fma_f32 v210, -v35, v203, v210
	v_fma_f32 v211, v35, v202, v211
	v_fma_f32 v212, -v37, v205, v212
	v_fma_f32 v213, v37, v204, v213
	v_fma_f32 v214, -v39, v207, v214
	v_fma_f32 v215, v39, v206, v215
	v_fma_f32 v200, v32, v208, v137
	v_fma_f32 v201, v32, v209, v153
	v_fma_f32 v202, v34, v210, v141
	v_fma_f32 v203, v34, v211, v157
	v_fma_f32 v204, v36, v212, v145
	v_fma_f32 v205, v36, v213, v161
	v_fma_f32 v206, v38, v214, v149
	v_fma_f32 v207, v38, v215, v165
	v_fma_f32 v200, -v33, v209, v200
	v_fma_f32 v201, v33, v208, v201
	v_fma_f32 v202, -v35, v211, v202
	v_fma_f32 v203, v35, v210, v203
	v_fma_f32 v204, -v37, v213, v204
	v_fma_f32 v205, v37, v212, v205
	v_fma_f32 v206, -v39, v215, v206
	v_fma_f32 v207, v39, v214, v207
	v_fma_f32 v208, v32, v200, v138
	v_fma_f32 v209, v32, v201, v154
	v_fma_f32 v210, v34, v202, v142
	v_fma_f32 v211, v34, v203, v158
	v_fma_f32 v212, v36, v204, v146
	v_fma_f32 v213, v36, v205, v162
	v_fma_f32 v214, v38, v206, v150
	v_fma_f32 v215, v38, v207, v166
	v_fma_f32 v208, -v33, v201, v208
	v_fma_f32 v209, v33, v200, v209
	v_fma_f32 v210, -v35, v203, v210
	v_fma_f32 v211, v35, v202, v211
	v_fma_f32 v212, -v37, v205, v212
	v_fma_f32 v213, v37, v204, v213
	v_fma_f32 v214, -v39, v207, v214
	v_fma_f32 v215, v39, v206, v215
	v_fma_f32 v200, v32, v208, v139
	v_fma_f32 v201, v32, v209, v155
	v_fma_f32 v202, v34, v210, v143
	v_fma_f32 v203, v34, v211, v159
	v_fma_f32 v204, v36, v212, v147
	v_fma_f32 v205, v36, v213, v163
	v_fma_f32 v206, v38, v214, v151
	v_fma_f32 v207, v38, v215, v167
	v_fma_f32 v200, -v33, v209, v200
	v_fma_f32 v201, v33, v208, v201
	v_fma_f32 v202, -v35, v211, v202
	v_fma_f32 v203, v35, v210, v203
	v_fma_f32 v204, -v37, v213, v204
	v_fma_f32 v205, v37, v212, v205
	v_fma_f32 v206, -v39, v215, v206
	v_fma_f32 v207, v39, v214, v207
	global_load_dwordx4 v[104:107], v238, s[20:21]
	v_add_u32_e32 v238, v238, v243
	v_mfma_f32_16x16x32_bf16 v[136:139], v[112:115], v[0:3], 0
	v_mfma_f32_16x16x32_bf16 v[140:143], v[112:115], v[4:7], 0
	v_mfma_f32_16x16x32_bf16 v[144:147], v[112:115], v[8:11], 0
	v_mfma_f32_16x16x32_bf16 v[148:151], v[112:115], v[12:15], 0
	v_mfma_f32_16x16x32_bf16 v[152:155], v[112:115], v[16:19], 0
	v_mfma_f32_16x16x32_bf16 v[156:159], v[112:115], v[20:23], 0
	v_mfma_f32_16x16x32_bf16 v[160:163], v[112:115], v[24:27], 0
	v_mfma_f32_16x16x32_bf16 v[164:167], v[112:115], v[28:31], 0
	v_fma_f32 v208, v32, v200, v168
	v_fma_f32 v209, v32, v201, v184
	v_fma_f32 v210, v34, v202, v172
	v_fma_f32 v211, v34, v203, v188
	v_fma_f32 v212, v36, v204, v176
	v_fma_f32 v213, v36, v205, v192
	v_fma_f32 v214, v38, v206, v180
	v_fma_f32 v215, v38, v207, v196
	v_fma_f32 v208, -v33, v201, v208
	v_fma_f32 v209, v33, v200, v209
	v_fma_f32 v210, -v35, v203, v210
	v_fma_f32 v211, v35, v202, v211
	v_fma_f32 v212, -v37, v205, v212
	v_fma_f32 v213, v37, v204, v213
	v_fma_f32 v214, -v39, v207, v214
	v_fma_f32 v215, v39, v206, v215
	v_fma_f32 v200, v32, v208, v169
	v_fma_f32 v201, v32, v209, v185
	v_fma_f32 v202, v34, v210, v173
	v_fma_f32 v203, v34, v211, v189
	v_fma_f32 v204, v36, v212, v177
	v_fma_f32 v205, v36, v213, v193
	v_fma_f32 v206, v38, v214, v181
	v_fma_f32 v207, v38, v215, v197
	v_fma_f32 v200, -v33, v209, v200
	v_fma_f32 v201, v33, v208, v201
	v_fma_f32 v202, -v35, v211, v202
	v_fma_f32 v203, v35, v210, v203
	v_fma_f32 v204, -v37, v213, v204
	v_fma_f32 v205, v37, v212, v205
	v_fma_f32 v206, -v39, v215, v206
	v_fma_f32 v207, v39, v214, v207
	v_fma_f32 v208, v32, v200, v170
	v_fma_f32 v209, v32, v201, v186
	v_fma_f32 v210, v34, v202, v174
	v_fma_f32 v211, v34, v203, v190
	v_fma_f32 v212, v36, v204, v178
	v_fma_f32 v213, v36, v205, v194
	v_fma_f32 v214, v38, v206, v182
	v_fma_f32 v215, v38, v207, v198
	v_fma_f32 v208, -v33, v201, v208
	v_fma_f32 v209, v33, v200, v209
	v_fma_f32 v210, -v35, v203, v210
; __device__ __forceinline__ unsigned f2bf(float f) { unsigned u = __builtin_bit_cast(unsigned, f); return (u + 0x7fffu + ((u >> 16) & 1u)) >> 16; }
; __device__ __forceinline__ bf16x8 pack8(const float (&f)[8]) { u32x4 h; h.x = pk2(f[0], f[1]); h.y = pk2(f[2], f[3]); h.z = pk2(f[4], f[5]); h.w = pk2(f[6], f[7]); return __builtin_bit_cast(bf16x8, h); }
; template <bool FINAL> __device__ __forceinline__ void phase_s5_scan(const Fr& F) {
;     ...
;         for (int sub = 0; sub < 4; ++sub) {
;             const bf16x8 A1 = __builtin_bit_cast(bf16x8, uc[sub]);
; #pragma unroll
;             for (int nt = 0; nt < 8; ++nt) {
;                 f32x4 acc = {0.f, 0.f, 0.f, 0.f};
;                 acc = __builtin_amdgcn_mfma_f32_16x16x32_bf16(A1, B1[nt], acc, 0, 0, 0);
; #pragma unroll
;                 for (int reg = 0; reg < 4; ++reg) BUl[(4 * lq + reg) * 132 + 16 * nt + l15] = acc[reg];
;             }
;             asm volatile("s_waitcnt lgkmcnt(0)" ::: "memory");
; #pragma unroll 4
;             for (int jj = 0; jj < 16; ++jj) {
;                 const float br_ = BUl[jj * 132 + lane], bi_ = BUl[jj * 132 + 64 + lane];
;                 const float nr = ar * xr - ai * xi + br_, ni = ar * xi + ai * xr + bi_; xr = nr; xi = ni;
;                 if (FINAL) { BUl[jj * 132 + lane] = xr; BUl[jj * 132 + 64 + lane] = xi; }
;             }
;             if (FINAL) {
;                 asm volatile("s_waitcnt lgkmcnt(0)" ::: "memory");
;                 f32x4 acc = {0.f, 0.f, 0.f, 0.f};
; #pragma unroll
;                 for (int ks = 0; ks < 4; ++ks) {
;                     const f32x4 t0 = *(const f32x4*)(BUl + l15 * 132 + 32 * ks + 8 * lq), t1 = *(const f32x4*)(BUl + l15 * 132 + 32 * ks + 8 * lq + 4);
;                     const float xf[8] = {t0.x, t0.y, t0.z, t0.w, t1.x, t1.y, t1.z, t1.w};
;                     acc = __builtin_amdgcn_mfma_f32_16x16x32_bf16(pack8(xf), Chi[ks], acc, 0, 0, 0);
;                 }
; #pragma unroll
;                 for (int reg = 0; reg < 4; ++reg) { const int tok = tokof(s, chunk * 64 + sub * 16 + 4 * lq + reg);
;                     Yb[((size_t)b * TB + tok) * D + g * 16 + l15] = (bf16)f2bf(acc[reg]); }
;                 asm volatile("s_waitcnt lgkmcnt(0)" ::: "memory");
;             }
;         }
;         if (!FINAL) { float* e = E + ((size_t)task * 64 + lane) * 2; e[0] = xr; e[1] = xi; }
;     }
	v_fma_f32 v211, v35, v202, v211
	v_fma_f32 v212, -v37, v205, v212
	v_fma_f32 v213, v37, v204, v213
	v_fma_f32 v214, -v39, v207, v214
	v_fma_f32 v215, v39, v206, v215
	v_fma_f32 v200, v32, v208, v171
	v_fma_f32 v201, v32, v209, v187
	v_fma_f32 v202, v34, v210, v175
	v_fma_f32 v203, v34, v211, v191
	v_fma_f32 v204, v36, v212, v179
	v_fma_f32 v205, v36, v213, v195
	v_fma_f32 v206, v38, v214, v183
	v_fma_f32 v207, v38, v215, v199
	v_fma_f32 v200, -v33, v209, v200
	v_fma_f32 v201, v33, v208, v201
	v_fma_f32 v202, -v35, v211, v202
	v_fma_f32 v203, v35, v210, v203
	v_fma_f32 v204, -v37, v213, v204
	v_fma_f32 v205, v37, v212, v205
	v_fma_f32 v206, -v39, v215, v206
	v_fma_f32 v207, v39, v214, v207
	global_load_dwordx4 v[108:111], v238, s[20:21]
	v_add_u32_e32 v238, v238, v243
	v_mfma_f32_16x16x32_bf16 v[168:171], v[116:119], v[0:3], 0
	v_mfma_f32_16x16x32_bf16 v[172:175], v[116:119], v[4:7], 0
	v_mfma_f32_16x16x32_bf16 v[176:179], v[116:119], v[8:11], 0
	v_mfma_f32_16x16x32_bf16 v[180:183], v[116:119], v[12:15], 0
	v_mfma_f32_16x16x32_bf16 v[184:187], v[116:119], v[16:19], 0
	v_mfma_f32_16x16x32_bf16 v[188:191], v[116:119], v[20:23], 0
	v_mfma_f32_16x16x32_bf16 v[192:195], v[116:119], v[24:27], 0
	v_mfma_f32_16x16x32_bf16 v[196:199], v[116:119], v[28:31], 0
	v_fma_f32 v208, v32, v200, v136
	v_fma_f32 v209, v32, v201, v152
	v_fma_f32 v210, v34, v202, v140
	v_fma_f32 v211, v34, v203, v156
	v_fma_f32 v212, v36, v204, v144
	v_fma_f32 v213, v36, v205, v160
	v_fma_f32 v214, v38, v206, v148
	v_fma_f32 v215, v38, v207, v164
	v_fma_f32 v208, -v33, v201, v208
	v_fma_f32 v209, v33, v200, v209
	v_fma_f32 v210, -v35, v203, v210
	v_fma_f32 v211, v35, v202, v211
	v_fma_f32 v212, -v37, v205, v212
	v_fma_f32 v213, v37, v204, v213
	v_fma_f32 v214, -v39, v207, v214
	v_fma_f32 v215, v39, v206, v215
	v_fma_f32 v200, v32, v208, v137
	v_fma_f32 v201, v32, v209, v153
	v_fma_f32 v202, v34, v210, v141
	v_fma_f32 v203, v34, v211, v157
	v_fma_f32 v204, v36, v212, v145
	v_fma_f32 v205, v36, v213, v161
	v_fma_f32 v206, v38, v214, v149
	v_fma_f32 v207, v38, v215, v165
	v_fma_f32 v200, -v33, v209, v200
	v_fma_f32 v201, v33, v208, v201
	v_fma_f32 v202, -v35, v211, v202
	v_fma_f32 v203, v35, v210, v203
	v_fma_f32 v204, -v37, v213, v204
	v_fma_f32 v205, v37, v212, v205
	v_fma_f32 v206, -v39, v215, v206
	v_fma_f32 v207, v39, v214, v207
	v_fma_f32 v208, v32, v200, v138
	v_fma_f32 v209, v32, v201, v154
	v_fma_f32 v210, v34, v202, v142
	v_fma_f32 v211, v34, v203, v158
	v_fma_f32 v212, v36, v204, v146
	v_fma_f32 v213, v36, v205, v162
	v_fma_f32 v214, v38, v206, v150
	v_fma_f32 v215, v38, v207, v166
	v_fma_f32 v208, -v33, v201, v208
	v_fma_f32 v209, v33, v200, v209
	v_fma_f32 v210, -v35, v203, v210
	v_fma_f32 v211, v35, v202, v211
	v_fma_f32 v212, -v37, v205, v212
	v_fma_f32 v213, v37, v204, v213
	v_fma_f32 v214, -v39, v207, v214
	v_fma_f32 v215, v39, v206, v215
	v_fma_f32 v200, v32, v208, v139
	v_fma_f32 v201, v32, v209, v155
	v_fma_f32 v202, v34, v210, v143
	v_fma_f32 v203, v34, v211, v159
	v_fma_f32 v204, v36, v212, v147
	v_fma_f32 v205, v36, v213, v163
	v_fma_f32 v206, v38, v214, v151
	v_fma_f32 v207, v38, v215, v167
	v_fma_f32 v200, -v33, v209, v200
	v_fma_f32 v201, v33, v208, v201
	v_fma_f32 v202, -v35, v211, v202
	v_fma_f32 v203, v35, v210, v203
	v_fma_f32 v204, -v37, v213, v204
	v_fma_f32 v205, v37, v212, v205
	v_fma_f32 v206, -v39, v215, v206
	v_fma_f32 v207, v39, v214, v207
	global_load_dwordx4 v[112:115], v238, s[20:21]
	v_add_u32_e32 v238, v238, v243
	v_fma_f32 v208, v32, v200, v168
	v_fma_f32 v209, v32, v201, v184
	v_fma_f32 v210, v34, v202, v172
	v_fma_f32 v211, v34, v203, v188
	v_fma_f32 v212, v36, v204, v176
	v_fma_f32 v213, v36, v205, v192
	v_fma_f32 v214, v38, v206, v180
	v_fma_f32 v215, v38, v207, v196
	v_fma_f32 v208, -v33, v201, v208
	v_fma_f32 v209, v33, v200, v209
	v_fma_f32 v210, -v35, v203, v210
	v_fma_f32 v211, v35, v202, v211
	v_fma_f32 v212, -v37, v205, v212
	v_fma_f32 v213, v37, v204, v213
	v_fma_f32 v214, -v39, v207, v214
	v_fma_f32 v215, v39, v206, v215
	v_fma_f32 v200, v32, v208, v169
	v_fma_f32 v201, v32, v209, v185
	v_fma_f32 v202, v34, v210, v173
	v_fma_f32 v203, v34, v211, v189
	v_fma_f32 v204, v36, v212, v177
	v_fma_f32 v205, v36, v213, v193
	v_fma_f32 v206, v38, v214, v181
	v_fma_f32 v207, v38, v215, v197
	v_fma_f32 v200, -v33, v209, v200
	v_fma_f32 v201, v33, v208, v201
	v_fma_f32 v202, -v35, v211, v202
	v_fma_f32 v203, v35, v210, v203
	v_fma_f32 v204, -v37, v213, v204
	v_fma_f32 v205, v37, v212, v205
	v_fma_f32 v206, -v39, v215, v206
	v_fma_f32 v207, v39, v214, v207
	v_fma_f32 v208, v32, v200, v170
	v_fma_f32 v209, v32, v201, v186
	v_fma_f32 v210, v34, v202, v174
	v_fma_f32 v211, v34, v203, v190
	v_fma_f32 v212, v36, v204, v178
	v_fma_f32 v213, v36, v205, v194
	v_fma_f32 v214, v38, v206, v182
	v_fma_f32 v215, v38, v207, v198
	v_fma_f32 v208, -v33, v201, v208
	v_fma_f32 v209, v33, v200, v209
	v_fma_f32 v210, -v35, v203, v210
	v_fma_f32 v211, v35, v202, v211
	v_fma_f32 v212, -v37, v205, v212
	v_fma_f32 v213, v37, v204, v213
	v_fma_f32 v214, -v39, v207, v214
	v_fma_f32 v215, v39, v206, v215
	v_fma_f32 v200, v32, v208, v171
	v_fma_f32 v201, v32, v209, v187
	v_fma_f32 v202, v34, v210, v175
	v_fma_f32 v203, v34, v211, v191
	v_fma_f32 v204, v36, v212, v179
	v_fma_f32 v205, v36, v213, v195
	v_fma_f32 v206, v38, v214, v183
	v_fma_f32 v207, v38, v215, v199
	v_fma_f32 v200, -v33, v209, v200
	v_fma_f32 v201, v33, v208, v201
	v_fma_f32 v202, -v35, v211, v202
	v_fma_f32 v203, v35, v210, v203
	v_fma_f32 v204, -v37, v213, v204
	v_fma_f32 v205, v37, v212, v205
	v_fma_f32 v206, -v39, v215, v206
	v_fma_f32 v207, v39, v214, v207
	global_load_dwordx4 v[116:119], v238, s[20:21]
	v_add_u32_e32 v238, v238, v243
	global_store_dwordx2 v240, v[200:201], s[22:23] offset:0
	global_store_dwordx2 v240, v[202:203], s[22:23] offset:128
	global_store_dwordx2 v240, v[204:205], s[22:23] offset:256
	global_store_dwordx2 v240, v[206:207], s[22:23] offset:384
	s_add_i32 s14, s14, 16
	s_add_i32 s19, s19, 1
	s_cmp_lt_u32 s19, s56
	s_cbranch_scc1 .Ls5a_grp
	s_waitcnt vmcnt(0) lgkmcnt(0)

; __device__ __forceinline__ bf16x8 pack8(const float (&f)[8]) { u32x4 h; h.x = pk2(f[0], f[1]); h.y = pk2(f[2], f[3]); h.z = pk2(f[4], f[5]); h.w = pk2(f[6], f[7]); return __builtin_bit_cast(bf16x8, h); }
;     __device__ __forceinline__ bf16* R(int i) const { return (bf16*)(ws + OFF_R0 + (size_t)i * RSZ); }
; template <bool FINAL> __device__ __forceinline__ void phase_s5_scan(const Fr& F) {
;     const bf16* U = F.R(1); float* E = (float*)F.R(6);
;     float* BUl = (float*)(F.lds + F.wave * 16384);
;     const int lane = F.lane, l15 = lane & 15, lq = lane >> 4;
;     const float* BBf = (const float*)(F.ws + OFF_BB);
;     const int sg = F.gw >> 4, g = sg & 63, s = sg >> 6;
;     const f32x4 av = *(const f32x4*)((const float*)(F.ws + OFF_S5A) + (sg * 64 + lane) * 4);
;     const float ar = av.x, ai = av.y;
;     bf16x8 B1[8];
; #pragma unroll
;     for (int nt = 0; nt < 8; ++nt) {
;         const int n = 16 * nt + l15; const float* bp = BBf + (size_t)(sg * 64 + (n & 63)) * 32 + 16 * (n >> 6) + 8 * (lq & 1);
;         const f32x4 t0 = *(const f32x4*)bp, t1 = *(const f32x4*)(bp + 4); const float f[8] = {t0.x, t0.y, t0.z, t0.w, t1.x, t1.y, t1.z, t1.w};
;         B1[nt] = lq < 2 ? pack8(f) : (bf16x8){0, 0, 0, 0, 0, 0, 0, 0};
;     }
;     bf16x8 Chi[4];
;     if (FINAL) {
; #pragma unroll
;         for (int ks = 0; ks < 4; ++ks) {
;             const int k = 32 * ks + 8 * lq; const float* cp = (k < 64 ? F.a->in[32] : F.a->in[33]) + (size_t)g * 1024 + l15 * 64 + (k & 63); const float sg_ = k < 64 ? 1.f : -1.f;
;             const f32x4 t0 = *(const f32x4*)cp, t1 = *(const f32x4*)(cp + 4); const float f[8] = {sg_ * t0.x, sg_ * t0.y, sg_ * t0.z, sg_ * t0.w, sg_ * t1.x, sg_ * t1.y, sg_ * t1.z, sg_ * t1.w};
;             Chi[ks] = pack8(f);
;         }
;     }
.LBB0_1716:
	s_or_b64 exec, exec, s[6:7]
	v_cmp_gt_i32_e32 vcc, 18, v2
	v_cmp_lt_i32_e64 s[6:7], 17, v3
	s_and_b64 s[6:7], vcc, s[6:7]
	s_and_saveexec_b64 s[12:13], s[6:7]
	s_cbranch_execz .LBB0_1762
	s_lshr_b32 s3, s36, 4
	s_and_b32 s8, s3, 63
	s_lshr_b32 s9, s3, 6
	s_and_b32 s55, s36, 15
	s_cmp_lt_u32 s55, 4
	s_cselect_b32 s56, 5, 4
	v_and_b32_e32 v236, 15, v130
	v_lshrrev_b32_e32 v237, 4, v130
	s_add_u32 s42, s26, 0x100000
	s_addc_u32 s43, s27, 0
	s_add_u32 s44, s26, 0x40000
	s_addc_u32 s45, s27, 0
	s_add_u32 s20, s26, 0x3400000
	s_addc_u32 s21, s27, 0
	s_add_u32 s22, s26, 0xde00000
	s_addc_u32 s23, s27, 0
	s_mul_i32 s15, s9, 0x2200000
	s_add_u32 s24, s26, s15
	s_addc_u32 s25, s27, 0
	s_add_u32 s24, s24, 0x9a00000
	s_addc_u32 s25, s25, 0
	s_load_dwordx2 s[46:47], s[0:1], 0x100
	s_load_dwordx2 s[48:49], s[0:1], 0x108
	s_lshl_b32 s15, s3, 6
	v_add_u32_e32 v216, s15, v236
	v_and_b32_e32 v217, 1, v237
	v_lshlrev_b32_e32 v217, 5, v217
	v_lshl_add_u32 v218, v216, 7, v217
	v_add_u32_e32 v219, 0x1000, v218
	global_load_dwordx4 v[56:59], v218, s[42:43] offset:0
	global_load_dwordx4 v[60:63], v218, s[42:43] offset:16
	global_load_dwordx4 v[64:67], v218, s[42:43] offset:2048
	global_load_dwordx4 v[68:71], v218, s[42:43] offset:2064
	global_load_dwordx4 v[72:75], v219, s[42:43] offset:0
	global_load_dwordx4 v[76:79], v219, s[42:43] offset:16
	global_load_dwordx4 v[80:83], v219, s[42:43] offset:2048
	global_load_dwordx4 v[84:87], v219, s[42:43] offset:2064
	global_load_dwordx4 v[88:91], v218, s[42:43] offset:64
	global_load_dwordx4 v[92:95], v218, s[42:43] offset:80
	global_load_dwordx4 v[96:99], v218, s[42:43] offset:2112
	global_load_dwordx4 v[100:103], v218, s[42:43] offset:2128
	global_load_dwordx4 v[104:107], v219, s[42:43] offset:64
	global_load_dwordx4 v[108:111], v219, s[42:43] offset:80
	global_load_dwordx4 v[112:115], v219, s[42:43] offset:2112
	global_load_dwordx4 v[116:119], v219, s[42:43] offset:2128
	v_lshlrev_b32_e32 v220, 4, v216
	global_load_dwordx2 v[32:33], v220, s[44:45] offset:0
	global_load_dwordx2 v[34:35], v220, s[44:45] offset:256
	global_load_dwordx2 v[36:37], v220, s[44:45] offset:512
	global_load_dwordx2 v[38:39], v220, s[44:45] offset:768
	s_waitcnt vmcnt(0)
	v_cmp_gt_u32_e32 vcc, 2, v237
	v_cvt_pk_bf16_f32 v0, v56, v57
	v_cvt_pk_bf16_f32 v1, v58, v59
	v_cvt_pk_bf16_f32 v2, v60, v61
	v_cvt_pk_bf16_f32 v3, v62, v63
	v_cvt_pk_bf16_f32 v4, v64, v65
	v_cvt_pk_bf16_f32 v5, v66, v67
	v_cvt_pk_bf16_f32 v6, v68, v69
	v_cvt_pk_bf16_f32 v7, v70, v71
	v_cvt_pk_bf16_f32 v8, v72, v73
	v_cvt_pk_bf16_f32 v9, v74, v75
	v_cvt_pk_bf16_f32 v10, v76, v77
	v_cvt_pk_bf16_f32 v11, v78, v79
	v_cvt_pk_bf16_f32 v12, v80, v81
	v_cvt_pk_bf16_f32 v13, v82, v83
	v_cvt_pk_bf16_f32 v14, v84, v85
	v_cvt_pk_bf16_f32 v15, v86, v87
	v_cvt_pk_bf16_f32 v16, v88, v89
	v_cvt_pk_bf16_f32 v17, v90, v91
	v_cvt_pk_bf16_f32 v18, v92, v93
	v_cvt_pk_bf16_f32 v19, v94, v95
	v_cvt_pk_bf16_f32 v20, v96, v97
	v_cvt_pk_bf16_f32 v21, v98, v99
	v_cvt_pk_bf16_f32 v22, v100, v101
	v_cvt_pk_bf16_f32 v23, v102, v103
	v_cvt_pk_bf16_f32 v24, v104, v105
	v_cvt_pk_bf16_f32 v25, v106, v107
	v_cvt_pk_bf16_f32 v26, v108, v109
	v_cvt_pk_bf16_f32 v27, v110, v111
	v_cvt_pk_bf16_f32 v28, v112, v113
	v_cvt_pk_bf16_f32 v29, v114, v115
	v_cvt_pk_bf16_f32 v30, v116, v117
	v_cvt_pk_bf16_f32 v31, v118, v119
	v_cndmask_b32_e32 v0, 0, v0, vcc
	v_cndmask_b32_e32 v1, 0, v1, vcc
	v_cndmask_b32_e32 v2, 0, v2, vcc
	v_cndmask_b32_e32 v3, 0, v3, vcc
	v_cndmask_b32_e32 v4, 0, v4, vcc
	v_cndmask_b32_e32 v5, 0, v5, vcc
	v_cndmask_b32_e32 v6, 0, v6, vcc
	v_cndmask_b32_e32 v7, 0, v7, vcc
	v_cndmask_b32_e32 v8, 0, v8, vcc
	v_cndmask_b32_e32 v9, 0, v9, vcc
	v_cndmask_b32_e32 v10, 0, v10, vcc
	v_cndmask_b32_e32 v11, 0, v11, vcc
	v_cndmask_b32_e32 v12, 0, v12, vcc
	v_cndmask_b32_e32 v13, 0, v13, vcc
	v_cndmask_b32_e32 v14, 0, v14, vcc
	v_cndmask_b32_e32 v15, 0, v15, vcc
	v_cndmask_b32_e32 v16, 0, v16, vcc
	v_cndmask_b32_e32 v17, 0, v17, vcc
	v_cndmask_b32_e32 v18, 0, v18, vcc
	v_cndmask_b32_e32 v19, 0, v19, vcc
	v_cndmask_b32_e32 v20, 0, v20, vcc
	v_cndmask_b32_e32 v21, 0, v21, vcc
	v_cndmask_b32_e32 v22, 0, v22, vcc
	v_cndmask_b32_e32 v23, 0, v23, vcc
	v_cndmask_b32_e32 v24, 0, v24, vcc
	v_cndmask_b32_e32 v25, 0, v25, vcc
	v_cndmask_b32_e32 v26, 0, v26, vcc
	v_cndmask_b32_e32 v27, 0, v27, vcc
	v_cndmask_b32_e32 v28, 0, v28, vcc
	v_cndmask_b32_e32 v29, 0, v29, vcc
	v_cndmask_b32_e32 v30, 0, v30, vcc
	v_cndmask_b32_e32 v31, 0, v31, vcc
	s_lshl_b32 s15, s8, 4
	v_add_u32_e32 v221, s15, v236
	v_lshl_add_u32 v221, v221, 6, v237
	v_lshlrev_b32_e32 v221, 2, v221
	s_waitcnt lgkmcnt(0)
	global_load_dword v56, v221, s[46:47] offset:0
	global_load_dword v57, v221, s[48:49] offset:0
	global_load_dword v58, v221, s[46:47] offset:64
	global_load_dword v59, v221, s[48:49] offset:64
	global_load_dword v60, v221, s[46:47] offset:128
	global_load_dword v61, v221, s[48:49] offset:128
	global_load_dword v62, v221, s[46:47] offset:192
	global_load_dword v63, v221, s[48:49] offset:192
	global_load_dword v64, v221, s[46:47] offset:16
	global_load_dword v65, v221, s[48:49] offset:16
	global_load_dword v66, v221, s[46:47] offset:80
	global_load_dword v67, v221, s[48:49] offset:80
	global_load_dword v68, v221, s[46:47] offset:144
	global_load_dword v69, v221, s[48:49] offset:144
	global_load_dword v70, v221, s[46:47] offset:208
	global_load_dword v71, v221, s[48:49] offset:208
	global_load_dword v72, v221, s[46:47] offset:32
	global_load_dword v73, v221, s[48:49] offset:32
	global_load_dword v74, v221, s[46:47] offset:96
	global_load_dword v75, v221, s[48:49] offset:96
	global_load_dword v76, v221, s[46:47] offset:160
	global_load_dword v77, v221, s[48:49] offset:160
	global_load_dword v78, v221, s[46:47] offset:224
	global_load_dword v79, v221, s[48:49] offset:224
	global_load_dword v80, v221, s[46:47] offset:48
	global_load_dword v81, v221, s[48:49] offset:48
	global_load_dword v82, v221, s[46:47] offset:112
	global_load_dword v83, v221, s[48:49] offset:112
	global_load_dword v84, v221, s[46:47] offset:176
	global_load_dword v85, v221, s[48:49] offset:176
	global_load_dword v86, v221, s[46:47] offset:240
	global_load_dword v87, v221, s[48:49] offset:240
	s_waitcnt vmcnt(0)
; __device__ __forceinline__ bf16x8 pack8(const float (&f)[8]) { u32x4 h; h.x = pk2(f[0], f[1]); h.y = pk2(f[2], f[3]); h.z = pk2(f[4], f[5]); h.w = pk2(f[6], f[7]); return __builtin_bit_cast(bf16x8, h); }
;     __device__ __forceinline__ bf16* R(int i) const { return (bf16*)(ws + OFF_R0 + (size_t)i * RSZ); }
; template <bool FINAL> __device__ __forceinline__ void phase_s5_scan(const Fr& F) {
;     ...
;             const int k = 32 * ks + 8 * lq; const float* cp = (k < 64 ? F.a->in[32] : F.a->in[33]) + (size_t)g * 1024 + l15 * 64 + (k & 63); const float sg_ = k < 64 ? 1.f : -1.f;
;             const f32x4 t0 = *(const f32x4*)cp, t1 = *(const f32x4*)(cp + 4); const float f[8] = {sg_ * t0.x, sg_ * t0.y, sg_ * t0.z, sg_ * t0.w, sg_ * t1.x, sg_ * t1.y, sg_ * t1.z, sg_ * t1.w};
;             Chi[ks] = pack8(f);
;         }
;     }
;     u32x4 ua[4]; float e0 = 0.f, e1 = 0.f;
;     {   const int ti = F.gw & 15, b = ti / 68, chunk = ti - b * 68;
; #pragma unroll
;         for (int sb = 0; sb < 4; ++sb) ua[sb] = lq < 2 ? *(const u32x4*)(U + ((size_t)b * TB + tokof(s, chunk * 64 + sb * 16 + l15)) * D + g * 16 + 8 * lq) : (u32x4){0u, 0u, 0u, 0u};
;         if (FINAL) { const float* e = E + ((size_t)(((s * 4 + b) * 64 + g) * 68 + chunk) * 64 + lane) * 2; e0 = e[0]; e1 = e[1]; } }
;     for (int ti = (F.gw & 15); ti < NB * 68; ti += 16) {
;         const int b = ti / 68, chunk = ti - b * 68, sbg = (s * 4 + b) * 64 + g, task = sbg * 68 + chunk;
;         float xr = FINAL ? e0 : 0.f, xi = FINAL ? e1 : 0.f;
;         bf16* Yb = F.R(4 + s);
;         u32x4 uc[4];
; #pragma unroll
;         for (int sb = 0; sb < 4; ++sb) uc[sb] = ua[sb];
;         if (ti + 16 < NB * 68) {
;             const int tn = ti + 16, bn = tn / 68, cn = tn - bn * 68;
; #pragma unroll
;             for (int sb = 0; sb < 4; ++sb) ua[sb] = lq < 2 ? *(const u32x4*)(U + ((size_t)bn * TB + tokof(s, cn * 64 + sb * 16 + l15)) * D + g * 16 + 8 * lq) : (u32x4){0u, 0u, 0u, 0u};
;             if (FINAL) { const float* e = E + ((size_t)(((s * 4 + bn) * 64 + g) * 68 + cn) * 64 + lane) * 2; e0 = e[0]; e1 = e[1]; }
	v_cvt_pk_bf16_f32 v40, v56, -v57
	v_cvt_pk_bf16_f32 v41, v58, -v59
	v_cvt_pk_bf16_f32 v42, v60, -v61
	v_cvt_pk_bf16_f32 v43, v62, -v63
	v_cvt_pk_bf16_f32 v44, v64, -v65
	v_cvt_pk_bf16_f32 v45, v66, -v67
	v_cvt_pk_bf16_f32 v46, v68, -v69
	v_cvt_pk_bf16_f32 v47, v70, -v71
	v_cvt_pk_bf16_f32 v48, v72, -v73
	v_cvt_pk_bf16_f32 v49, v74, -v75
	v_cvt_pk_bf16_f32 v50, v76, -v77
	v_cvt_pk_bf16_f32 v51, v78, -v79
	v_cvt_pk_bf16_f32 v52, v80, -v81
	v_cvt_pk_bf16_f32 v53, v82, -v83
	v_cvt_pk_bf16_f32 v54, v84, -v85
	v_cvt_pk_bf16_f32 v55, v86, -v87
	s_lshl_b32 s15, s68, 14
	v_lshlrev_b32_e32 v241, 10, v237
	v_lshl_add_u32 v241, v236, 4, v241
	v_add_u32_e32 v241, s15, v241
	v_lshlrev_b32_e32 v242, 8, v236
	v_lshl_add_u32 v242, v237, 4, v242
	v_add_u32_e32 v242, s15, v242
	s_cmp_eq_u32 s9, 0
	s_mov_b32 s18, 0xffffe000
	s_cselect_b32 s18, 0x2000, s18
	v_mov_b32_e32 v243, s18
	s_mov_b32 s14, s55
	s_lshl_b32 s15, s14, 2
	v_lshrrev_b32_e32 v244, 2, v236
	v_add_u32_e32 v244, s15, v244
	v_mul_u32_u24_e32 v245, 0xf1, v244
	v_lshrrev_b32_e32 v245, 14, v245
	v_mul_u32_u24_e32 v232, 68, v245
	v_sub_u32_e32 v244, v244, v232
	v_and_b32_e32 v232, 3, v236
	v_lshl_add_u32 v232, v244, 6, v232
	v_mov_b32_e32 v233, 0x11ff
	v_mov_b32_e32 v234, 0xff
	v_cmp_gt_u32_e32 vcc, 4, v244
	s_nop 1
	v_cndmask_b32_e32 v233, v233, v234, vcc
	v_sub_u32_e32 v233, v233, v232
	s_cmp_eq_u32 s9, 0
	s_cselect_b64 vcc, -1, 0
	s_nop 1
	v_cndmask_b32_e32 v232, v233, v232, vcc
	v_mul_u32_u24_e32 v245, 0x1100, v245
	v_add_u32_e32 v232, v232, v245
	s_lshl_b32 s16, s8, 5
	v_and_b32_e32 v233, 1, v237
	v_lshl_add_u32 v233, v233, 4, s16
	v_lshl_add_u32 v238, v232, 11, v233
	global_load_dwordx4 v[56:59], v238, s[20:21]
	v_add_u32_e32 v238, v238, v243
	global_load_dwordx4 v[60:63], v238, s[20:21]
	v_add_u32_e32 v238, v238, v243
	global_load_dwordx4 v[64:67], v238, s[20:21]
	v_add_u32_e32 v238, v238, v243
	global_load_dwordx4 v[68:71], v238, s[20:21]
	v_add_u32_e32 v238, v238, v243
	global_load_dwordx4 v[72:75], v238, s[20:21]
	v_add_u32_e32 v238, v238, v243
	global_load_dwordx4 v[76:79], v238, s[20:21]
	v_add_u32_e32 v238, v238, v243
	global_load_dwordx4 v[80:83], v238, s[20:21]
	v_add_u32_e32 v238, v238, v243
	global_load_dwordx4 v[84:87], v238, s[20:21]
	v_add_u32_e32 v238, v238, v243
	global_load_dwordx4 v[88:91], v238, s[20:21]
	v_add_u32_e32 v238, v238, v243
	global_load_dwordx4 v[92:95], v238, s[20:21]
	v_add_u32_e32 v238, v238, v243
	global_load_dwordx4 v[96:99], v238, s[20:21]
	v_add_u32_e32 v238, v238, v243
	global_load_dwordx4 v[100:103], v238, s[20:21]
	v_add_u32_e32 v238, v238, v243
	global_load_dwordx4 v[104:107], v238, s[20:21]
	v_add_u32_e32 v238, v238, v243
	global_load_dwordx4 v[108:111], v238, s[20:21]
	v_add_u32_e32 v238, v238, v243
	global_load_dwordx4 v[112:115], v238, s[20:21]
	v_add_u32_e32 v238, v238, v243
	global_load_dwordx4 v[116:119], v238, s[20:21]
	v_add_u32_e32 v238, v238, v243
	s_mov_b32 s19, 0
.Ls5b_grp:
	s_lshl_b32 s15, s14, 2
	v_lshrrev_b32_e32 v244, 2, v236
	v_add_u32_e32 v244, s15, v244
	v_mul_u32_u24_e32 v245, 0xf1, v244
	v_lshrrev_b32_e32 v245, 14, v245
	v_mul_u32_u24_e32 v232, 68, v245
	v_sub_u32_e32 v244, v244, v232
	v_and_b32_e32 v232, 3, v236
	v_lshl_add_u32 v232, v244, 6, v232
	v_mov_b32_e32 v233, 0x11ff
	v_mov_b32_e32 v234, 0xff
	v_cmp_gt_u32_e32 vcc, 4, v244
	s_nop 1
	v_cndmask_b32_e32 v233, v233, v234, vcc
	v_sub_u32_e32 v233, v233, v232
	s_cmp_eq_u32 s9, 0
	s_cselect_b64 vcc, -1, 0
	s_nop 1
	v_cndmask_b32_e32 v232, v233, v232, vcc
	v_mul_u32_u24_e32 v245, 0x1100, v245
	v_add_u32_e32 v232, v232, v245
	s_lshl_b32 s16, s8, 5
	v_and_b32_e32 v233, 1, v237
	v_lshl_add_u32 v233, v233, 4, s16
	v_lshl_add_u32 v235, v232, 11, v233
	v_lshl_add_u32 v233, v237, 3, s16
	v_lshl_add_u32 v239, v232, 11, v233
	v_add_u32_e32 v244, s15, v237
	v_mul_u32_u24_e32 v245, 0xf1, v244
	v_lshrrev_b32_e32 v245, 14, v245
	v_mul_u32_u24_e32 v232, 68, v245
	v_sub_u32_e32 v244, v244, v232
	s_lshl_b32 s17, s9, 2
	v_add_u32_e32 v245, s17, v245
	v_lshl_add_u32 v245, v245, 6, s8
	v_mul_u32_u24_e32 v245, 68, v245
	v_add_u32_e32 v245, v245, v244
	v_lshl_add_u32 v245, v245, 6, v236
	v_lshlrev_b32_e32 v240, 3, v245
	s_add_i32 s54, s14, 16
	s_lshl_b32 s15, s54, 2
	v_lshrrev_b32_e32 v244, 2, v236
	v_add_u32_e32 v244, s15, v244
	v_mul_u32_u24_e32 v245, 0xf1, v244
	v_lshrrev_b32_e32 v245, 14, v245
	v_mul_u32_u24_e32 v232, 68, v245
	v_sub_u32_e32 v244, v244, v232
	v_and_b32_e32 v232, 3, v236
	v_lshl_add_u32 v232, v244, 6, v232
	v_mov_b32_e32 v233, 0x11ff
	v_mov_b32_e32 v234, 0xff
	v_cmp_gt_u32_e32 vcc, 4, v244
	s_nop 1
	v_cndmask_b32_e32 v233, v233, v234, vcc
	v_sub_u32_e32 v233, v233, v232
	s_cmp_eq_u32 s9, 0
	s_cselect_b64 vcc, -1, 0
	s_nop 1
	v_cndmask_b32_e32 v232, v233, v232, vcc
	v_mul_u32_u24_e32 v245, 0x1100, v245
	v_add_u32_e32 v232, v232, v245
	s_lshl_b32 s16, s8, 5
	v_and_b32_e32 v233, 1, v237
	v_lshl_add_u32 v233, v233, 4, s16
	v_lshl_add_u32 v238, v232, 11, v233
	global_load_dwordx2 v[200:201], v240, s[22:23] offset:0
	global_load_dwordx2 v[202:203], v240, s[22:23] offset:128
	global_load_dwordx2 v[204:205], v240, s[22:23] offset:256
	global_load_dwordx2 v[206:207], v240, s[22:23] offset:384
	s_waitcnt vmcnt(0)
; __device__ __forceinline__ unsigned f2bf(float f) { unsigned u = __builtin_bit_cast(unsigned, f); return (u + 0x7fffu + ((u >> 16) & 1u)) >> 16; }
; __device__ __forceinline__ bf16x8 pack8(const float (&f)[8]) { u32x4 h; h.x = pk2(f[0], f[1]); h.y = pk2(f[2], f[3]); h.z = pk2(f[4], f[5]); h.w = pk2(f[6], f[7]); return __builtin_bit_cast(bf16x8, h); }
; template <bool FINAL> __device__ __forceinline__ void phase_s5_scan(const Fr& F) {
;     ...
; #pragma unroll
;         for (int sub = 0; sub < 4; ++sub) {
;             const bf16x8 A1 = __builtin_bit_cast(bf16x8, uc[sub]);
; #pragma unroll
;             for (int nt = 0; nt < 8; ++nt) {
;                 f32x4 acc = {0.f, 0.f, 0.f, 0.f};
;                 acc = __builtin_amdgcn_mfma_f32_16x16x32_bf16(A1, B1[nt], acc, 0, 0, 0);
; #pragma unroll
;                 for (int reg = 0; reg < 4; ++reg) BUl[(4 * lq + reg) * 132 + 16 * nt + l15] = acc[reg];
;             }
;             asm volatile("s_waitcnt lgkmcnt(0)" ::: "memory");
; #pragma unroll 4
;             for (int jj = 0; jj < 16; ++jj) {
;                 const float br_ = BUl[jj * 132 + lane], bi_ = BUl[jj * 132 + 64 + lane];
;                 const float nr = ar * xr - ai * xi + br_, ni = ar * xi + ai * xr + bi_; xr = nr; xi = ni;
;                 if (FINAL) { BUl[jj * 132 + lane] = xr; BUl[jj * 132 + 64 + lane] = xi; }
;             }
;             if (FINAL) {
;                 asm volatile("s_waitcnt lgkmcnt(0)" ::: "memory");
;                 f32x4 acc = {0.f, 0.f, 0.f, 0.f};
; #pragma unroll
;                 for (int ks = 0; ks < 4; ++ks) {
;                     const f32x4 t0 = *(const f32x4*)(BUl + l15 * 132 + 32 * ks + 8 * lq), t1 = *(const f32x4*)(BUl + l15 * 132 + 32 * ks + 8 * lq + 4);
;                     const float xf[8] = {t0.x, t0.y, t0.z, t0.w, t1.x, t1.y, t1.z, t1.w};
;                     acc = __builtin_amdgcn_mfma_f32_16x16x32_bf16(pack8(xf), Chi[ks], acc, 0, 0, 0);
;                 }
; #pragma unroll
;                 for (int reg = 0; reg < 4; ++reg) { const int tok = tokof(s, chunk * 64 + sub * 16 + 4 * lq + reg);
;                     Yb[((size_t)b * TB + tok) * D + g * 16 + l15] = (bf16)f2bf(acc[reg]); }
;                 asm volatile("s_waitcnt lgkmcnt(0)" ::: "memory");
	v_mfma_f32_16x16x32_bf16 v[136:139], v[56:59], v[0:3], 0
	v_mfma_f32_16x16x32_bf16 v[140:143], v[56:59], v[4:7], 0
	v_mfma_f32_16x16x32_bf16 v[144:147], v[56:59], v[8:11], 0
	v_mfma_f32_16x16x32_bf16 v[148:151], v[56:59], v[12:15], 0
	v_mfma_f32_16x16x32_bf16 v[152:155], v[56:59], v[16:19], 0
	v_mfma_f32_16x16x32_bf16 v[156:159], v[56:59], v[20:23], 0
	v_mfma_f32_16x16x32_bf16 v[160:163], v[56:59], v[24:27], 0
	v_mfma_f32_16x16x32_bf16 v[164:167], v[56:59], v[28:31], 0
	v_mfma_f32_16x16x32_bf16 v[168:171], v[60:63], v[0:3], 0
	v_mfma_f32_16x16x32_bf16 v[172:175], v[60:63], v[4:7], 0
	v_mfma_f32_16x16x32_bf16 v[176:179], v[60:63], v[8:11], 0
	v_mfma_f32_16x16x32_bf16 v[180:183], v[60:63], v[12:15], 0
	v_mfma_f32_16x16x32_bf16 v[184:187], v[60:63], v[16:19], 0
	v_mfma_f32_16x16x32_bf16 v[188:191], v[60:63], v[20:23], 0
	v_mfma_f32_16x16x32_bf16 v[192:195], v[60:63], v[24:27], 0
	v_mfma_f32_16x16x32_bf16 v[196:199], v[60:63], v[28:31], 0
	v_fma_f32 v208, v32, v200, v136
	v_fma_f32 v209, v32, v201, v152
	v_fma_f32 v210, v34, v202, v140
	v_fma_f32 v211, v34, v203, v156
	v_fma_f32 v212, v36, v204, v144
	v_fma_f32 v213, v36, v205, v160
	v_fma_f32 v214, v38, v206, v148
	v_fma_f32 v215, v38, v207, v164
	v_fma_f32 v208, -v33, v201, v208
	v_fma_f32 v209, v33, v200, v209
	v_fma_f32 v210, -v35, v203, v210
	v_fma_f32 v211, v35, v202, v211
	v_fma_f32 v212, -v37, v205, v212
	v_fma_f32 v213, v37, v204, v213
	v_fma_f32 v214, -v39, v207, v214
	v_fma_f32 v215, v39, v206, v215
	v_cvt_pk_bf16_f32 v124, v208, v209
	v_cvt_pk_bf16_f32 v125, v210, v211
	v_cvt_pk_bf16_f32 v126, v212, v213
	v_cvt_pk_bf16_f32 v127, v214, v215
	ds_write_b128 v241, v[124:127] offset:0
	v_fma_f32 v200, v32, v208, v137
	v_fma_f32 v201, v32, v209, v153
	v_fma_f32 v202, v34, v210, v141
	v_fma_f32 v203, v34, v211, v157
	v_fma_f32 v204, v36, v212, v145
	v_fma_f32 v205, v36, v213, v161
	v_fma_f32 v206, v38, v214, v149
	v_fma_f32 v207, v38, v215, v165
	v_fma_f32 v200, -v33, v209, v200
	v_fma_f32 v201, v33, v208, v201
	v_fma_f32 v202, -v35, v211, v202
	v_fma_f32 v203, v35, v210, v203
	v_fma_f32 v204, -v37, v213, v204
	v_fma_f32 v205, v37, v212, v205
	v_fma_f32 v206, -v39, v215, v206
	v_fma_f32 v207, v39, v214, v207
	v_cvt_pk_bf16_f32 v124, v200, v201
	v_cvt_pk_bf16_f32 v125, v202, v203
	v_cvt_pk_bf16_f32 v126, v204, v205
	v_cvt_pk_bf16_f32 v127, v206, v207
	ds_write_b128 v241, v[124:127] offset:256
	v_fma_f32 v208, v32, v200, v138
	v_fma_f32 v209, v32, v201, v154
	v_fma_f32 v210, v34, v202, v142
	v_fma_f32 v211, v34, v203, v158
	v_fma_f32 v212, v36, v204, v146
	v_fma_f32 v213, v36, v205, v162
	v_fma_f32 v214, v38, v206, v150
	v_fma_f32 v215, v38, v207, v166
	v_fma_f32 v208, -v33, v201, v208
	v_fma_f32 v209, v33, v200, v209
	v_fma_f32 v210, -v35, v203, v210
	v_fma_f32 v211, v35, v202, v211
	v_fma_f32 v212, -v37, v205, v212
	v_fma_f32 v213, v37, v204, v213
	v_fma_f32 v214, -v39, v207, v214
	v_fma_f32 v215, v39, v206, v215
	v_cvt_pk_bf16_f32 v124, v208, v209
	v_cvt_pk_bf16_f32 v125, v210, v211
	v_cvt_pk_bf16_f32 v126, v212, v213
	v_cvt_pk_bf16_f32 v127, v214, v215
	ds_write_b128 v241, v[124:127] offset:512
	v_fma_f32 v200, v32, v208, v139
	v_fma_f32 v201, v32, v209, v155
	v_fma_f32 v202, v34, v210, v143
	v_fma_f32 v203, v34, v211, v159
	v_fma_f32 v204, v36, v212, v147
	v_fma_f32 v205, v36, v213, v163
	v_fma_f32 v206, v38, v214, v151
	v_fma_f32 v207, v38, v215, v167
	v_fma_f32 v200, -v33, v209, v200
	v_fma_f32 v201, v33, v208, v201
	v_fma_f32 v202, -v35, v211, v202
	v_fma_f32 v203, v35, v210, v203
	v_fma_f32 v204, -v37, v213, v204
	v_fma_f32 v205, v37, v212, v205
	v_fma_f32 v206, -v39, v215, v206
	v_fma_f32 v207, v39, v214, v207
	v_cvt_pk_bf16_f32 v124, v200, v201
	v_cvt_pk_bf16_f32 v125, v202, v203
	v_cvt_pk_bf16_f32 v126, v204, v205
	v_cvt_pk_bf16_f32 v127, v206, v207
	ds_write_b128 v241, v[124:127] offset:768
	s_waitcnt lgkmcnt(0)
	ds_read_b128 v[216:219], v242 offset:0
	ds_read_b128 v[220:223], v242 offset:64
	ds_read_b128 v[224:227], v242 offset:128
	ds_read_b128 v[228:231], v242 offset:192
	s_waitcnt lgkmcnt(0)
	v_mfma_f32_16x16x32_bf16 v[120:123], v[40:43], v[216:219], 0
	v_mfma_f32_16x16x32_bf16 v[120:123], v[44:47], v[220:223], v[120:123]
	v_mfma_f32_16x16x32_bf16 v[120:123], v[48:51], v[224:227], v[120:123]
	v_mfma_f32_16x16x32_bf16 v[120:123], v[52:55], v[228:231], v[120:123]
	global_load_dwordx4 v[56:59], v238, s[20:21]
	v_add_u32_e32 v238, v238, v243
	s_nop 7
	v_cvt_pk_bf16_f32 v124, v120, v121
	v_cvt_pk_bf16_f32 v125, v122, v123
	s_nop 0
	global_store_dwordx2 v239, v[124:125], s[24:25]
	v_add_u32_e32 v239, v239, v243
	v_mfma_f32_16x16x32_bf16 v[136:139], v[64:67], v[0:3], 0
	v_mfma_f32_16x16x32_bf16 v[140:143], v[64:67], v[4:7], 0
	v_mfma_f32_16x16x32_bf16 v[144:147], v[64:67], v[8:11], 0
	v_mfma_f32_16x16x32_bf16 v[148:151], v[64:67], v[12:15], 0
	v_mfma_f32_16x16x32_bf16 v[152:155], v[64:67], v[16:19], 0
	v_mfma_f32_16x16x32_bf16 v[156:159], v[64:67], v[20:23], 0
	v_mfma_f32_16x16x32_bf16 v[160:163], v[64:67], v[24:27], 0
	v_mfma_f32_16x16x32_bf16 v[164:167], v[64:67], v[28:31], 0
	v_fma_f32 v208, v32, v200, v168
	v_fma_f32 v209, v32, v201, v184
	v_fma_f32 v210, v34, v202, v172
	v_fma_f32 v211, v34, v203, v188
	v_fma_f32 v212, v36, v204, v176
	v_fma_f32 v213, v36, v205, v192
	v_fma_f32 v214, v38, v206, v180
	v_fma_f32 v215, v38, v207, v196
	v_fma_f32 v208, -v33, v201, v208
	v_fma_f32 v209, v33, v200, v209
	v_fma_f32 v210, -v35, v203, v210
	v_fma_f32 v211, v35, v202, v211
	v_fma_f32 v212, -v37, v205, v212
	v_fma_f32 v213, v37, v204, v213
	v_fma_f32 v214, -v39, v207, v214
	v_fma_f32 v215, v39, v206, v215
	v_cvt_pk_bf16_f32 v124, v208, v209
	v_cvt_pk_bf16_f32 v125, v210, v211
; __device__ __forceinline__ unsigned f2bf(float f) { unsigned u = __builtin_bit_cast(unsigned, f); return (u + 0x7fffu + ((u >> 16) & 1u)) >> 16; }
; __device__ __forceinline__ bf16x8 pack8(const float (&f)[8]) { u32x4 h; h.x = pk2(f[0], f[1]); h.y = pk2(f[2], f[3]); h.z = pk2(f[4], f[5]); h.w = pk2(f[6], f[7]); return __builtin_bit_cast(bf16x8, h); }
; template <bool FINAL> __device__ __forceinline__ void phase_s5_scan(const Fr& F) {
;     ...
; #pragma unroll
;         for (int sub = 0; sub < 4; ++sub) {
;             const bf16x8 A1 = __builtin_bit_cast(bf16x8, uc[sub]);
; #pragma unroll
;             for (int nt = 0; nt < 8; ++nt) {
;                 f32x4 acc = {0.f, 0.f, 0.f, 0.f};
;                 acc = __builtin_amdgcn_mfma_f32_16x16x32_bf16(A1, B1[nt], acc, 0, 0, 0);
; #pragma unroll
;                 for (int reg = 0; reg < 4; ++reg) BUl[(4 * lq + reg) * 132 + 16 * nt + l15] = acc[reg];
;             }
;             asm volatile("s_waitcnt lgkmcnt(0)" ::: "memory");
; #pragma unroll 4
;             for (int jj = 0; jj < 16; ++jj) {
;                 const float br_ = BUl[jj * 132 + lane], bi_ = BUl[jj * 132 + 64 + lane];
;                 const float nr = ar * xr - ai * xi + br_, ni = ar * xi + ai * xr + bi_; xr = nr; xi = ni;
;                 if (FINAL) { BUl[jj * 132 + lane] = xr; BUl[jj * 132 + 64 + lane] = xi; }
;             }
;             if (FINAL) {
;                 asm volatile("s_waitcnt lgkmcnt(0)" ::: "memory");
;                 f32x4 acc = {0.f, 0.f, 0.f, 0.f};
; #pragma unroll
;                 for (int ks = 0; ks < 4; ++ks) {
;                     const f32x4 t0 = *(const f32x4*)(BUl + l15 * 132 + 32 * ks + 8 * lq), t1 = *(const f32x4*)(BUl + l15 * 132 + 32 * ks + 8 * lq + 4);
;                     const float xf[8] = {t0.x, t0.y, t0.z, t0.w, t1.x, t1.y, t1.z, t1.w};
;                     acc = __builtin_amdgcn_mfma_f32_16x16x32_bf16(pack8(xf), Chi[ks], acc, 0, 0, 0);
;                 }
; #pragma unroll
;                 for (int reg = 0; reg < 4; ++reg) { const int tok = tokof(s, chunk * 64 + sub * 16 + 4 * lq + reg);
;                     Yb[((size_t)b * TB + tok) * D + g * 16 + l15] = (bf16)f2bf(acc[reg]); }
;                 asm volatile("s_waitcnt lgkmcnt(0)" ::: "memory");
	v_cvt_pk_bf16_f32 v126, v212, v213
	v_cvt_pk_bf16_f32 v127, v214, v215
	ds_write_b128 v241, v[124:127] offset:0
	v_fma_f32 v200, v32, v208, v169
	v_fma_f32 v201, v32, v209, v185
	v_fma_f32 v202, v34, v210, v173
	v_fma_f32 v203, v34, v211, v189
	v_fma_f32 v204, v36, v212, v177
	v_fma_f32 v205, v36, v213, v193
	v_fma_f32 v206, v38, v214, v181
	v_fma_f32 v207, v38, v215, v197
	v_fma_f32 v200, -v33, v209, v200
	v_fma_f32 v201, v33, v208, v201
	v_fma_f32 v202, -v35, v211, v202
	v_fma_f32 v203, v35, v210, v203
	v_fma_f32 v204, -v37, v213, v204
	v_fma_f32 v205, v37, v212, v205
	v_fma_f32 v206, -v39, v215, v206
	v_fma_f32 v207, v39, v214, v207
	v_cvt_pk_bf16_f32 v124, v200, v201
	v_cvt_pk_bf16_f32 v125, v202, v203
	v_cvt_pk_bf16_f32 v126, v204, v205
	v_cvt_pk_bf16_f32 v127, v206, v207
	ds_write_b128 v241, v[124:127] offset:256
	v_fma_f32 v208, v32, v200, v170
	v_fma_f32 v209, v32, v201, v186
	v_fma_f32 v210, v34, v202, v174
	v_fma_f32 v211, v34, v203, v190
	v_fma_f32 v212, v36, v204, v178
	v_fma_f32 v213, v36, v205, v194
	v_fma_f32 v214, v38, v206, v182
	v_fma_f32 v215, v38, v207, v198
	v_fma_f32 v208, -v33, v201, v208
	v_fma_f32 v209, v33, v200, v209
	v_fma_f32 v210, -v35, v203, v210
	v_fma_f32 v211, v35, v202, v211
	v_fma_f32 v212, -v37, v205, v212
	v_fma_f32 v213, v37, v204, v213
	v_fma_f32 v214, -v39, v207, v214
	v_fma_f32 v215, v39, v206, v215
	v_cvt_pk_bf16_f32 v124, v208, v209
	v_cvt_pk_bf16_f32 v125, v210, v211
	v_cvt_pk_bf16_f32 v126, v212, v213
	v_cvt_pk_bf16_f32 v127, v214, v215
	ds_write_b128 v241, v[124:127] offset:512
	v_fma_f32 v200, v32, v208, v171
	v_fma_f32 v201, v32, v209, v187
	v_fma_f32 v202, v34, v210, v175
	v_fma_f32 v203, v34, v211, v191
	v_fma_f32 v204, v36, v212, v179
	v_fma_f32 v205, v36, v213, v195
	v_fma_f32 v206, v38, v214, v183
	v_fma_f32 v207, v38, v215, v199
	v_fma_f32 v200, -v33, v209, v200
	v_fma_f32 v201, v33, v208, v201
	v_fma_f32 v202, -v35, v211, v202
	v_fma_f32 v203, v35, v210, v203
	v_fma_f32 v204, -v37, v213, v204
	v_fma_f32 v205, v37, v212, v205
	v_fma_f32 v206, -v39, v215, v206
	v_fma_f32 v207, v39, v214, v207
	v_cvt_pk_bf16_f32 v124, v200, v201
	v_cvt_pk_bf16_f32 v125, v202, v203
	v_cvt_pk_bf16_f32 v126, v204, v205
	v_cvt_pk_bf16_f32 v127, v206, v207
	ds_write_b128 v241, v[124:127] offset:768
	s_waitcnt lgkmcnt(0)
	ds_read_b128 v[216:219], v242 offset:0
	ds_read_b128 v[220:223], v242 offset:64
	ds_read_b128 v[224:227], v242 offset:128
	ds_read_b128 v[228:231], v242 offset:192
	s_waitcnt lgkmcnt(0)
	v_mfma_f32_16x16x32_bf16 v[120:123], v[40:43], v[216:219], 0
	v_mfma_f32_16x16x32_bf16 v[120:123], v[44:47], v[220:223], v[120:123]
	v_mfma_f32_16x16x32_bf16 v[120:123], v[48:51], v[224:227], v[120:123]
	v_mfma_f32_16x16x32_bf16 v[120:123], v[52:55], v[228:231], v[120:123]
	global_load_dwordx4 v[60:63], v238, s[20:21]
	v_add_u32_e32 v238, v238, v243
	s_nop 7
	v_cvt_pk_bf16_f32 v124, v120, v121
	v_cvt_pk_bf16_f32 v125, v122, v123
	s_nop 0
	global_store_dwordx2 v239, v[124:125], s[24:25]
	v_add_u32_e32 v239, v239, v243
	v_mfma_f32_16x16x32_bf16 v[168:171], v[68:71], v[0:3], 0
	v_mfma_f32_16x16x32_bf16 v[172:175], v[68:71], v[4:7], 0
	v_mfma_f32_16x16x32_bf16 v[176:179], v[68:71], v[8:11], 0
	v_mfma_f32_16x16x32_bf16 v[180:183], v[68:71], v[12:15], 0
	v_mfma_f32_16x16x32_bf16 v[184:187], v[68:71], v[16:19], 0
	v_mfma_f32_16x16x32_bf16 v[188:191], v[68:71], v[20:23], 0
	v_mfma_f32_16x16x32_bf16 v[192:195], v[68:71], v[24:27], 0
	v_mfma_f32_16x16x32_bf16 v[196:199], v[68:71], v[28:31], 0
	v_fma_f32 v208, v32, v200, v136
	v_fma_f32 v209, v32, v201, v152
	v_fma_f32 v210, v34, v202, v140
	v_fma_f32 v211, v34, v203, v156
	v_fma_f32 v212, v36, v204, v144
	v_fma_f32 v213, v36, v205, v160
	v_fma_f32 v214, v38, v206, v148
	v_fma_f32 v215, v38, v207, v164
	v_fma_f32 v208, -v33, v201, v208
	v_fma_f32 v209, v33, v200, v209
	v_fma_f32 v210, -v35, v203, v210
	v_fma_f32 v211, v35, v202, v211
	v_fma_f32 v212, -v37, v205, v212
	v_fma_f32 v213, v37, v204, v213
	v_fma_f32 v214, -v39, v207, v214
	v_fma_f32 v215, v39, v206, v215
	v_cvt_pk_bf16_f32 v124, v208, v209
	v_cvt_pk_bf16_f32 v125, v210, v211
	v_cvt_pk_bf16_f32 v126, v212, v213
	v_cvt_pk_bf16_f32 v127, v214, v215
	ds_write_b128 v241, v[124:127] offset:0
	v_fma_f32 v200, v32, v208, v137
	v_fma_f32 v201, v32, v209, v153
	v_fma_f32 v202, v34, v210, v141
	v_fma_f32 v203, v34, v211, v157
	v_fma_f32 v204, v36, v212, v145
	v_fma_f32 v205, v36, v213, v161
	v_fma_f32 v206, v38, v214, v149
	v_fma_f32 v207, v38, v215, v165
	v_fma_f32 v200, -v33, v209, v200
	v_fma_f32 v201, v33, v208, v201
	v_fma_f32 v202, -v35, v211, v202
	v_fma_f32 v203, v35, v210, v203
	v_fma_f32 v204, -v37, v213, v204
	v_fma_f32 v205, v37, v212, v205
	v_fma_f32 v206, -v39, v215, v206
	v_fma_f32 v207, v39, v214, v207
	v_cvt_pk_bf16_f32 v124, v200, v201
	v_cvt_pk_bf16_f32 v125, v202, v203
	v_cvt_pk_bf16_f32 v126, v204, v205
	v_cvt_pk_bf16_f32 v127, v206, v207
	ds_write_b128 v241, v[124:127] offset:256
	v_fma_f32 v208, v32, v200, v138
	v_fma_f32 v209, v32, v201, v154
	v_fma_f32 v210, v34, v202, v142
	v_fma_f32 v211, v34, v203, v158
	v_fma_f32 v212, v36, v204, v146
	v_fma_f32 v213, v36, v205, v162
	v_fma_f32 v214, v38, v206, v150
	v_fma_f32 v215, v38, v207, v166
	v_fma_f32 v208, -v33, v201, v208
	v_fma_f32 v209, v33, v200, v209
	v_fma_f32 v210, -v35, v203, v210
	v_fma_f32 v211, v35, v202, v211
	v_fma_f32 v212, -v37, v205, v212
	v_fma_f32 v213, v37, v204, v213
	v_fma_f32 v214, -v39, v207, v214
	v_fma_f32 v215, v39, v206, v215
	v_cvt_pk_bf16_f32 v124, v208, v209
	v_cvt_pk_bf16_f32 v125, v210, v211
	v_cvt_pk_bf16_f32 v126, v212, v213
	v_cvt_pk_bf16_f32 v127, v214, v215
	ds_write_b128 v241, v[124:127] offset:512
	v_fma_f32 v200, v32, v208, v139
	v_fma_f32 v201, v32, v209, v155
	v_fma_f32 v202, v34, v210, v143
	v_fma_f32 v203, v34, v211, v159
	v_fma_f32 v204, v36, v212, v147
	v_fma_f32 v205, v36, v213, v163
	v_fma_f32 v206, v38, v214, v151
	v_fma_f32 v207, v38, v215, v167
	v_fma_f32 v200, -v33, v209, v200
	v_fma_f32 v201, v33, v208, v201
	v_fma_f32 v202, -v35, v211, v202
	v_fma_f32 v203, v35, v210, v203
	v_fma_f32 v204, -v37, v213, v204
	v_fma_f32 v205, v37, v212, v205
	v_fma_f32 v206, -v39, v215, v206
	v_fma_f32 v207, v39, v214, v207
	v_cvt_pk_bf16_f32 v124, v200, v201
	v_cvt_pk_bf16_f32 v125, v202, v203
	v_cvt_pk_bf16_f32 v126, v204, v205
	v_cvt_pk_bf16_f32 v127, v206, v207
	ds_write_b128 v241, v[124:127] offset:768
	s_waitcnt lgkmcnt(0)
; __device__ __forceinline__ unsigned f2bf(float f) { unsigned u = __builtin_bit_cast(unsigned, f); return (u + 0x7fffu + ((u >> 16) & 1u)) >> 16; }
; __device__ __forceinline__ bf16x8 pack8(const float (&f)[8]) { u32x4 h; h.x = pk2(f[0], f[1]); h.y = pk2(f[2], f[3]); h.z = pk2(f[4], f[5]); h.w = pk2(f[6], f[7]); return __builtin_bit_cast(bf16x8, h); }
; template <bool FINAL> __device__ __forceinline__ void phase_s5_scan(const Fr& F) {
;     ...
; #pragma unroll
;         for (int sub = 0; sub < 4; ++sub) {
;             const bf16x8 A1 = __builtin_bit_cast(bf16x8, uc[sub]);
; #pragma unroll
;             for (int nt = 0; nt < 8; ++nt) {
;                 f32x4 acc = {0.f, 0.f, 0.f, 0.f};
;                 acc = __builtin_amdgcn_mfma_f32_16x16x32_bf16(A1, B1[nt], acc, 0, 0, 0);
; #pragma unroll
;                 for (int reg = 0; reg < 4; ++reg) BUl[(4 * lq + reg) * 132 + 16 * nt + l15] = acc[reg];
;             }
;             asm volatile("s_waitcnt lgkmcnt(0)" ::: "memory");
; #pragma unroll 4
;             for (int jj = 0; jj < 16; ++jj) {
;                 const float br_ = BUl[jj * 132 + lane], bi_ = BUl[jj * 132 + 64 + lane];
;                 const float nr = ar * xr - ai * xi + br_, ni = ar * xi + ai * xr + bi_; xr = nr; xi = ni;
;                 if (FINAL) { BUl[jj * 132 + lane] = xr; BUl[jj * 132 + 64 + lane] = xi; }
;             }
;             if (FINAL) {
;                 asm volatile("s_waitcnt lgkmcnt(0)" ::: "memory");
;                 f32x4 acc = {0.f, 0.f, 0.f, 0.f};
; #pragma unroll
;                 for (int ks = 0; ks < 4; ++ks) {
;                     const f32x4 t0 = *(const f32x4*)(BUl + l15 * 132 + 32 * ks + 8 * lq), t1 = *(const f32x4*)(BUl + l15 * 132 + 32 * ks + 8 * lq + 4);
;                     const float xf[8] = {t0.x, t0.y, t0.z, t0.w, t1.x, t1.y, t1.z, t1.w};
;                     acc = __builtin_amdgcn_mfma_f32_16x16x32_bf16(pack8(xf), Chi[ks], acc, 0, 0, 0);
;                 }
; #pragma unroll
;                 for (int reg = 0; reg < 4; ++reg) { const int tok = tokof(s, chunk * 64 + sub * 16 + 4 * lq + reg);
;                     Yb[((size_t)b * TB + tok) * D + g * 16 + l15] = (bf16)f2bf(acc[reg]); }
;                 asm volatile("s_waitcnt lgkmcnt(0)" ::: "memory");
	ds_read_b128 v[216:219], v242 offset:0
	ds_read_b128 v[220:223], v242 offset:64
	ds_read_b128 v[224:227], v242 offset:128
	ds_read_b128 v[228:231], v242 offset:192
	s_waitcnt lgkmcnt(0)
	v_mfma_f32_16x16x32_bf16 v[120:123], v[40:43], v[216:219], 0
	v_mfma_f32_16x16x32_bf16 v[120:123], v[44:47], v[220:223], v[120:123]
	v_mfma_f32_16x16x32_bf16 v[120:123], v[48:51], v[224:227], v[120:123]
	v_mfma_f32_16x16x32_bf16 v[120:123], v[52:55], v[228:231], v[120:123]
	global_load_dwordx4 v[64:67], v238, s[20:21]
	v_add_u32_e32 v238, v238, v243
	s_nop 7
	v_cvt_pk_bf16_f32 v124, v120, v121
	v_cvt_pk_bf16_f32 v125, v122, v123
	s_nop 0
	global_store_dwordx2 v239, v[124:125], s[24:25]
	v_add_u32_e32 v239, v239, v243
	v_mfma_f32_16x16x32_bf16 v[136:139], v[72:75], v[0:3], 0
	v_mfma_f32_16x16x32_bf16 v[140:143], v[72:75], v[4:7], 0
	v_mfma_f32_16x16x32_bf16 v[144:147], v[72:75], v[8:11], 0
	v_mfma_f32_16x16x32_bf16 v[148:151], v[72:75], v[12:15], 0
	v_mfma_f32_16x16x32_bf16 v[152:155], v[72:75], v[16:19], 0
	v_mfma_f32_16x16x32_bf16 v[156:159], v[72:75], v[20:23], 0
	v_mfma_f32_16x16x32_bf16 v[160:163], v[72:75], v[24:27], 0
	v_mfma_f32_16x16x32_bf16 v[164:167], v[72:75], v[28:31], 0
	v_fma_f32 v208, v32, v200, v168
	v_fma_f32 v209, v32, v201, v184
	v_fma_f32 v210, v34, v202, v172
	v_fma_f32 v211, v34, v203, v188
	v_fma_f32 v212, v36, v204, v176
	v_fma_f32 v213, v36, v205, v192
	v_fma_f32 v214, v38, v206, v180
	v_fma_f32 v215, v38, v207, v196
	v_fma_f32 v208, -v33, v201, v208
	v_fma_f32 v209, v33, v200, v209
	v_fma_f32 v210, -v35, v203, v210
	v_fma_f32 v211, v35, v202, v211
	v_fma_f32 v212, -v37, v205, v212
	v_fma_f32 v213, v37, v204, v213
	v_fma_f32 v214, -v39, v207, v214
	v_fma_f32 v215, v39, v206, v215
	v_cvt_pk_bf16_f32 v124, v208, v209
	v_cvt_pk_bf16_f32 v125, v210, v211
	v_cvt_pk_bf16_f32 v126, v212, v213
	v_cvt_pk_bf16_f32 v127, v214, v215
	ds_write_b128 v241, v[124:127] offset:0
	v_fma_f32 v200, v32, v208, v169
	v_fma_f32 v201, v32, v209, v185
	v_fma_f32 v202, v34, v210, v173
	v_fma_f32 v203, v34, v211, v189
	v_fma_f32 v204, v36, v212, v177
	v_fma_f32 v205, v36, v213, v193
	v_fma_f32 v206, v38, v214, v181
	v_fma_f32 v207, v38, v215, v197
	v_fma_f32 v200, -v33, v209, v200
	v_fma_f32 v201, v33, v208, v201
	v_fma_f32 v202, -v35, v211, v202
	v_fma_f32 v203, v35, v210, v203
	v_fma_f32 v204, -v37, v213, v204
	v_fma_f32 v205, v37, v212, v205
	v_fma_f32 v206, -v39, v215, v206
	v_fma_f32 v207, v39, v214, v207
	v_cvt_pk_bf16_f32 v124, v200, v201
	v_cvt_pk_bf16_f32 v125, v202, v203
	v_cvt_pk_bf16_f32 v126, v204, v205
	v_cvt_pk_bf16_f32 v127, v206, v207
	ds_write_b128 v241, v[124:127] offset:256
	v_fma_f32 v208, v32, v200, v170
	v_fma_f32 v209, v32, v201, v186
	v_fma_f32 v210, v34, v202, v174
	v_fma_f32 v211, v34, v203, v190
	v_fma_f32 v212, v36, v204, v178
	v_fma_f32 v213, v36, v205, v194
	v_fma_f32 v214, v38, v206, v182
	v_fma_f32 v215, v38, v207, v198
	v_fma_f32 v208, -v33, v201, v208
	v_fma_f32 v209, v33, v200, v209
	v_fma_f32 v210, -v35, v203, v210
	v_fma_f32 v211, v35, v202, v211
	v_fma_f32 v212, -v37, v205, v212
	v_fma_f32 v213, v37, v204, v213
	v_fma_f32 v214, -v39, v207, v214
	v_fma_f32 v215, v39, v206, v215
	v_cvt_pk_bf16_f32 v124, v208, v209
	v_cvt_pk_bf16_f32 v125, v210, v211
	v_cvt_pk_bf16_f32 v126, v212, v213
	v_cvt_pk_bf16_f32 v127, v214, v215
	ds_write_b128 v241, v[124:127] offset:512
	v_fma_f32 v200, v32, v208, v171
	v_fma_f32 v201, v32, v209, v187
	v_fma_f32 v202, v34, v210, v175
	v_fma_f32 v203, v34, v211, v191
	v_fma_f32 v204, v36, v212, v179
	v_fma_f32 v205, v36, v213, v195
	v_fma_f32 v206, v38, v214, v183
	v_fma_f32 v207, v38, v215, v199
	v_fma_f32 v200, -v33, v209, v200
	v_fma_f32 v201, v33, v208, v201
	v_fma_f32 v202, -v35, v211, v202
	v_fma_f32 v203, v35, v210, v203
	v_fma_f32 v204, -v37, v213, v204
	v_fma_f32 v205, v37, v212, v205
	v_fma_f32 v206, -v39, v215, v206
	v_fma_f32 v207, v39, v214, v207
	v_cvt_pk_bf16_f32 v124, v200, v201
	v_cvt_pk_bf16_f32 v125, v202, v203
	v_cvt_pk_bf16_f32 v126, v204, v205
	v_cvt_pk_bf16_f32 v127, v206, v207
	ds_write_b128 v241, v[124:127] offset:768
	s_waitcnt lgkmcnt(0)
	ds_read_b128 v[216:219], v242 offset:0
	ds_read_b128 v[220:223], v242 offset:64
	ds_read_b128 v[224:227], v242 offset:128
	ds_read_b128 v[228:231], v242 offset:192
	s_waitcnt lgkmcnt(0)
; __device__ __forceinline__ unsigned f2bf(float f) { unsigned u = __builtin_bit_cast(unsigned, f); return (u + 0x7fffu + ((u >> 16) & 1u)) >> 16; }
; __device__ __forceinline__ bf16x8 pack8(const float (&f)[8]) { u32x4 h; h.x = pk2(f[0], f[1]); h.y = pk2(f[2], f[3]); h.z = pk2(f[4], f[5]); h.w = pk2(f[6], f[7]); return __builtin_bit_cast(bf16x8, h); }
; template <bool FINAL> __device__ __forceinline__ void phase_s5_scan(const Fr& F) {
;     ...
; #pragma unroll
;         for (int sub = 0; sub < 4; ++sub) {
;             const bf16x8 A1 = __builtin_bit_cast(bf16x8, uc[sub]);
; #pragma unroll
;             for (int nt = 0; nt < 8; ++nt) {
;                 f32x4 acc = {0.f, 0.f, 0.f, 0.f};
;                 acc = __builtin_amdgcn_mfma_f32_16x16x32_bf16(A1, B1[nt], acc, 0, 0, 0);
; #pragma unroll
;                 for (int reg = 0; reg < 4; ++reg) BUl[(4 * lq + reg) * 132 + 16 * nt + l15] = acc[reg];
;             }
;             asm volatile("s_waitcnt lgkmcnt(0)" ::: "memory");
; #pragma unroll 4
;             for (int jj = 0; jj < 16; ++jj) {
;                 const float br_ = BUl[jj * 132 + lane], bi_ = BUl[jj * 132 + 64 + lane];
;                 const float nr = ar * xr - ai * xi + br_, ni = ar * xi + ai * xr + bi_; xr = nr; xi = ni;
;                 if (FINAL) { BUl[jj * 132 + lane] = xr; BUl[jj * 132 + 64 + lane] = xi; }
;             }
;             if (FINAL) {
;                 asm volatile("s_waitcnt lgkmcnt(0)" ::: "memory");
;                 f32x4 acc = {0.f, 0.f, 0.f, 0.f};
; #pragma unroll
;                 for (int ks = 0; ks < 4; ++ks) {
;                     const f32x4 t0 = *(const f32x4*)(BUl + l15 * 132 + 32 * ks + 8 * lq), t1 = *(const f32x4*)(BUl + l15 * 132 + 32 * ks + 8 * lq + 4);
;                     const float xf[8] = {t0.x, t0.y, t0.z, t0.w, t1.x, t1.y, t1.z, t1.w};
;                     acc = __builtin_amdgcn_mfma_f32_16x16x32_bf16(pack8(xf), Chi[ks], acc, 0, 0, 0);
;                 }
; #pragma unroll
;                 for (int reg = 0; reg < 4; ++reg) { const int tok = tokof(s, chunk * 64 + sub * 16 + 4 * lq + reg);
;                     Yb[((size_t)b * TB + tok) * D + g * 16 + l15] = (bf16)f2bf(acc[reg]); }
;                 asm volatile("s_waitcnt lgkmcnt(0)" ::: "memory");
	v_mfma_f32_16x16x32_bf16 v[120:123], v[40:43], v[216:219], 0
	v_mfma_f32_16x16x32_bf16 v[120:123], v[44:47], v[220:223], v[120:123]
	v_mfma_f32_16x16x32_bf16 v[120:123], v[48:51], v[224:227], v[120:123]
	v_mfma_f32_16x16x32_bf16 v[120:123], v[52:55], v[228:231], v[120:123]
	global_load_dwordx4 v[68:71], v238, s[20:21]
	v_add_u32_e32 v238, v238, v243
	s_nop 7
	v_cvt_pk_bf16_f32 v124, v120, v121
	v_cvt_pk_bf16_f32 v125, v122, v123
	s_nop 0
	global_store_dwordx2 v239, v[124:125], s[24:25]
	v_add_u32_e32 v239, v239, v243
	v_mfma_f32_16x16x32_bf16 v[168:171], v[76:79], v[0:3], 0
	v_mfma_f32_16x16x32_bf16 v[172:175], v[76:79], v[4:7], 0
	v_mfma_f32_16x16x32_bf16 v[176:179], v[76:79], v[8:11], 0
	v_mfma_f32_16x16x32_bf16 v[180:183], v[76:79], v[12:15], 0
	v_mfma_f32_16x16x32_bf16 v[184:187], v[76:79], v[16:19], 0
	v_mfma_f32_16x16x32_bf16 v[188:191], v[76:79], v[20:23], 0
	v_mfma_f32_16x16x32_bf16 v[192:195], v[76:79], v[24:27], 0
	v_mfma_f32_16x16x32_bf16 v[196:199], v[76:79], v[28:31], 0
	v_fma_f32 v208, v32, v200, v136
	v_fma_f32 v209, v32, v201, v152
	v_fma_f32 v210, v34, v202, v140
	v_fma_f32 v211, v34, v203, v156
	v_fma_f32 v212, v36, v204, v144
	v_fma_f32 v213, v36, v205, v160
	v_fma_f32 v214, v38, v206, v148
	v_fma_f32 v215, v38, v207, v164
	v_fma_f32 v208, -v33, v201, v208
	v_fma_f32 v209, v33, v200, v209
	v_fma_f32 v210, -v35, v203, v210
	v_fma_f32 v211, v35, v202, v211
	v_fma_f32 v212, -v37, v205, v212
	v_fma_f32 v213, v37, v204, v213
	v_fma_f32 v214, -v39, v207, v214
	v_fma_f32 v215, v39, v206, v215
	v_cvt_pk_bf16_f32 v124, v208, v209
	v_cvt_pk_bf16_f32 v125, v210, v211
	v_cvt_pk_bf16_f32 v126, v212, v213
	v_cvt_pk_bf16_f32 v127, v214, v215
	ds_write_b128 v241, v[124:127] offset:0
	v_fma_f32 v200, v32, v208, v137
	v_fma_f32 v201, v32, v209, v153
	v_fma_f32 v202, v34, v210, v141
	v_fma_f32 v203, v34, v211, v157
	v_fma_f32 v204, v36, v212, v145
	v_fma_f32 v205, v36, v213, v161
	v_fma_f32 v206, v38, v214, v149
	v_fma_f32 v207, v38, v215, v165
	v_fma_f32 v200, -v33, v209, v200
	v_fma_f32 v201, v33, v208, v201
	v_fma_f32 v202, -v35, v211, v202
	v_fma_f32 v203, v35, v210, v203
	v_fma_f32 v204, -v37, v213, v204
	v_fma_f32 v205, v37, v212, v205
	v_fma_f32 v206, -v39, v215, v206
	v_fma_f32 v207, v39, v214, v207
	v_cvt_pk_bf16_f32 v124, v200, v201
	v_cvt_pk_bf16_f32 v125, v202, v203
	v_cvt_pk_bf16_f32 v126, v204, v205
	v_cvt_pk_bf16_f32 v127, v206, v207
	ds_write_b128 v241, v[124:127] offset:256
	v_fma_f32 v208, v32, v200, v138
	v_fma_f32 v209, v32, v201, v154
	v_fma_f32 v210, v34, v202, v142
	v_fma_f32 v211, v34, v203, v158
	v_fma_f32 v212, v36, v204, v146
	v_fma_f32 v213, v36, v205, v162
	v_fma_f32 v214, v38, v206, v150
	v_fma_f32 v215, v38, v207, v166
	v_fma_f32 v208, -v33, v201, v208
	v_fma_f32 v209, v33, v200, v209
	v_fma_f32 v210, -v35, v203, v210
	v_fma_f32 v211, v35, v202, v211
	v_fma_f32 v212, -v37, v205, v212
	v_fma_f32 v213, v37, v204, v213
	v_fma_f32 v214, -v39, v207, v214
	v_fma_f32 v215, v39, v206, v215
	v_cvt_pk_bf16_f32 v124, v208, v209
	v_cvt_pk_bf16_f32 v125, v210, v211
	v_cvt_pk_bf16_f32 v126, v212, v213
	v_cvt_pk_bf16_f32 v127, v214, v215
	ds_write_b128 v241, v[124:127] offset:512
	v_fma_f32 v200, v32, v208, v139
	v_fma_f32 v201, v32, v209, v155
	v_fma_f32 v202, v34, v210, v143
	v_fma_f32 v203, v34, v211, v159
	v_fma_f32 v204, v36, v212, v147
	v_fma_f32 v205, v36, v213, v163
	v_fma_f32 v206, v38, v214, v151
	v_fma_f32 v207, v38, v215, v167
	v_fma_f32 v200, -v33, v209, v200
	v_fma_f32 v201, v33, v208, v201
	v_fma_f32 v202, -v35, v211, v202
	v_fma_f32 v203, v35, v210, v203
	v_fma_f32 v204, -v37, v213, v204
	v_fma_f32 v205, v37, v212, v205
	v_fma_f32 v206, -v39, v215, v206
	v_fma_f32 v207, v39, v214, v207
	v_cvt_pk_bf16_f32 v124, v200, v201
	v_cvt_pk_bf16_f32 v125, v202, v203
	v_cvt_pk_bf16_f32 v126, v204, v205
	v_cvt_pk_bf16_f32 v127, v206, v207
	ds_write_b128 v241, v[124:127] offset:768
	s_waitcnt lgkmcnt(0)
	ds_read_b128 v[216:219], v242 offset:0
	ds_read_b128 v[220:223], v242 offset:64
	ds_read_b128 v[224:227], v242 offset:128
	ds_read_b128 v[228:231], v242 offset:192
	s_waitcnt lgkmcnt(0)
	v_mfma_f32_16x16x32_bf16 v[120:123], v[40:43], v[216:219], 0
	v_mfma_f32_16x16x32_bf16 v[120:123], v[44:47], v[220:223], v[120:123]
	v_mfma_f32_16x16x32_bf16 v[120:123], v[48:51], v[224:227], v[120:123]
	v_mfma_f32_16x16x32_bf16 v[120:123], v[52:55], v[228:231], v[120:123]
	global_load_dwordx4 v[72:75], v238, s[20:21]
	v_add_u32_e32 v238, v238, v243
	s_nop 7
	v_cvt_pk_bf16_f32 v124, v120, v121
	v_cvt_pk_bf16_f32 v125, v122, v123
	s_nop 0
	global_store_dwordx2 v239, v[124:125], s[24:25]
	v_add_u32_e32 v239, v239, v243
	v_mfma_f32_16x16x32_bf16 v[136:139], v[80:83], v[0:3], 0
	v_mfma_f32_16x16x32_bf16 v[140:143], v[80:83], v[4:7], 0
	v_mfma_f32_16x16x32_bf16 v[144:147], v[80:83], v[8:11], 0
	v_mfma_f32_16x16x32_bf16 v[148:151], v[80:83], v[12:15], 0
	v_mfma_f32_16x16x32_bf16 v[152:155], v[80:83], v[16:19], 0
	v_mfma_f32_16x16x32_bf16 v[156:159], v[80:83], v[20:23], 0
	v_mfma_f32_16x16x32_bf16 v[160:163], v[80:83], v[24:27], 0
	v_mfma_f32_16x16x32_bf16 v[164:167], v[80:83], v[28:31], 0
	v_fma_f32 v208, v32, v200, v168
	v_fma_f32 v209, v32, v201, v184
	v_fma_f32 v210, v34, v202, v172
	v_fma_f32 v211, v34, v203, v188
	v_fma_f32 v212, v36, v204, v176
	v_fma_f32 v213, v36, v205, v192
	v_fma_f32 v214, v38, v206, v180
	v_fma_f32 v215, v38, v207, v196
	v_fma_f32 v208, -v33, v201, v208
	v_fma_f32 v209, v33, v200, v209
	v_fma_f32 v210, -v35, v203, v210
	v_fma_f32 v211, v35, v202, v211
	v_fma_f32 v212, -v37, v205, v212
	v_fma_f32 v213, v37, v204, v213
	v_fma_f32 v214, -v39, v207, v214
	v_fma_f32 v215, v39, v206, v215
	v_cvt_pk_bf16_f32 v124, v208, v209
; __device__ __forceinline__ unsigned f2bf(float f) { unsigned u = __builtin_bit_cast(unsigned, f); return (u + 0x7fffu + ((u >> 16) & 1u)) >> 16; }
; __device__ __forceinline__ bf16x8 pack8(const float (&f)[8]) { u32x4 h; h.x = pk2(f[0], f[1]); h.y = pk2(f[2], f[3]); h.z = pk2(f[4], f[5]); h.w = pk2(f[6], f[7]); return __builtin_bit_cast(bf16x8, h); }
; template <bool FINAL> __device__ __forceinline__ void phase_s5_scan(const Fr& F) {
;     ...
; #pragma unroll
;         for (int sub = 0; sub < 4; ++sub) {
;             const bf16x8 A1 = __builtin_bit_cast(bf16x8, uc[sub]);
; #pragma unroll
;             for (int nt = 0; nt < 8; ++nt) {
;                 f32x4 acc = {0.f, 0.f, 0.f, 0.f};
;                 acc = __builtin_amdgcn_mfma_f32_16x16x32_bf16(A1, B1[nt], acc, 0, 0, 0);
; #pragma unroll
;                 for (int reg = 0; reg < 4; ++reg) BUl[(4 * lq + reg) * 132 + 16 * nt + l15] = acc[reg];
;             }
;             asm volatile("s_waitcnt lgkmcnt(0)" ::: "memory");
; #pragma unroll 4
;             for (int jj = 0; jj < 16; ++jj) {
;                 const float br_ = BUl[jj * 132 + lane], bi_ = BUl[jj * 132 + 64 + lane];
;                 const float nr = ar * xr - ai * xi + br_, ni = ar * xi + ai * xr + bi_; xr = nr; xi = ni;
;                 if (FINAL) { BUl[jj * 132 + lane] = xr; BUl[jj * 132 + 64 + lane] = xi; }
;             }
;             if (FINAL) {
;                 asm volatile("s_waitcnt lgkmcnt(0)" ::: "memory");
;                 f32x4 acc = {0.f, 0.f, 0.f, 0.f};
; #pragma unroll
;                 for (int ks = 0; ks < 4; ++ks) {
;                     const f32x4 t0 = *(const f32x4*)(BUl + l15 * 132 + 32 * ks + 8 * lq), t1 = *(const f32x4*)(BUl + l15 * 132 + 32 * ks + 8 * lq + 4);
;                     const float xf[8] = {t0.x, t0.y, t0.z, t0.w, t1.x, t1.y, t1.z, t1.w};
;                     acc = __builtin_amdgcn_mfma_f32_16x16x32_bf16(pack8(xf), Chi[ks], acc, 0, 0, 0);
;                 }
; #pragma unroll
;                 for (int reg = 0; reg < 4; ++reg) { const int tok = tokof(s, chunk * 64 + sub * 16 + 4 * lq + reg);
;                     Yb[((size_t)b * TB + tok) * D + g * 16 + l15] = (bf16)f2bf(acc[reg]); }
;                 asm volatile("s_waitcnt lgkmcnt(0)" ::: "memory");
	v_cvt_pk_bf16_f32 v125, v210, v211
	v_cvt_pk_bf16_f32 v126, v212, v213
	v_cvt_pk_bf16_f32 v127, v214, v215
	ds_write_b128 v241, v[124:127] offset:0
	v_fma_f32 v200, v32, v208, v169
	v_fma_f32 v201, v32, v209, v185
	v_fma_f32 v202, v34, v210, v173
	v_fma_f32 v203, v34, v211, v189
	v_fma_f32 v204, v36, v212, v177
	v_fma_f32 v205, v36, v213, v193
	v_fma_f32 v206, v38, v214, v181
	v_fma_f32 v207, v38, v215, v197
	v_fma_f32 v200, -v33, v209, v200
	v_fma_f32 v201, v33, v208, v201
	v_fma_f32 v202, -v35, v211, v202
	v_fma_f32 v203, v35, v210, v203
	v_fma_f32 v204, -v37, v213, v204
	v_fma_f32 v205, v37, v212, v205
	v_fma_f32 v206, -v39, v215, v206
	v_fma_f32 v207, v39, v214, v207
	v_cvt_pk_bf16_f32 v124, v200, v201
	v_cvt_pk_bf16_f32 v125, v202, v203
	v_cvt_pk_bf16_f32 v126, v204, v205
	v_cvt_pk_bf16_f32 v127, v206, v207
	ds_write_b128 v241, v[124:127] offset:256
	v_fma_f32 v208, v32, v200, v170
	v_fma_f32 v209, v32, v201, v186
	v_fma_f32 v210, v34, v202, v174
	v_fma_f32 v211, v34, v203, v190
	v_fma_f32 v212, v36, v204, v178
	v_fma_f32 v213, v36, v205, v194
	v_fma_f32 v214, v38, v206, v182
	v_fma_f32 v215, v38, v207, v198
	v_fma_f32 v208, -v33, v201, v208
	v_fma_f32 v209, v33, v200, v209
	v_fma_f32 v210, -v35, v203, v210
	v_fma_f32 v211, v35, v202, v211
	v_fma_f32 v212, -v37, v205, v212
	v_fma_f32 v213, v37, v204, v213
	v_fma_f32 v214, -v39, v207, v214
	v_fma_f32 v215, v39, v206, v215
	v_cvt_pk_bf16_f32 v124, v208, v209
	v_cvt_pk_bf16_f32 v125, v210, v211
	v_cvt_pk_bf16_f32 v126, v212, v213
	v_cvt_pk_bf16_f32 v127, v214, v215
	ds_write_b128 v241, v[124:127] offset:512
	v_fma_f32 v200, v32, v208, v171
	v_fma_f32 v201, v32, v209, v187
	v_fma_f32 v202, v34, v210, v175
	v_fma_f32 v203, v34, v211, v191
	v_fma_f32 v204, v36, v212, v179
	v_fma_f32 v205, v36, v213, v195
	v_fma_f32 v206, v38, v214, v183
	v_fma_f32 v207, v38, v215, v199
	v_fma_f32 v200, -v33, v209, v200
	v_fma_f32 v201, v33, v208, v201
	v_fma_f32 v202, -v35, v211, v202
	v_fma_f32 v203, v35, v210, v203
	v_fma_f32 v204, -v37, v213, v204
	v_fma_f32 v205, v37, v212, v205
	v_fma_f32 v206, -v39, v215, v206
	v_fma_f32 v207, v39, v214, v207
	v_cvt_pk_bf16_f32 v124, v200, v201
	v_cvt_pk_bf16_f32 v125, v202, v203
	v_cvt_pk_bf16_f32 v126, v204, v205
	v_cvt_pk_bf16_f32 v127, v206, v207
	ds_write_b128 v241, v[124:127] offset:768
	s_waitcnt lgkmcnt(0)
	ds_read_b128 v[216:219], v242 offset:0
	ds_read_b128 v[220:223], v242 offset:64
	ds_read_b128 v[224:227], v242 offset:128
	ds_read_b128 v[228:231], v242 offset:192
	s_waitcnt lgkmcnt(0)
	v_mfma_f32_16x16x32_bf16 v[120:123], v[40:43], v[216:219], 0
	v_mfma_f32_16x16x32_bf16 v[120:123], v[44:47], v[220:223], v[120:123]
	v_mfma_f32_16x16x32_bf16 v[120:123], v[48:51], v[224:227], v[120:123]
	v_mfma_f32_16x16x32_bf16 v[120:123], v[52:55], v[228:231], v[120:123]
	global_load_dwordx4 v[76:79], v238, s[20:21]
	v_add_u32_e32 v238, v238, v243
	s_nop 7
	v_cvt_pk_bf16_f32 v124, v120, v121
	v_cvt_pk_bf16_f32 v125, v122, v123
	s_nop 0
	global_store_dwordx2 v239, v[124:125], s[24:25]
	v_add_u32_e32 v239, v239, v243
	v_mfma_f32_16x16x32_bf16 v[168:171], v[84:87], v[0:3], 0
	v_mfma_f32_16x16x32_bf16 v[172:175], v[84:87], v[4:7], 0
	v_mfma_f32_16x16x32_bf16 v[176:179], v[84:87], v[8:11], 0
	v_mfma_f32_16x16x32_bf16 v[180:183], v[84:87], v[12:15], 0
	v_mfma_f32_16x16x32_bf16 v[184:187], v[84:87], v[16:19], 0
	v_mfma_f32_16x16x32_bf16 v[188:191], v[84:87], v[20:23], 0
	v_mfma_f32_16x16x32_bf16 v[192:195], v[84:87], v[24:27], 0
	v_mfma_f32_16x16x32_bf16 v[196:199], v[84:87], v[28:31], 0
	v_fma_f32 v208, v32, v200, v136
	v_fma_f32 v209, v32, v201, v152
	v_fma_f32 v210, v34, v202, v140
	v_fma_f32 v211, v34, v203, v156
	v_fma_f32 v212, v36, v204, v144
	v_fma_f32 v213, v36, v205, v160
	v_fma_f32 v214, v38, v206, v148
	v_fma_f32 v215, v38, v207, v164
	v_fma_f32 v208, -v33, v201, v208
	v_fma_f32 v209, v33, v200, v209
	v_fma_f32 v210, -v35, v203, v210
	v_fma_f32 v211, v35, v202, v211
	v_fma_f32 v212, -v37, v205, v212
	v_fma_f32 v213, v37, v204, v213
	v_fma_f32 v214, -v39, v207, v214
	v_fma_f32 v215, v39, v206, v215
	v_cvt_pk_bf16_f32 v124, v208, v209
	v_cvt_pk_bf16_f32 v125, v210, v211
	v_cvt_pk_bf16_f32 v126, v212, v213
	v_cvt_pk_bf16_f32 v127, v214, v215
	ds_write_b128 v241, v[124:127] offset:0
	v_fma_f32 v200, v32, v208, v137
	v_fma_f32 v201, v32, v209, v153
	v_fma_f32 v202, v34, v210, v141
	v_fma_f32 v203, v34, v211, v157
	v_fma_f32 v204, v36, v212, v145
	v_fma_f32 v205, v36, v213, v161
	v_fma_f32 v206, v38, v214, v149
	v_fma_f32 v207, v38, v215, v165
	v_fma_f32 v200, -v33, v209, v200
	v_fma_f32 v201, v33, v208, v201
	v_fma_f32 v202, -v35, v211, v202
	v_fma_f32 v203, v35, v210, v203
	v_fma_f32 v204, -v37, v213, v204
	v_fma_f32 v205, v37, v212, v205
	v_fma_f32 v206, -v39, v215, v206
	v_fma_f32 v207, v39, v214, v207
	v_cvt_pk_bf16_f32 v124, v200, v201
	v_cvt_pk_bf16_f32 v125, v202, v203
	v_cvt_pk_bf16_f32 v126, v204, v205
	v_cvt_pk_bf16_f32 v127, v206, v207
	ds_write_b128 v241, v[124:127] offset:256
	v_fma_f32 v208, v32, v200, v138
	v_fma_f32 v209, v32, v201, v154
	v_fma_f32 v210, v34, v202, v142
	v_fma_f32 v211, v34, v203, v158
	v_fma_f32 v212, v36, v204, v146
	v_fma_f32 v213, v36, v205, v162
	v_fma_f32 v214, v38, v206, v150
	v_fma_f32 v215, v38, v207, v166
	v_fma_f32 v208, -v33, v201, v208
	v_fma_f32 v209, v33, v200, v209
	v_fma_f32 v210, -v35, v203, v210
	v_fma_f32 v211, v35, v202, v211
	v_fma_f32 v212, -v37, v205, v212
	v_fma_f32 v213, v37, v204, v213
	v_fma_f32 v214, -v39, v207, v214
	v_fma_f32 v215, v39, v206, v215
	v_cvt_pk_bf16_f32 v124, v208, v209
	v_cvt_pk_bf16_f32 v125, v210, v211
	v_cvt_pk_bf16_f32 v126, v212, v213
	v_cvt_pk_bf16_f32 v127, v214, v215
	ds_write_b128 v241, v[124:127] offset:512
	v_fma_f32 v200, v32, v208, v139
	v_fma_f32 v201, v32, v209, v155
	v_fma_f32 v202, v34, v210, v143
	v_fma_f32 v203, v34, v211, v159
	v_fma_f32 v204, v36, v212, v147
	v_fma_f32 v205, v36, v213, v163
	v_fma_f32 v206, v38, v214, v151
	v_fma_f32 v207, v38, v215, v167
	v_fma_f32 v200, -v33, v209, v200
	v_fma_f32 v201, v33, v208, v201
	v_fma_f32 v202, -v35, v211, v202
	v_fma_f32 v203, v35, v210, v203
	v_fma_f32 v204, -v37, v213, v204
	v_fma_f32 v205, v37, v212, v205
	v_fma_f32 v206, -v39, v215, v206
	v_fma_f32 v207, v39, v214, v207
	v_cvt_pk_bf16_f32 v124, v200, v201
	v_cvt_pk_bf16_f32 v125, v202, v203
	v_cvt_pk_bf16_f32 v126, v204, v205
	v_cvt_pk_bf16_f32 v127, v206, v207
	ds_write_b128 v241, v[124:127] offset:768
	s_waitcnt lgkmcnt(0)
; __device__ __forceinline__ unsigned f2bf(float f) { unsigned u = __builtin_bit_cast(unsigned, f); return (u + 0x7fffu + ((u >> 16) & 1u)) >> 16; }
; __device__ __forceinline__ bf16x8 pack8(const float (&f)[8]) { u32x4 h; h.x = pk2(f[0], f[1]); h.y = pk2(f[2], f[3]); h.z = pk2(f[4], f[5]); h.w = pk2(f[6], f[7]); return __builtin_bit_cast(bf16x8, h); }
; template <bool FINAL> __device__ __forceinline__ void phase_s5_scan(const Fr& F) {
;     ...
; #pragma unroll
;         for (int sub = 0; sub < 4; ++sub) {
;             const bf16x8 A1 = __builtin_bit_cast(bf16x8, uc[sub]);
; #pragma unroll
;             for (int nt = 0; nt < 8; ++nt) {
;                 f32x4 acc = {0.f, 0.f, 0.f, 0.f};
;                 acc = __builtin_amdgcn_mfma_f32_16x16x32_bf16(A1, B1[nt], acc, 0, 0, 0);
; #pragma unroll
;                 for (int reg = 0; reg < 4; ++reg) BUl[(4 * lq + reg) * 132 + 16 * nt + l15] = acc[reg];
;             }
;             asm volatile("s_waitcnt lgkmcnt(0)" ::: "memory");
; #pragma unroll 4
;             for (int jj = 0; jj < 16; ++jj) {
;                 const float br_ = BUl[jj * 132 + lane], bi_ = BUl[jj * 132 + 64 + lane];
;                 const float nr = ar * xr - ai * xi + br_, ni = ar * xi + ai * xr + bi_; xr = nr; xi = ni;
;                 if (FINAL) { BUl[jj * 132 + lane] = xr; BUl[jj * 132 + 64 + lane] = xi; }
;             }
;             if (FINAL) {
;                 asm volatile("s_waitcnt lgkmcnt(0)" ::: "memory");
;                 f32x4 acc = {0.f, 0.f, 0.f, 0.f};
; #pragma unroll
;                 for (int ks = 0; ks < 4; ++ks) {
;                     const f32x4 t0 = *(const f32x4*)(BUl + l15 * 132 + 32 * ks + 8 * lq), t1 = *(const f32x4*)(BUl + l15 * 132 + 32 * ks + 8 * lq + 4);
;                     const float xf[8] = {t0.x, t0.y, t0.z, t0.w, t1.x, t1.y, t1.z, t1.w};
;                     acc = __builtin_amdgcn_mfma_f32_16x16x32_bf16(pack8(xf), Chi[ks], acc, 0, 0, 0);
;                 }
; #pragma unroll
;                 for (int reg = 0; reg < 4; ++reg) { const int tok = tokof(s, chunk * 64 + sub * 16 + 4 * lq + reg);
;                     Yb[((size_t)b * TB + tok) * D + g * 16 + l15] = (bf16)f2bf(acc[reg]); }
;                 asm volatile("s_waitcnt lgkmcnt(0)" ::: "memory");
	ds_read_b128 v[216:219], v242 offset:0
	ds_read_b128 v[220:223], v242 offset:64
	ds_read_b128 v[224:227], v242 offset:128
	ds_read_b128 v[228:231], v242 offset:192
	s_waitcnt lgkmcnt(0)
	v_mfma_f32_16x16x32_bf16 v[120:123], v[40:43], v[216:219], 0
	v_mfma_f32_16x16x32_bf16 v[120:123], v[44:47], v[220:223], v[120:123]
	v_mfma_f32_16x16x32_bf16 v[120:123], v[48:51], v[224:227], v[120:123]
	v_mfma_f32_16x16x32_bf16 v[120:123], v[52:55], v[228:231], v[120:123]
	global_load_dwordx4 v[80:83], v238, s[20:21]
	v_add_u32_e32 v238, v238, v243
	s_nop 7
	v_cvt_pk_bf16_f32 v124, v120, v121
	v_cvt_pk_bf16_f32 v125, v122, v123
	s_nop 0
	global_store_dwordx2 v239, v[124:125], s[24:25]
	v_add_u32_e32 v239, v239, v243
	v_mfma_f32_16x16x32_bf16 v[136:139], v[88:91], v[0:3], 0
	v_mfma_f32_16x16x32_bf16 v[140:143], v[88:91], v[4:7], 0
	v_mfma_f32_16x16x32_bf16 v[144:147], v[88:91], v[8:11], 0
	v_mfma_f32_16x16x32_bf16 v[148:151], v[88:91], v[12:15], 0
	v_mfma_f32_16x16x32_bf16 v[152:155], v[88:91], v[16:19], 0
	v_mfma_f32_16x16x32_bf16 v[156:159], v[88:91], v[20:23], 0
	v_mfma_f32_16x16x32_bf16 v[160:163], v[88:91], v[24:27], 0
	v_mfma_f32_16x16x32_bf16 v[164:167], v[88:91], v[28:31], 0
	v_fma_f32 v208, v32, v200, v168
	v_fma_f32 v209, v32, v201, v184
	v_fma_f32 v210, v34, v202, v172
	v_fma_f32 v211, v34, v203, v188
	v_fma_f32 v212, v36, v204, v176
	v_fma_f32 v213, v36, v205, v192
	v_fma_f32 v214, v38, v206, v180
	v_fma_f32 v215, v38, v207, v196
	v_fma_f32 v208, -v33, v201, v208
	v_fma_f32 v209, v33, v200, v209
	v_fma_f32 v210, -v35, v203, v210
	v_fma_f32 v211, v35, v202, v211
	v_fma_f32 v212, -v37, v205, v212
	v_fma_f32 v213, v37, v204, v213
	v_fma_f32 v214, -v39, v207, v214
	v_fma_f32 v215, v39, v206, v215
	v_cvt_pk_bf16_f32 v124, v208, v209
	v_cvt_pk_bf16_f32 v125, v210, v211
	v_cvt_pk_bf16_f32 v126, v212, v213
	v_cvt_pk_bf16_f32 v127, v214, v215
	ds_write_b128 v241, v[124:127] offset:0
	v_fma_f32 v200, v32, v208, v169
	v_fma_f32 v201, v32, v209, v185
	v_fma_f32 v202, v34, v210, v173
	v_fma_f32 v203, v34, v211, v189
	v_fma_f32 v204, v36, v212, v177
	v_fma_f32 v205, v36, v213, v193
	v_fma_f32 v206, v38, v214, v181
	v_fma_f32 v207, v38, v215, v197
	v_fma_f32 v200, -v33, v209, v200
	v_fma_f32 v201, v33, v208, v201
	v_fma_f32 v202, -v35, v211, v202
	v_fma_f32 v203, v35, v210, v203
	v_fma_f32 v204, -v37, v213, v204
	v_fma_f32 v205, v37, v212, v205
	v_fma_f32 v206, -v39, v215, v206
	v_fma_f32 v207, v39, v214, v207
	v_cvt_pk_bf16_f32 v124, v200, v201
	v_cvt_pk_bf16_f32 v125, v202, v203
	v_cvt_pk_bf16_f32 v126, v204, v205
	v_cvt_pk_bf16_f32 v127, v206, v207
	ds_write_b128 v241, v[124:127] offset:256
	v_fma_f32 v208, v32, v200, v170
	v_fma_f32 v209, v32, v201, v186
	v_fma_f32 v210, v34, v202, v174
	v_fma_f32 v211, v34, v203, v190
	v_fma_f32 v212, v36, v204, v178
	v_fma_f32 v213, v36, v205, v194
	v_fma_f32 v214, v38, v206, v182
	v_fma_f32 v215, v38, v207, v198
	v_fma_f32 v208, -v33, v201, v208
	v_fma_f32 v209, v33, v200, v209
	v_fma_f32 v210, -v35, v203, v210
	v_fma_f32 v211, v35, v202, v211
	v_fma_f32 v212, -v37, v205, v212
	v_fma_f32 v213, v37, v204, v213
	v_fma_f32 v214, -v39, v207, v214
	v_fma_f32 v215, v39, v206, v215
	v_cvt_pk_bf16_f32 v124, v208, v209
	v_cvt_pk_bf16_f32 v125, v210, v211
	v_cvt_pk_bf16_f32 v126, v212, v213
	v_cvt_pk_bf16_f32 v127, v214, v215
	ds_write_b128 v241, v[124:127] offset:512
	v_fma_f32 v200, v32, v208, v171
	v_fma_f32 v201, v32, v209, v187
	v_fma_f32 v202, v34, v210, v175
	v_fma_f32 v203, v34, v211, v191
	v_fma_f32 v204, v36, v212, v179
	v_fma_f32 v205, v36, v213, v195
	v_fma_f32 v206, v38, v214, v183
	v_fma_f32 v207, v38, v215, v199
	v_fma_f32 v200, -v33, v209, v200
	v_fma_f32 v201, v33, v208, v201
	v_fma_f32 v202, -v35, v211, v202
	v_fma_f32 v203, v35, v210, v203
	v_fma_f32 v204, -v37, v213, v204
	v_fma_f32 v205, v37, v212, v205
	v_fma_f32 v206, -v39, v215, v206
	v_fma_f32 v207, v39, v214, v207
	v_cvt_pk_bf16_f32 v124, v200, v201
	v_cvt_pk_bf16_f32 v125, v202, v203
	v_cvt_pk_bf16_f32 v126, v204, v205
	v_cvt_pk_bf16_f32 v127, v206, v207
	ds_write_b128 v241, v[124:127] offset:768
	s_waitcnt lgkmcnt(0)
	ds_read_b128 v[216:219], v242 offset:0
	ds_read_b128 v[220:223], v242 offset:64
	ds_read_b128 v[224:227], v242 offset:128
	ds_read_b128 v[228:231], v242 offset:192
	s_waitcnt lgkmcnt(0)
; __device__ __forceinline__ unsigned f2bf(float f) { unsigned u = __builtin_bit_cast(unsigned, f); return (u + 0x7fffu + ((u >> 16) & 1u)) >> 16; }
; __device__ __forceinline__ bf16x8 pack8(const float (&f)[8]) { u32x4 h; h.x = pk2(f[0], f[1]); h.y = pk2(f[2], f[3]); h.z = pk2(f[4], f[5]); h.w = pk2(f[6], f[7]); return __builtin_bit_cast(bf16x8, h); }
; template <bool FINAL> __device__ __forceinline__ void phase_s5_scan(const Fr& F) {
;     ...
; #pragma unroll
;         for (int sub = 0; sub < 4; ++sub) {
;             const bf16x8 A1 = __builtin_bit_cast(bf16x8, uc[sub]);
; #pragma unroll
;             for (int nt = 0; nt < 8; ++nt) {
;                 f32x4 acc = {0.f, 0.f, 0.f, 0.f};
;                 acc = __builtin_amdgcn_mfma_f32_16x16x32_bf16(A1, B1[nt], acc, 0, 0, 0);
; #pragma unroll
;                 for (int reg = 0; reg < 4; ++reg) BUl[(4 * lq + reg) * 132 + 16 * nt + l15] = acc[reg];
;             }
;             asm volatile("s_waitcnt lgkmcnt(0)" ::: "memory");
; #pragma unroll 4
;             for (int jj = 0; jj < 16; ++jj) {
;                 const float br_ = BUl[jj * 132 + lane], bi_ = BUl[jj * 132 + 64 + lane];
;                 const float nr = ar * xr - ai * xi + br_, ni = ar * xi + ai * xr + bi_; xr = nr; xi = ni;
;                 if (FINAL) { BUl[jj * 132 + lane] = xr; BUl[jj * 132 + 64 + lane] = xi; }
;             }
;             if (FINAL) {
;                 asm volatile("s_waitcnt lgkmcnt(0)" ::: "memory");
;                 f32x4 acc = {0.f, 0.f, 0.f, 0.f};
; #pragma unroll
;                 for (int ks = 0; ks < 4; ++ks) {
;                     const f32x4 t0 = *(const f32x4*)(BUl + l15 * 132 + 32 * ks + 8 * lq), t1 = *(const f32x4*)(BUl + l15 * 132 + 32 * ks + 8 * lq + 4);
;                     const float xf[8] = {t0.x, t0.y, t0.z, t0.w, t1.x, t1.y, t1.z, t1.w};
;                     acc = __builtin_amdgcn_mfma_f32_16x16x32_bf16(pack8(xf), Chi[ks], acc, 0, 0, 0);
;                 }
; #pragma unroll
;                 for (int reg = 0; reg < 4; ++reg) { const int tok = tokof(s, chunk * 64 + sub * 16 + 4 * lq + reg);
;                     Yb[((size_t)b * TB + tok) * D + g * 16 + l15] = (bf16)f2bf(acc[reg]); }
;                 asm volatile("s_waitcnt lgkmcnt(0)" ::: "memory");
	v_mfma_f32_16x16x32_bf16 v[120:123], v[40:43], v[216:219], 0
	v_mfma_f32_16x16x32_bf16 v[120:123], v[44:47], v[220:223], v[120:123]
	v_mfma_f32_16x16x32_bf16 v[120:123], v[48:51], v[224:227], v[120:123]
	v_mfma_f32_16x16x32_bf16 v[120:123], v[52:55], v[228:231], v[120:123]
	global_load_dwordx4 v[84:87], v238, s[20:21]
	v_add_u32_e32 v238, v238, v243
	s_nop 7
	v_cvt_pk_bf16_f32 v124, v120, v121
	v_cvt_pk_bf16_f32 v125, v122, v123
	s_nop 0
	global_store_dwordx2 v239, v[124:125], s[24:25]
	v_add_u32_e32 v239, v239, v243
	v_mfma_f32_16x16x32_bf16 v[168:171], v[92:95], v[0:3], 0
	v_mfma_f32_16x16x32_bf16 v[172:175], v[92:95], v[4:7], 0
	v_mfma_f32_16x16x32_bf16 v[176:179], v[92:95], v[8:11], 0
	v_mfma_f32_16x16x32_bf16 v[180:183], v[92:95], v[12:15], 0
	v_mfma_f32_16x16x32_bf16 v[184:187], v[92:95], v[16:19], 0
	v_mfma_f32_16x16x32_bf16 v[188:191], v[92:95], v[20:23], 0
	v_mfma_f32_16x16x32_bf16 v[192:195], v[92:95], v[24:27], 0
	v_mfma_f32_16x16x32_bf16 v[196:199], v[92:95], v[28:31], 0
	v_fma_f32 v208, v32, v200, v136
	v_fma_f32 v209, v32, v201, v152
	v_fma_f32 v210, v34, v202, v140
	v_fma_f32 v211, v34, v203, v156
	v_fma_f32 v212, v36, v204, v144
	v_fma_f32 v213, v36, v205, v160
	v_fma_f32 v214, v38, v206, v148
	v_fma_f32 v215, v38, v207, v164
	v_fma_f32 v208, -v33, v201, v208
	v_fma_f32 v209, v33, v200, v209
	v_fma_f32 v210, -v35, v203, v210
	v_fma_f32 v211, v35, v202, v211
	v_fma_f32 v212, -v37, v205, v212
	v_fma_f32 v213, v37, v204, v213
	v_fma_f32 v214, -v39, v207, v214
	v_fma_f32 v215, v39, v206, v215
	v_cvt_pk_bf16_f32 v124, v208, v209
	v_cvt_pk_bf16_f32 v125, v210, v211
	v_cvt_pk_bf16_f32 v126, v212, v213
	v_cvt_pk_bf16_f32 v127, v214, v215
	ds_write_b128 v241, v[124:127] offset:0
	v_fma_f32 v200, v32, v208, v137
	v_fma_f32 v201, v32, v209, v153
	v_fma_f32 v202, v34, v210, v141
	v_fma_f32 v203, v34, v211, v157
	v_fma_f32 v204, v36, v212, v145
	v_fma_f32 v205, v36, v213, v161
	v_fma_f32 v206, v38, v214, v149
	v_fma_f32 v207, v38, v215, v165
	v_fma_f32 v200, -v33, v209, v200
	v_fma_f32 v201, v33, v208, v201
	v_fma_f32 v202, -v35, v211, v202
	v_fma_f32 v203, v35, v210, v203
	v_fma_f32 v204, -v37, v213, v204
	v_fma_f32 v205, v37, v212, v205
	v_fma_f32 v206, -v39, v215, v206
	v_fma_f32 v207, v39, v214, v207
	v_cvt_pk_bf16_f32 v124, v200, v201
	v_cvt_pk_bf16_f32 v125, v202, v203
	v_cvt_pk_bf16_f32 v126, v204, v205
	v_cvt_pk_bf16_f32 v127, v206, v207
	ds_write_b128 v241, v[124:127] offset:256
	v_fma_f32 v208, v32, v200, v138
	v_fma_f32 v209, v32, v201, v154
	v_fma_f32 v210, v34, v202, v142
	v_fma_f32 v211, v34, v203, v158
	v_fma_f32 v212, v36, v204, v146
	v_fma_f32 v213, v36, v205, v162
	v_fma_f32 v214, v38, v206, v150
	v_fma_f32 v215, v38, v207, v166
	v_fma_f32 v208, -v33, v201, v208
	v_fma_f32 v209, v33, v200, v209
	v_fma_f32 v210, -v35, v203, v210
	v_fma_f32 v211, v35, v202, v211
	v_fma_f32 v212, -v37, v205, v212
	v_fma_f32 v213, v37, v204, v213
	v_fma_f32 v214, -v39, v207, v214
	v_fma_f32 v215, v39, v206, v215
	v_cvt_pk_bf16_f32 v124, v208, v209
	v_cvt_pk_bf16_f32 v125, v210, v211
	v_cvt_pk_bf16_f32 v126, v212, v213
	v_cvt_pk_bf16_f32 v127, v214, v215
	ds_write_b128 v241, v[124:127] offset:512
	v_fma_f32 v200, v32, v208, v139
	v_fma_f32 v201, v32, v209, v155
	v_fma_f32 v202, v34, v210, v143
	v_fma_f32 v203, v34, v211, v159
	v_fma_f32 v204, v36, v212, v147
	v_fma_f32 v205, v36, v213, v163
	v_fma_f32 v206, v38, v214, v151
	v_fma_f32 v207, v38, v215, v167
	v_fma_f32 v200, -v33, v209, v200
	v_fma_f32 v201, v33, v208, v201
	v_fma_f32 v202, -v35, v211, v202
	v_fma_f32 v203, v35, v210, v203
	v_fma_f32 v204, -v37, v213, v204
	v_fma_f32 v205, v37, v212, v205
	v_fma_f32 v206, -v39, v215, v206
	v_fma_f32 v207, v39, v214, v207
	v_cvt_pk_bf16_f32 v124, v200, v201
	v_cvt_pk_bf16_f32 v125, v202, v203
	v_cvt_pk_bf16_f32 v126, v204, v205
	v_cvt_pk_bf16_f32 v127, v206, v207
	ds_write_b128 v241, v[124:127] offset:768
	s_waitcnt lgkmcnt(0)
	ds_read_b128 v[216:219], v242 offset:0
	ds_read_b128 v[220:223], v242 offset:64
	ds_read_b128 v[224:227], v242 offset:128
	ds_read_b128 v[228:231], v242 offset:192
	s_waitcnt lgkmcnt(0)
	v_mfma_f32_16x16x32_bf16 v[120:123], v[40:43], v[216:219], 0
	v_mfma_f32_16x16x32_bf16 v[120:123], v[44:47], v[220:223], v[120:123]
	v_mfma_f32_16x16x32_bf16 v[120:123], v[48:51], v[224:227], v[120:123]
	v_mfma_f32_16x16x32_bf16 v[120:123], v[52:55], v[228:231], v[120:123]
	global_load_dwordx4 v[88:91], v238, s[20:21]
	v_add_u32_e32 v238, v238, v243
	s_nop 7
	v_cvt_pk_bf16_f32 v124, v120, v121
	v_cvt_pk_bf16_f32 v125, v122, v123
	s_nop 0
	global_store_dwordx2 v239, v[124:125], s[24:25]
	v_add_u32_e32 v239, v239, v243
	v_mfma_f32_16x16x32_bf16 v[136:139], v[96:99], v[0:3], 0
	v_mfma_f32_16x16x32_bf16 v[140:143], v[96:99], v[4:7], 0
	v_mfma_f32_16x16x32_bf16 v[144:147], v[96:99], v[8:11], 0
	v_mfma_f32_16x16x32_bf16 v[148:151], v[96:99], v[12:15], 0
	v_mfma_f32_16x16x32_bf16 v[152:155], v[96:99], v[16:19], 0
	v_mfma_f32_16x16x32_bf16 v[156:159], v[96:99], v[20:23], 0
	v_mfma_f32_16x16x32_bf16 v[160:163], v[96:99], v[24:27], 0
	v_mfma_f32_16x16x32_bf16 v[164:167], v[96:99], v[28:31], 0
	v_fma_f32 v208, v32, v200, v168
	v_fma_f32 v209, v32, v201, v184
	v_fma_f32 v210, v34, v202, v172
	v_fma_f32 v211, v34, v203, v188
	v_fma_f32 v212, v36, v204, v176
	v_fma_f32 v213, v36, v205, v192
	v_fma_f32 v214, v38, v206, v180
	v_fma_f32 v215, v38, v207, v196
	v_fma_f32 v208, -v33, v201, v208
	v_fma_f32 v209, v33, v200, v209
	v_fma_f32 v210, -v35, v203, v210
	v_fma_f32 v211, v35, v202, v211
	v_fma_f32 v212, -v37, v205, v212
	v_fma_f32 v213, v37, v204, v213
	v_fma_f32 v214, -v39, v207, v214
	v_fma_f32 v215, v39, v206, v215
	v_cvt_pk_bf16_f32 v124, v208, v209
; __device__ __forceinline__ unsigned f2bf(float f) { unsigned u = __builtin_bit_cast(unsigned, f); return (u + 0x7fffu + ((u >> 16) & 1u)) >> 16; }
; __device__ __forceinline__ bf16x8 pack8(const float (&f)[8]) { u32x4 h; h.x = pk2(f[0], f[1]); h.y = pk2(f[2], f[3]); h.z = pk2(f[4], f[5]); h.w = pk2(f[6], f[7]); return __builtin_bit_cast(bf16x8, h); }
; template <bool FINAL> __device__ __forceinline__ void phase_s5_scan(const Fr& F) {
;     ...
; #pragma unroll
;         for (int sub = 0; sub < 4; ++sub) {
;             const bf16x8 A1 = __builtin_bit_cast(bf16x8, uc[sub]);
; #pragma unroll
;             for (int nt = 0; nt < 8; ++nt) {
;                 f32x4 acc = {0.f, 0.f, 0.f, 0.f};
;                 acc = __builtin_amdgcn_mfma_f32_16x16x32_bf16(A1, B1[nt], acc, 0, 0, 0);
; #pragma unroll
;                 for (int reg = 0; reg < 4; ++reg) BUl[(4 * lq + reg) * 132 + 16 * nt + l15] = acc[reg];
;             }
;             asm volatile("s_waitcnt lgkmcnt(0)" ::: "memory");
; #pragma unroll 4
;             for (int jj = 0; jj < 16; ++jj) {
;                 const float br_ = BUl[jj * 132 + lane], bi_ = BUl[jj * 132 + 64 + lane];
;                 const float nr = ar * xr - ai * xi + br_, ni = ar * xi + ai * xr + bi_; xr = nr; xi = ni;
;                 if (FINAL) { BUl[jj * 132 + lane] = xr; BUl[jj * 132 + 64 + lane] = xi; }
;             }
;             if (FINAL) {
;                 asm volatile("s_waitcnt lgkmcnt(0)" ::: "memory");
;                 f32x4 acc = {0.f, 0.f, 0.f, 0.f};
; #pragma unroll
;                 for (int ks = 0; ks < 4; ++ks) {
;                     const f32x4 t0 = *(const f32x4*)(BUl + l15 * 132 + 32 * ks + 8 * lq), t1 = *(const f32x4*)(BUl + l15 * 132 + 32 * ks + 8 * lq + 4);
;                     const float xf[8] = {t0.x, t0.y, t0.z, t0.w, t1.x, t1.y, t1.z, t1.w};
;                     acc = __builtin_amdgcn_mfma_f32_16x16x32_bf16(pack8(xf), Chi[ks], acc, 0, 0, 0);
;                 }
; #pragma unroll
;                 for (int reg = 0; reg < 4; ++reg) { const int tok = tokof(s, chunk * 64 + sub * 16 + 4 * lq + reg);
;                     Yb[((size_t)b * TB + tok) * D + g * 16 + l15] = (bf16)f2bf(acc[reg]); }
;                 asm volatile("s_waitcnt lgkmcnt(0)" ::: "memory");
	v_cvt_pk_bf16_f32 v125, v210, v211
	v_cvt_pk_bf16_f32 v126, v212, v213
	v_cvt_pk_bf16_f32 v127, v214, v215
	ds_write_b128 v241, v[124:127] offset:0
	v_fma_f32 v200, v32, v208, v169
	v_fma_f32 v201, v32, v209, v185
	v_fma_f32 v202, v34, v210, v173
	v_fma_f32 v203, v34, v211, v189
	v_fma_f32 v204, v36, v212, v177
	v_fma_f32 v205, v36, v213, v193
	v_fma_f32 v206, v38, v214, v181
	v_fma_f32 v207, v38, v215, v197
	v_fma_f32 v200, -v33, v209, v200
	v_fma_f32 v201, v33, v208, v201
	v_fma_f32 v202, -v35, v211, v202
	v_fma_f32 v203, v35, v210, v203
	v_fma_f32 v204, -v37, v213, v204
	v_fma_f32 v205, v37, v212, v205
	v_fma_f32 v206, -v39, v215, v206
	v_fma_f32 v207, v39, v214, v207
	v_cvt_pk_bf16_f32 v124, v200, v201
	v_cvt_pk_bf16_f32 v125, v202, v203
	v_cvt_pk_bf16_f32 v126, v204, v205
	v_cvt_pk_bf16_f32 v127, v206, v207
	ds_write_b128 v241, v[124:127] offset:256
	v_fma_f32 v208, v32, v200, v170
	v_fma_f32 v209, v32, v201, v186
	v_fma_f32 v210, v34, v202, v174
	v_fma_f32 v211, v34, v203, v190
	v_fma_f32 v212, v36, v204, v178
	v_fma_f32 v213, v36, v205, v194
	v_fma_f32 v214, v38, v206, v182
	v_fma_f32 v215, v38, v207, v198
	v_fma_f32 v208, -v33, v201, v208
	v_fma_f32 v209, v33, v200, v209
	v_fma_f32 v210, -v35, v203, v210
	v_fma_f32 v211, v35, v202, v211
	v_fma_f32 v212, -v37, v205, v212
	v_fma_f32 v213, v37, v204, v213
	v_fma_f32 v214, -v39, v207, v214
	v_fma_f32 v215, v39, v206, v215
	v_cvt_pk_bf16_f32 v124, v208, v209
	v_cvt_pk_bf16_f32 v125, v210, v211
	v_cvt_pk_bf16_f32 v126, v212, v213
	v_cvt_pk_bf16_f32 v127, v214, v215
	ds_write_b128 v241, v[124:127] offset:512
	v_fma_f32 v200, v32, v208, v171
	v_fma_f32 v201, v32, v209, v187
	v_fma_f32 v202, v34, v210, v175
	v_fma_f32 v203, v34, v211, v191
	v_fma_f32 v204, v36, v212, v179
	v_fma_f32 v205, v36, v213, v195
	v_fma_f32 v206, v38, v214, v183
	v_fma_f32 v207, v38, v215, v199
	v_fma_f32 v200, -v33, v209, v200
	v_fma_f32 v201, v33, v208, v201
	v_fma_f32 v202, -v35, v211, v202
	v_fma_f32 v203, v35, v210, v203
	v_fma_f32 v204, -v37, v213, v204
	v_fma_f32 v205, v37, v212, v205
	v_fma_f32 v206, -v39, v215, v206
	v_fma_f32 v207, v39, v214, v207
	v_cvt_pk_bf16_f32 v124, v200, v201
	v_cvt_pk_bf16_f32 v125, v202, v203
	v_cvt_pk_bf16_f32 v126, v204, v205
	v_cvt_pk_bf16_f32 v127, v206, v207
	ds_write_b128 v241, v[124:127] offset:768
	s_waitcnt lgkmcnt(0)
	ds_read_b128 v[216:219], v242 offset:0
	ds_read_b128 v[220:223], v242 offset:64
	ds_read_b128 v[224:227], v242 offset:128
	ds_read_b128 v[228:231], v242 offset:192
	s_waitcnt lgkmcnt(0)
	v_mfma_f32_16x16x32_bf16 v[120:123], v[40:43], v[216:219], 0
	v_mfma_f32_16x16x32_bf16 v[120:123], v[44:47], v[220:223], v[120:123]
	v_mfma_f32_16x16x32_bf16 v[120:123], v[48:51], v[224:227], v[120:123]
	v_mfma_f32_16x16x32_bf16 v[120:123], v[52:55], v[228:231], v[120:123]
	global_load_dwordx4 v[92:95], v238, s[20:21]
	v_add_u32_e32 v238, v238, v243
	s_nop 7
	v_cvt_pk_bf16_f32 v124, v120, v121
	v_cvt_pk_bf16_f32 v125, v122, v123
	s_nop 0
	global_store_dwordx2 v239, v[124:125], s[24:25]
	v_add_u32_e32 v239, v239, v243
	v_mfma_f32_16x16x32_bf16 v[168:171], v[100:103], v[0:3], 0
	v_mfma_f32_16x16x32_bf16 v[172:175], v[100:103], v[4:7], 0
	v_mfma_f32_16x16x32_bf16 v[176:179], v[100:103], v[8:11], 0
	v_mfma_f32_16x16x32_bf16 v[180:183], v[100:103], v[12:15], 0
	v_mfma_f32_16x16x32_bf16 v[184:187], v[100:103], v[16:19], 0
	v_mfma_f32_16x16x32_bf16 v[188:191], v[100:103], v[20:23], 0
	v_mfma_f32_16x16x32_bf16 v[192:195], v[100:103], v[24:27], 0
	v_mfma_f32_16x16x32_bf16 v[196:199], v[100:103], v[28:31], 0
	v_fma_f32 v208, v32, v200, v136
	v_fma_f32 v209, v32, v201, v152
	v_fma_f32 v210, v34, v202, v140
	v_fma_f32 v211, v34, v203, v156
	v_fma_f32 v212, v36, v204, v144
	v_fma_f32 v213, v36, v205, v160
	v_fma_f32 v214, v38, v206, v148
	v_fma_f32 v215, v38, v207, v164
	v_fma_f32 v208, -v33, v201, v208
	v_fma_f32 v209, v33, v200, v209
	v_fma_f32 v210, -v35, v203, v210
	v_fma_f32 v211, v35, v202, v211
	v_fma_f32 v212, -v37, v205, v212
	v_fma_f32 v213, v37, v204, v213
	v_fma_f32 v214, -v39, v207, v214
	v_fma_f32 v215, v39, v206, v215
	v_cvt_pk_bf16_f32 v124, v208, v209
	v_cvt_pk_bf16_f32 v125, v210, v211
	v_cvt_pk_bf16_f32 v126, v212, v213
	v_cvt_pk_bf16_f32 v127, v214, v215
	ds_write_b128 v241, v[124:127] offset:0
	v_fma_f32 v200, v32, v208, v137
	v_fma_f32 v201, v32, v209, v153
	v_fma_f32 v202, v34, v210, v141
	v_fma_f32 v203, v34, v211, v157
	v_fma_f32 v204, v36, v212, v145
	v_fma_f32 v205, v36, v213, v161
	v_fma_f32 v206, v38, v214, v149
	v_fma_f32 v207, v38, v215, v165
	v_fma_f32 v200, -v33, v209, v200
	v_fma_f32 v201, v33, v208, v201
	v_fma_f32 v202, -v35, v211, v202
	v_fma_f32 v203, v35, v210, v203
	v_fma_f32 v204, -v37, v213, v204
	v_fma_f32 v205, v37, v212, v205
	v_fma_f32 v206, -v39, v215, v206
	v_fma_f32 v207, v39, v214, v207
	v_cvt_pk_bf16_f32 v124, v200, v201
	v_cvt_pk_bf16_f32 v125, v202, v203
	v_cvt_pk_bf16_f32 v126, v204, v205
	v_cvt_pk_bf16_f32 v127, v206, v207
	ds_write_b128 v241, v[124:127] offset:256
	v_fma_f32 v208, v32, v200, v138
	v_fma_f32 v209, v32, v201, v154
	v_fma_f32 v210, v34, v202, v142
	v_fma_f32 v211, v34, v203, v158
	v_fma_f32 v212, v36, v204, v146
	v_fma_f32 v213, v36, v205, v162
	v_fma_f32 v214, v38, v206, v150
	v_fma_f32 v215, v38, v207, v166
	v_fma_f32 v208, -v33, v201, v208
	v_fma_f32 v209, v33, v200, v209
	v_fma_f32 v210, -v35, v203, v210
	v_fma_f32 v211, v35, v202, v211
	v_fma_f32 v212, -v37, v205, v212
	v_fma_f32 v213, v37, v204, v213
	v_fma_f32 v214, -v39, v207, v214
	v_fma_f32 v215, v39, v206, v215
	v_cvt_pk_bf16_f32 v124, v208, v209
	v_cvt_pk_bf16_f32 v125, v210, v211
	v_cvt_pk_bf16_f32 v126, v212, v213
	v_cvt_pk_bf16_f32 v127, v214, v215
	ds_write_b128 v241, v[124:127] offset:512
	v_fma_f32 v200, v32, v208, v139
	v_fma_f32 v201, v32, v209, v155
	v_fma_f32 v202, v34, v210, v143
	v_fma_f32 v203, v34, v211, v159
	v_fma_f32 v204, v36, v212, v147
	v_fma_f32 v205, v36, v213, v163
	v_fma_f32 v206, v38, v214, v151
	v_fma_f32 v207, v38, v215, v167
	v_fma_f32 v200, -v33, v209, v200
	v_fma_f32 v201, v33, v208, v201
	v_fma_f32 v202, -v35, v211, v202
	v_fma_f32 v203, v35, v210, v203
	v_fma_f32 v204, -v37, v213, v204
	v_fma_f32 v205, v37, v212, v205
	v_fma_f32 v206, -v39, v215, v206
	v_fma_f32 v207, v39, v214, v207
	v_cvt_pk_bf16_f32 v124, v200, v201
	v_cvt_pk_bf16_f32 v125, v202, v203
	v_cvt_pk_bf16_f32 v126, v204, v205
	v_cvt_pk_bf16_f32 v127, v206, v207
	ds_write_b128 v241, v[124:127] offset:768
	s_waitcnt lgkmcnt(0)
; __device__ __forceinline__ unsigned f2bf(float f) { unsigned u = __builtin_bit_cast(unsigned, f); return (u + 0x7fffu + ((u >> 16) & 1u)) >> 16; }
; __device__ __forceinline__ bf16x8 pack8(const float (&f)[8]) { u32x4 h; h.x = pk2(f[0], f[1]); h.y = pk2(f[2], f[3]); h.z = pk2(f[4], f[5]); h.w = pk2(f[6], f[7]); return __builtin_bit_cast(bf16x8, h); }
; template <bool FINAL> __device__ __forceinline__ void phase_s5_scan(const Fr& F) {
;     ...
; #pragma unroll
;         for (int sub = 0; sub < 4; ++sub) {
;             const bf16x8 A1 = __builtin_bit_cast(bf16x8, uc[sub]);
; #pragma unroll
;             for (int nt = 0; nt < 8; ++nt) {
;                 f32x4 acc = {0.f, 0.f, 0.f, 0.f};
;                 acc = __builtin_amdgcn_mfma_f32_16x16x32_bf16(A1, B1[nt], acc, 0, 0, 0);
; #pragma unroll
;                 for (int reg = 0; reg < 4; ++reg) BUl[(4 * lq + reg) * 132 + 16 * nt + l15] = acc[reg];
;             }
;             asm volatile("s_waitcnt lgkmcnt(0)" ::: "memory");
; #pragma unroll 4
;             for (int jj = 0; jj < 16; ++jj) {
;                 const float br_ = BUl[jj * 132 + lane], bi_ = BUl[jj * 132 + 64 + lane];
;                 const float nr = ar * xr - ai * xi + br_, ni = ar * xi + ai * xr + bi_; xr = nr; xi = ni;
;                 if (FINAL) { BUl[jj * 132 + lane] = xr; BUl[jj * 132 + 64 + lane] = xi; }
;             }
;             if (FINAL) {
;                 asm volatile("s_waitcnt lgkmcnt(0)" ::: "memory");
;                 f32x4 acc = {0.f, 0.f, 0.f, 0.f};
; #pragma unroll
;                 for (int ks = 0; ks < 4; ++ks) {
;                     const f32x4 t0 = *(const f32x4*)(BUl + l15 * 132 + 32 * ks + 8 * lq), t1 = *(const f32x4*)(BUl + l15 * 132 + 32 * ks + 8 * lq + 4);
;                     const float xf[8] = {t0.x, t0.y, t0.z, t0.w, t1.x, t1.y, t1.z, t1.w};
;                     acc = __builtin_amdgcn_mfma_f32_16x16x32_bf16(pack8(xf), Chi[ks], acc, 0, 0, 0);
;                 }
; #pragma unroll
;                 for (int reg = 0; reg < 4; ++reg) { const int tok = tokof(s, chunk * 64 + sub * 16 + 4 * lq + reg);
;                     Yb[((size_t)b * TB + tok) * D + g * 16 + l15] = (bf16)f2bf(acc[reg]); }
;                 asm volatile("s_waitcnt lgkmcnt(0)" ::: "memory");
	ds_read_b128 v[216:219], v242 offset:0
	ds_read_b128 v[220:223], v242 offset:64
	ds_read_b128 v[224:227], v242 offset:128
	ds_read_b128 v[228:231], v242 offset:192
	s_waitcnt lgkmcnt(0)
	v_mfma_f32_16x16x32_bf16 v[120:123], v[40:43], v[216:219], 0
	v_mfma_f32_16x16x32_bf16 v[120:123], v[44:47], v[220:223], v[120:123]
	v_mfma_f32_16x16x32_bf16 v[120:123], v[48:51], v[224:227], v[120:123]
	v_mfma_f32_16x16x32_bf16 v[120:123], v[52:55], v[228:231], v[120:123]
	global_load_dwordx4 v[96:99], v238, s[20:21]
	v_add_u32_e32 v238, v238, v243
	s_nop 7
	v_cvt_pk_bf16_f32 v124, v120, v121
	v_cvt_pk_bf16_f32 v125, v122, v123
	s_nop 0
	global_store_dwordx2 v239, v[124:125], s[24:25]
	v_add_u32_e32 v239, v239, v243
	v_mfma_f32_16x16x32_bf16 v[136:139], v[104:107], v[0:3], 0
	v_mfma_f32_16x16x32_bf16 v[140:143], v[104:107], v[4:7], 0
	v_mfma_f32_16x16x32_bf16 v[144:147], v[104:107], v[8:11], 0
	v_mfma_f32_16x16x32_bf16 v[148:151], v[104:107], v[12:15], 0
	v_mfma_f32_16x16x32_bf16 v[152:155], v[104:107], v[16:19], 0
	v_mfma_f32_16x16x32_bf16 v[156:159], v[104:107], v[20:23], 0
	v_mfma_f32_16x16x32_bf16 v[160:163], v[104:107], v[24:27], 0
	v_mfma_f32_16x16x32_bf16 v[164:167], v[104:107], v[28:31], 0
	v_fma_f32 v208, v32, v200, v168
	v_fma_f32 v209, v32, v201, v184
	v_fma_f32 v210, v34, v202, v172
	v_fma_f32 v211, v34, v203, v188
	v_fma_f32 v212, v36, v204, v176
	v_fma_f32 v213, v36, v205, v192
	v_fma_f32 v214, v38, v206, v180
	v_fma_f32 v215, v38, v207, v196
	v_fma_f32 v208, -v33, v201, v208
	v_fma_f32 v209, v33, v200, v209
	v_fma_f32 v210, -v35, v203, v210
	v_fma_f32 v211, v35, v202, v211
	v_fma_f32 v212, -v37, v205, v212
	v_fma_f32 v213, v37, v204, v213
	v_fma_f32 v214, -v39, v207, v214
	v_fma_f32 v215, v39, v206, v215
	v_cvt_pk_bf16_f32 v124, v208, v209
	v_cvt_pk_bf16_f32 v125, v210, v211
	v_cvt_pk_bf16_f32 v126, v212, v213
	v_cvt_pk_bf16_f32 v127, v214, v215
	ds_write_b128 v241, v[124:127] offset:0
	v_fma_f32 v200, v32, v208, v169
	v_fma_f32 v201, v32, v209, v185
	v_fma_f32 v202, v34, v210, v173
	v_fma_f32 v203, v34, v211, v189
	v_fma_f32 v204, v36, v212, v177
	v_fma_f32 v205, v36, v213, v193
	v_fma_f32 v206, v38, v214, v181
	v_fma_f32 v207, v38, v215, v197
	v_fma_f32 v200, -v33, v209, v200
	v_fma_f32 v201, v33, v208, v201
	v_fma_f32 v202, -v35, v211, v202
	v_fma_f32 v203, v35, v210, v203
	v_fma_f32 v204, -v37, v213, v204
	v_fma_f32 v205, v37, v212, v205
	v_fma_f32 v206, -v39, v215, v206
	v_fma_f32 v207, v39, v214, v207
	v_cvt_pk_bf16_f32 v124, v200, v201
	v_cvt_pk_bf16_f32 v125, v202, v203
	v_cvt_pk_bf16_f32 v126, v204, v205
	v_cvt_pk_bf16_f32 v127, v206, v207
	ds_write_b128 v241, v[124:127] offset:256
	v_fma_f32 v208, v32, v200, v170
	v_fma_f32 v209, v32, v201, v186
	v_fma_f32 v210, v34, v202, v174
	v_fma_f32 v211, v34, v203, v190
	v_fma_f32 v212, v36, v204, v178
	v_fma_f32 v213, v36, v205, v194
	v_fma_f32 v214, v38, v206, v182
	v_fma_f32 v215, v38, v207, v198
	v_fma_f32 v208, -v33, v201, v208
	v_fma_f32 v209, v33, v200, v209
	v_fma_f32 v210, -v35, v203, v210
	v_fma_f32 v211, v35, v202, v211
	v_fma_f32 v212, -v37, v205, v212
	v_fma_f32 v213, v37, v204, v213
	v_fma_f32 v214, -v39, v207, v214
	v_fma_f32 v215, v39, v206, v215
	v_cvt_pk_bf16_f32 v124, v208, v209
	v_cvt_pk_bf16_f32 v125, v210, v211
	v_cvt_pk_bf16_f32 v126, v212, v213
	v_cvt_pk_bf16_f32 v127, v214, v215
	ds_write_b128 v241, v[124:127] offset:512
	v_fma_f32 v200, v32, v208, v171
	v_fma_f32 v201, v32, v209, v187
	v_fma_f32 v202, v34, v210, v175
	v_fma_f32 v203, v34, v211, v191
	v_fma_f32 v204, v36, v212, v179
	v_fma_f32 v205, v36, v213, v195
	v_fma_f32 v206, v38, v214, v183
	v_fma_f32 v207, v38, v215, v199
	v_fma_f32 v200, -v33, v209, v200
	v_fma_f32 v201, v33, v208, v201
	v_fma_f32 v202, -v35, v211, v202
	v_fma_f32 v203, v35, v210, v203
	v_fma_f32 v204, -v37, v213, v204
	v_fma_f32 v205, v37, v212, v205
	v_fma_f32 v206, -v39, v215, v206
	v_fma_f32 v207, v39, v214, v207
	v_cvt_pk_bf16_f32 v124, v200, v201
	v_cvt_pk_bf16_f32 v125, v202, v203
	v_cvt_pk_bf16_f32 v126, v204, v205
	v_cvt_pk_bf16_f32 v127, v206, v207
	ds_write_b128 v241, v[124:127] offset:768
	s_waitcnt lgkmcnt(0)
	ds_read_b128 v[216:219], v242 offset:0
	ds_read_b128 v[220:223], v242 offset:64
	ds_read_b128 v[224:227], v242 offset:128
	ds_read_b128 v[228:231], v242 offset:192
	s_waitcnt lgkmcnt(0)
; __device__ __forceinline__ unsigned f2bf(float f) { unsigned u = __builtin_bit_cast(unsigned, f); return (u + 0x7fffu + ((u >> 16) & 1u)) >> 16; }
; __device__ __forceinline__ bf16x8 pack8(const float (&f)[8]) { u32x4 h; h.x = pk2(f[0], f[1]); h.y = pk2(f[2], f[3]); h.z = pk2(f[4], f[5]); h.w = pk2(f[6], f[7]); return __builtin_bit_cast(bf16x8, h); }
; template <bool FINAL> __device__ __forceinline__ void phase_s5_scan(const Fr& F) {
;     ...
; #pragma unroll
;         for (int sub = 0; sub < 4; ++sub) {
;             const bf16x8 A1 = __builtin_bit_cast(bf16x8, uc[sub]);
; #pragma unroll
;             for (int nt = 0; nt < 8; ++nt) {
;                 f32x4 acc = {0.f, 0.f, 0.f, 0.f};
;                 acc = __builtin_amdgcn_mfma_f32_16x16x32_bf16(A1, B1[nt], acc, 0, 0, 0);
; #pragma unroll
;                 for (int reg = 0; reg < 4; ++reg) BUl[(4 * lq + reg) * 132 + 16 * nt + l15] = acc[reg];
;             }
;             asm volatile("s_waitcnt lgkmcnt(0)" ::: "memory");
; #pragma unroll 4
;             for (int jj = 0; jj < 16; ++jj) {
;                 const float br_ = BUl[jj * 132 + lane], bi_ = BUl[jj * 132 + 64 + lane];
;                 const float nr = ar * xr - ai * xi + br_, ni = ar * xi + ai * xr + bi_; xr = nr; xi = ni;
;                 if (FINAL) { BUl[jj * 132 + lane] = xr; BUl[jj * 132 + 64 + lane] = xi; }
;             }
;             if (FINAL) {
;                 asm volatile("s_waitcnt lgkmcnt(0)" ::: "memory");
;                 f32x4 acc = {0.f, 0.f, 0.f, 0.f};
; #pragma unroll
;                 for (int ks = 0; ks < 4; ++ks) {
;                     const f32x4 t0 = *(const f32x4*)(BUl + l15 * 132 + 32 * ks + 8 * lq), t1 = *(const f32x4*)(BUl + l15 * 132 + 32 * ks + 8 * lq + 4);
;                     const float xf[8] = {t0.x, t0.y, t0.z, t0.w, t1.x, t1.y, t1.z, t1.w};
;                     acc = __builtin_amdgcn_mfma_f32_16x16x32_bf16(pack8(xf), Chi[ks], acc, 0, 0, 0);
;                 }
; #pragma unroll
;                 for (int reg = 0; reg < 4; ++reg) { const int tok = tokof(s, chunk * 64 + sub * 16 + 4 * lq + reg);
;                     Yb[((size_t)b * TB + tok) * D + g * 16 + l15] = (bf16)f2bf(acc[reg]); }
;                 asm volatile("s_waitcnt lgkmcnt(0)" ::: "memory");
	v_mfma_f32_16x16x32_bf16 v[120:123], v[40:43], v[216:219], 0
	v_mfma_f32_16x16x32_bf16 v[120:123], v[44:47], v[220:223], v[120:123]
	v_mfma_f32_16x16x32_bf16 v[120:123], v[48:51], v[224:227], v[120:123]
	v_mfma_f32_16x16x32_bf16 v[120:123], v[52:55], v[228:231], v[120:123]
	global_load_dwordx4 v[100:103], v238, s[20:21]
	v_add_u32_e32 v238, v238, v243
	s_nop 7
	v_cvt_pk_bf16_f32 v124, v120, v121
	v_cvt_pk_bf16_f32 v125, v122, v123
	s_nop 0
	global_store_dwordx2 v239, v[124:125], s[24:25]
	v_add_u32_e32 v239, v239, v243
	v_mfma_f32_16x16x32_bf16 v[168:171], v[108:111], v[0:3], 0
	v_mfma_f32_16x16x32_bf16 v[172:175], v[108:111], v[4:7], 0
	v_mfma_f32_16x16x32_bf16 v[176:179], v[108:111], v[8:11], 0
	v_mfma_f32_16x16x32_bf16 v[180:183], v[108:111], v[12:15], 0
	v_mfma_f32_16x16x32_bf16 v[184:187], v[108:111], v[16:19], 0
	v_mfma_f32_16x16x32_bf16 v[188:191], v[108:111], v[20:23], 0
	v_mfma_f32_16x16x32_bf16 v[192:195], v[108:111], v[24:27], 0
	v_mfma_f32_16x16x32_bf16 v[196:199], v[108:111], v[28:31], 0
	v_fma_f32 v208, v32, v200, v136
	v_fma_f32 v209, v32, v201, v152
	v_fma_f32 v210, v34, v202, v140
	v_fma_f32 v211, v34, v203, v156
	v_fma_f32 v212, v36, v204, v144
	v_fma_f32 v213, v36, v205, v160
	v_fma_f32 v214, v38, v206, v148
	v_fma_f32 v215, v38, v207, v164
	v_fma_f32 v208, -v33, v201, v208
	v_fma_f32 v209, v33, v200, v209
	v_fma_f32 v210, -v35, v203, v210
	v_fma_f32 v211, v35, v202, v211
	v_fma_f32 v212, -v37, v205, v212
	v_fma_f32 v213, v37, v204, v213
	v_fma_f32 v214, -v39, v207, v214
	v_fma_f32 v215, v39, v206, v215
	v_cvt_pk_bf16_f32 v124, v208, v209
	v_cvt_pk_bf16_f32 v125, v210, v211
	v_cvt_pk_bf16_f32 v126, v212, v213
	v_cvt_pk_bf16_f32 v127, v214, v215
	ds_write_b128 v241, v[124:127] offset:0
	v_fma_f32 v200, v32, v208, v137
	v_fma_f32 v201, v32, v209, v153
	v_fma_f32 v202, v34, v210, v141
	v_fma_f32 v203, v34, v211, v157
	v_fma_f32 v204, v36, v212, v145
	v_fma_f32 v205, v36, v213, v161
	v_fma_f32 v206, v38, v214, v149
	v_fma_f32 v207, v38, v215, v165
	v_fma_f32 v200, -v33, v209, v200
	v_fma_f32 v201, v33, v208, v201
	v_fma_f32 v202, -v35, v211, v202
	v_fma_f32 v203, v35, v210, v203
	v_fma_f32 v204, -v37, v213, v204
	v_fma_f32 v205, v37, v212, v205
	v_fma_f32 v206, -v39, v215, v206
	v_fma_f32 v207, v39, v214, v207
	v_cvt_pk_bf16_f32 v124, v200, v201
	v_cvt_pk_bf16_f32 v125, v202, v203
	v_cvt_pk_bf16_f32 v126, v204, v205
	v_cvt_pk_bf16_f32 v127, v206, v207
	ds_write_b128 v241, v[124:127] offset:256
	v_fma_f32 v208, v32, v200, v138
	v_fma_f32 v209, v32, v201, v154
	v_fma_f32 v210, v34, v202, v142
	v_fma_f32 v211, v34, v203, v158
	v_fma_f32 v212, v36, v204, v146
	v_fma_f32 v213, v36, v205, v162
	v_fma_f32 v214, v38, v206, v150
	v_fma_f32 v215, v38, v207, v166
	v_fma_f32 v208, -v33, v201, v208
	v_fma_f32 v209, v33, v200, v209
	v_fma_f32 v210, -v35, v203, v210
	v_fma_f32 v211, v35, v202, v211
	v_fma_f32 v212, -v37, v205, v212
	v_fma_f32 v213, v37, v204, v213
	v_fma_f32 v214, -v39, v207, v214
	v_fma_f32 v215, v39, v206, v215
	v_cvt_pk_bf16_f32 v124, v208, v209
	v_cvt_pk_bf16_f32 v125, v210, v211
	v_cvt_pk_bf16_f32 v126, v212, v213
	v_cvt_pk_bf16_f32 v127, v214, v215
	ds_write_b128 v241, v[124:127] offset:512
	v_fma_f32 v200, v32, v208, v139
	v_fma_f32 v201, v32, v209, v155
	v_fma_f32 v202, v34, v210, v143
	v_fma_f32 v203, v34, v211, v159
	v_fma_f32 v204, v36, v212, v147
	v_fma_f32 v205, v36, v213, v163
	v_fma_f32 v206, v38, v214, v151
	v_fma_f32 v207, v38, v215, v167
	v_fma_f32 v200, -v33, v209, v200
	v_fma_f32 v201, v33, v208, v201
	v_fma_f32 v202, -v35, v211, v202
	v_fma_f32 v203, v35, v210, v203
	v_fma_f32 v204, -v37, v213, v204
	v_fma_f32 v205, v37, v212, v205
	v_fma_f32 v206, -v39, v215, v206
	v_fma_f32 v207, v39, v214, v207
	v_cvt_pk_bf16_f32 v124, v200, v201
	v_cvt_pk_bf16_f32 v125, v202, v203
	v_cvt_pk_bf16_f32 v126, v204, v205
	v_cvt_pk_bf16_f32 v127, v206, v207
	ds_write_b128 v241, v[124:127] offset:768
	s_waitcnt lgkmcnt(0)
	ds_read_b128 v[216:219], v242 offset:0
	ds_read_b128 v[220:223], v242 offset:64
	ds_read_b128 v[224:227], v242 offset:128
	ds_read_b128 v[228:231], v242 offset:192
	s_waitcnt lgkmcnt(0)
	v_mfma_f32_16x16x32_bf16 v[120:123], v[40:43], v[216:219], 0
	v_mfma_f32_16x16x32_bf16 v[120:123], v[44:47], v[220:223], v[120:123]
	v_mfma_f32_16x16x32_bf16 v[120:123], v[48:51], v[224:227], v[120:123]
	v_mfma_f32_16x16x32_bf16 v[120:123], v[52:55], v[228:231], v[120:123]
	global_load_dwordx4 v[104:107], v238, s[20:21]
	v_add_u32_e32 v238, v238, v243
	s_nop 7
	v_cvt_pk_bf16_f32 v124, v120, v121
	v_cvt_pk_bf16_f32 v125, v122, v123
	s_nop 0
	global_store_dwordx2 v239, v[124:125], s[24:25]
	v_add_u32_e32 v239, v239, v243
	v_mfma_f32_16x16x32_bf16 v[136:139], v[112:115], v[0:3], 0
	v_mfma_f32_16x16x32_bf16 v[140:143], v[112:115], v[4:7], 0
	v_mfma_f32_16x16x32_bf16 v[144:147], v[112:115], v[8:11], 0
	v_mfma_f32_16x16x32_bf16 v[148:151], v[112:115], v[12:15], 0
	v_mfma_f32_16x16x32_bf16 v[152:155], v[112:115], v[16:19], 0
	v_mfma_f32_16x16x32_bf16 v[156:159], v[112:115], v[20:23], 0
	v_mfma_f32_16x16x32_bf16 v[160:163], v[112:115], v[24:27], 0
	v_mfma_f32_16x16x32_bf16 v[164:167], v[112:115], v[28:31], 0
	v_fma_f32 v208, v32, v200, v168
	v_fma_f32 v209, v32, v201, v184
	v_fma_f32 v210, v34, v202, v172
	v_fma_f32 v211, v34, v203, v188
	v_fma_f32 v212, v36, v204, v176
	v_fma_f32 v213, v36, v205, v192
	v_fma_f32 v214, v38, v206, v180
	v_fma_f32 v215, v38, v207, v196
	v_fma_f32 v208, -v33, v201, v208
	v_fma_f32 v209, v33, v200, v209
	v_fma_f32 v210, -v35, v203, v210
	v_fma_f32 v211, v35, v202, v211
	v_fma_f32 v212, -v37, v205, v212
	v_fma_f32 v213, v37, v204, v213
	v_fma_f32 v214, -v39, v207, v214
	v_fma_f32 v215, v39, v206, v215
; __device__ __forceinline__ unsigned f2bf(float f) { unsigned u = __builtin_bit_cast(unsigned, f); return (u + 0x7fffu + ((u >> 16) & 1u)) >> 16; }
; __device__ __forceinline__ bf16x8 pack8(const float (&f)[8]) { u32x4 h; h.x = pk2(f[0], f[1]); h.y = pk2(f[2], f[3]); h.z = pk2(f[4], f[5]); h.w = pk2(f[6], f[7]); return __builtin_bit_cast(bf16x8, h); }
; template <bool FINAL> __device__ __forceinline__ void phase_s5_scan(const Fr& F) {
;     ...
; #pragma unroll
;         for (int sub = 0; sub < 4; ++sub) {
;             const bf16x8 A1 = __builtin_bit_cast(bf16x8, uc[sub]);
; #pragma unroll
;             for (int nt = 0; nt < 8; ++nt) {
;                 f32x4 acc = {0.f, 0.f, 0.f, 0.f};
;                 acc = __builtin_amdgcn_mfma_f32_16x16x32_bf16(A1, B1[nt], acc, 0, 0, 0);
; #pragma unroll
;                 for (int reg = 0; reg < 4; ++reg) BUl[(4 * lq + reg) * 132 + 16 * nt + l15] = acc[reg];
;             }
;             asm volatile("s_waitcnt lgkmcnt(0)" ::: "memory");
; #pragma unroll 4
;             for (int jj = 0; jj < 16; ++jj) {
;                 const float br_ = BUl[jj * 132 + lane], bi_ = BUl[jj * 132 + 64 + lane];
;                 const float nr = ar * xr - ai * xi + br_, ni = ar * xi + ai * xr + bi_; xr = nr; xi = ni;
;                 if (FINAL) { BUl[jj * 132 + lane] = xr; BUl[jj * 132 + 64 + lane] = xi; }
;             }
;             if (FINAL) {
;                 asm volatile("s_waitcnt lgkmcnt(0)" ::: "memory");
;                 f32x4 acc = {0.f, 0.f, 0.f, 0.f};
; #pragma unroll
;                 for (int ks = 0; ks < 4; ++ks) {
;                     const f32x4 t0 = *(const f32x4*)(BUl + l15 * 132 + 32 * ks + 8 * lq), t1 = *(const f32x4*)(BUl + l15 * 132 + 32 * ks + 8 * lq + 4);
;                     const float xf[8] = {t0.x, t0.y, t0.z, t0.w, t1.x, t1.y, t1.z, t1.w};
;                     acc = __builtin_amdgcn_mfma_f32_16x16x32_bf16(pack8(xf), Chi[ks], acc, 0, 0, 0);
;                 }
; #pragma unroll
;                 for (int reg = 0; reg < 4; ++reg) { const int tok = tokof(s, chunk * 64 + sub * 16 + 4 * lq + reg);
;                     Yb[((size_t)b * TB + tok) * D + g * 16 + l15] = (bf16)f2bf(acc[reg]); }
;                 asm volatile("s_waitcnt lgkmcnt(0)" ::: "memory");
	v_cvt_pk_bf16_f32 v124, v208, v209
	v_cvt_pk_bf16_f32 v125, v210, v211
	v_cvt_pk_bf16_f32 v126, v212, v213
	v_cvt_pk_bf16_f32 v127, v214, v215
	ds_write_b128 v241, v[124:127] offset:0
	v_fma_f32 v200, v32, v208, v169
	v_fma_f32 v201, v32, v209, v185
	v_fma_f32 v202, v34, v210, v173
	v_fma_f32 v203, v34, v211, v189
	v_fma_f32 v204, v36, v212, v177
	v_fma_f32 v205, v36, v213, v193
	v_fma_f32 v206, v38, v214, v181
	v_fma_f32 v207, v38, v215, v197
	v_fma_f32 v200, -v33, v209, v200
	v_fma_f32 v201, v33, v208, v201
	v_fma_f32 v202, -v35, v211, v202
	v_fma_f32 v203, v35, v210, v203
	v_fma_f32 v204, -v37, v213, v204
	v_fma_f32 v205, v37, v212, v205
	v_fma_f32 v206, -v39, v215, v206
	v_fma_f32 v207, v39, v214, v207
	v_cvt_pk_bf16_f32 v124, v200, v201
	v_cvt_pk_bf16_f32 v125, v202, v203
	v_cvt_pk_bf16_f32 v126, v204, v205
	v_cvt_pk_bf16_f32 v127, v206, v207
	ds_write_b128 v241, v[124:127] offset:256
	v_fma_f32 v208, v32, v200, v170
	v_fma_f32 v209, v32, v201, v186
	v_fma_f32 v210, v34, v202, v174
	v_fma_f32 v211, v34, v203, v190
	v_fma_f32 v212, v36, v204, v178
	v_fma_f32 v213, v36, v205, v194
	v_fma_f32 v214, v38, v206, v182
	v_fma_f32 v215, v38, v207, v198
	v_fma_f32 v208, -v33, v201, v208
	v_fma_f32 v209, v33, v200, v209
	v_fma_f32 v210, -v35, v203, v210
	v_fma_f32 v211, v35, v202, v211
	v_fma_f32 v212, -v37, v205, v212
	v_fma_f32 v213, v37, v204, v213
	v_fma_f32 v214, -v39, v207, v214
	v_fma_f32 v215, v39, v206, v215
	v_cvt_pk_bf16_f32 v124, v208, v209
	v_cvt_pk_bf16_f32 v125, v210, v211
	v_cvt_pk_bf16_f32 v126, v212, v213
	v_cvt_pk_bf16_f32 v127, v214, v215
	ds_write_b128 v241, v[124:127] offset:512
	v_fma_f32 v200, v32, v208, v171
	v_fma_f32 v201, v32, v209, v187
	v_fma_f32 v202, v34, v210, v175
	v_fma_f32 v203, v34, v211, v191
	v_fma_f32 v204, v36, v212, v179
	v_fma_f32 v205, v36, v213, v195
	v_fma_f32 v206, v38, v214, v183
	v_fma_f32 v207, v38, v215, v199
	v_fma_f32 v200, -v33, v209, v200
	v_fma_f32 v201, v33, v208, v201
	v_fma_f32 v202, -v35, v211, v202
	v_fma_f32 v203, v35, v210, v203
	v_fma_f32 v204, -v37, v213, v204
	v_fma_f32 v205, v37, v212, v205
	v_fma_f32 v206, -v39, v215, v206
	v_fma_f32 v207, v39, v214, v207
	v_cvt_pk_bf16_f32 v124, v200, v201
	v_cvt_pk_bf16_f32 v125, v202, v203
	v_cvt_pk_bf16_f32 v126, v204, v205
	v_cvt_pk_bf16_f32 v127, v206, v207
	ds_write_b128 v241, v[124:127] offset:768
	s_waitcnt lgkmcnt(0)
	ds_read_b128 v[216:219], v242 offset:0
	ds_read_b128 v[220:223], v242 offset:64
	ds_read_b128 v[224:227], v242 offset:128
	ds_read_b128 v[228:231], v242 offset:192
	s_waitcnt lgkmcnt(0)
	v_mfma_f32_16x16x32_bf16 v[120:123], v[40:43], v[216:219], 0
	v_mfma_f32_16x16x32_bf16 v[120:123], v[44:47], v[220:223], v[120:123]
	v_mfma_f32_16x16x32_bf16 v[120:123], v[48:51], v[224:227], v[120:123]
	v_mfma_f32_16x16x32_bf16 v[120:123], v[52:55], v[228:231], v[120:123]
	global_load_dwordx4 v[108:111], v238, s[20:21]
	v_add_u32_e32 v238, v238, v243
	s_nop 7
	v_cvt_pk_bf16_f32 v124, v120, v121
	v_cvt_pk_bf16_f32 v125, v122, v123
	s_nop 0
	global_store_dwordx2 v239, v[124:125], s[24:25]
	v_add_u32_e32 v239, v239, v243
	v_mfma_f32_16x16x32_bf16 v[168:171], v[116:119], v[0:3], 0
	v_mfma_f32_16x16x32_bf16 v[172:175], v[116:119], v[4:7], 0
	v_mfma_f32_16x16x32_bf16 v[176:179], v[116:119], v[8:11], 0
	v_mfma_f32_16x16x32_bf16 v[180:183], v[116:119], v[12:15], 0
	v_mfma_f32_16x16x32_bf16 v[184:187], v[116:119], v[16:19], 0
	v_mfma_f32_16x16x32_bf16 v[188:191], v[116:119], v[20:23], 0
	v_mfma_f32_16x16x32_bf16 v[192:195], v[116:119], v[24:27], 0
	v_mfma_f32_16x16x32_bf16 v[196:199], v[116:119], v[28:31], 0
	v_fma_f32 v208, v32, v200, v136
	v_fma_f32 v209, v32, v201, v152
	v_fma_f32 v210, v34, v202, v140
	v_fma_f32 v211, v34, v203, v156
	v_fma_f32 v212, v36, v204, v144
	v_fma_f32 v213, v36, v205, v160
	v_fma_f32 v214, v38, v206, v148
	v_fma_f32 v215, v38, v207, v164
	v_fma_f32 v208, -v33, v201, v208
	v_fma_f32 v209, v33, v200, v209
	v_fma_f32 v210, -v35, v203, v210
	v_fma_f32 v211, v35, v202, v211
	v_fma_f32 v212, -v37, v205, v212
	v_fma_f32 v213, v37, v204, v213
	v_fma_f32 v214, -v39, v207, v214
	v_fma_f32 v215, v39, v206, v215
	v_cvt_pk_bf16_f32 v124, v208, v209
	v_cvt_pk_bf16_f32 v125, v210, v211
	v_cvt_pk_bf16_f32 v126, v212, v213
	v_cvt_pk_bf16_f32 v127, v214, v215
	ds_write_b128 v241, v[124:127] offset:0
	v_fma_f32 v200, v32, v208, v137
	v_fma_f32 v201, v32, v209, v153
	v_fma_f32 v202, v34, v210, v141
	v_fma_f32 v203, v34, v211, v157
	v_fma_f32 v204, v36, v212, v145
	v_fma_f32 v205, v36, v213, v161
	v_fma_f32 v206, v38, v214, v149
	v_fma_f32 v207, v38, v215, v165
	v_fma_f32 v200, -v33, v209, v200
	v_fma_f32 v201, v33, v208, v201
	v_fma_f32 v202, -v35, v211, v202
	v_fma_f32 v203, v35, v210, v203
	v_fma_f32 v204, -v37, v213, v204
	v_fma_f32 v205, v37, v212, v205
	v_fma_f32 v206, -v39, v215, v206
	v_fma_f32 v207, v39, v214, v207
	v_cvt_pk_bf16_f32 v124, v200, v201
	v_cvt_pk_bf16_f32 v125, v202, v203
	v_cvt_pk_bf16_f32 v126, v204, v205
	v_cvt_pk_bf16_f32 v127, v206, v207
	ds_write_b128 v241, v[124:127] offset:256
	v_fma_f32 v208, v32, v200, v138
	v_fma_f32 v209, v32, v201, v154
	v_fma_f32 v210, v34, v202, v142
	v_fma_f32 v211, v34, v203, v158
	v_fma_f32 v212, v36, v204, v146
	v_fma_f32 v213, v36, v205, v162
	v_fma_f32 v214, v38, v206, v150
	v_fma_f32 v215, v38, v207, v166
	v_fma_f32 v208, -v33, v201, v208
	v_fma_f32 v209, v33, v200, v209
	v_fma_f32 v210, -v35, v203, v210
	v_fma_f32 v211, v35, v202, v211
	v_fma_f32 v212, -v37, v205, v212
	v_fma_f32 v213, v37, v204, v213
	v_fma_f32 v214, -v39, v207, v214
	v_fma_f32 v215, v39, v206, v215
	v_cvt_pk_bf16_f32 v124, v208, v209
	v_cvt_pk_bf16_f32 v125, v210, v211
	v_cvt_pk_bf16_f32 v126, v212, v213
	v_cvt_pk_bf16_f32 v127, v214, v215
	ds_write_b128 v241, v[124:127] offset:512
	v_fma_f32 v200, v32, v208, v139
	v_fma_f32 v201, v32, v209, v155
	v_fma_f32 v202, v34, v210, v143
	v_fma_f32 v203, v34, v211, v159
	v_fma_f32 v204, v36, v212, v147
	v_fma_f32 v205, v36, v213, v163
	v_fma_f32 v206, v38, v214, v151
	v_fma_f32 v207, v38, v215, v167
	v_fma_f32 v200, -v33, v209, v200
	v_fma_f32 v201, v33, v208, v201
	v_fma_f32 v202, -v35, v211, v202
	v_fma_f32 v203, v35, v210, v203
	v_fma_f32 v204, -v37, v213, v204
	v_fma_f32 v205, v37, v212, v205
	v_fma_f32 v206, -v39, v215, v206
	v_fma_f32 v207, v39, v214, v207
	v_cvt_pk_bf16_f32 v124, v200, v201
	v_cvt_pk_bf16_f32 v125, v202, v203
	v_cvt_pk_bf16_f32 v126, v204, v205
	v_cvt_pk_bf16_f32 v127, v206, v207
	ds_write_b128 v241, v[124:127] offset:768
	s_waitcnt lgkmcnt(0)
; __device__ __forceinline__ unsigned f2bf(float f) { unsigned u = __builtin_bit_cast(unsigned, f); return (u + 0x7fffu + ((u >> 16) & 1u)) >> 16; }
; __device__ __forceinline__ bf16x8 pack8(const float (&f)[8]) { u32x4 h; h.x = pk2(f[0], f[1]); h.y = pk2(f[2], f[3]); h.z = pk2(f[4], f[5]); h.w = pk2(f[6], f[7]); return __builtin_bit_cast(bf16x8, h); }
; template <bool FINAL> __device__ __forceinline__ void phase_s5_scan(const Fr& F) {
;     ...
; #pragma unroll
;         for (int sub = 0; sub < 4; ++sub) {
;             const bf16x8 A1 = __builtin_bit_cast(bf16x8, uc[sub]);
; #pragma unroll
;             for (int nt = 0; nt < 8; ++nt) {
;                 f32x4 acc = {0.f, 0.f, 0.f, 0.f};
;                 acc = __builtin_amdgcn_mfma_f32_16x16x32_bf16(A1, B1[nt], acc, 0, 0, 0);
; #pragma unroll
;                 for (int reg = 0; reg < 4; ++reg) BUl[(4 * lq + reg) * 132 + 16 * nt + l15] = acc[reg];
;             }
;             asm volatile("s_waitcnt lgkmcnt(0)" ::: "memory");
; #pragma unroll 4
;             for (int jj = 0; jj < 16; ++jj) {
;                 const float br_ = BUl[jj * 132 + lane], bi_ = BUl[jj * 132 + 64 + lane];
;                 const float nr = ar * xr - ai * xi + br_, ni = ar * xi + ai * xr + bi_; xr = nr; xi = ni;
;                 if (FINAL) { BUl[jj * 132 + lane] = xr; BUl[jj * 132 + 64 + lane] = xi; }
;             }
;             if (FINAL) {
;                 asm volatile("s_waitcnt lgkmcnt(0)" ::: "memory");
;                 f32x4 acc = {0.f, 0.f, 0.f, 0.f};
; #pragma unroll
;                 for (int ks = 0; ks < 4; ++ks) {
;                     const f32x4 t0 = *(const f32x4*)(BUl + l15 * 132 + 32 * ks + 8 * lq), t1 = *(const f32x4*)(BUl + l15 * 132 + 32 * ks + 8 * lq + 4);
;                     const float xf[8] = {t0.x, t0.y, t0.z, t0.w, t1.x, t1.y, t1.z, t1.w};
;                     acc = __builtin_amdgcn_mfma_f32_16x16x32_bf16(pack8(xf), Chi[ks], acc, 0, 0, 0);
;                 }
; #pragma unroll
;                 for (int reg = 0; reg < 4; ++reg) { const int tok = tokof(s, chunk * 64 + sub * 16 + 4 * lq + reg);
;                     Yb[((size_t)b * TB + tok) * D + g * 16 + l15] = (bf16)f2bf(acc[reg]); }
;                 asm volatile("s_waitcnt lgkmcnt(0)" ::: "memory");
;             }
;         }
;         if (!FINAL) { float* e = E + ((size_t)task * 64 + lane) * 2; e[0] = xr; e[1] = xi; }
;     }
	ds_read_b128 v[216:219], v242 offset:0
	ds_read_b128 v[220:223], v242 offset:64
	ds_read_b128 v[224:227], v242 offset:128
	ds_read_b128 v[228:231], v242 offset:192
	s_waitcnt lgkmcnt(0)
	v_mfma_f32_16x16x32_bf16 v[120:123], v[40:43], v[216:219], 0
	v_mfma_f32_16x16x32_bf16 v[120:123], v[44:47], v[220:223], v[120:123]
	v_mfma_f32_16x16x32_bf16 v[120:123], v[48:51], v[224:227], v[120:123]
	v_mfma_f32_16x16x32_bf16 v[120:123], v[52:55], v[228:231], v[120:123]
	global_load_dwordx4 v[112:115], v238, s[20:21]
	v_add_u32_e32 v238, v238, v243
	s_nop 7
	v_cvt_pk_bf16_f32 v124, v120, v121
	v_cvt_pk_bf16_f32 v125, v122, v123
	s_nop 0
	global_store_dwordx2 v239, v[124:125], s[24:25]
	v_add_u32_e32 v239, v239, v243
	v_fma_f32 v208, v32, v200, v168
	v_fma_f32 v209, v32, v201, v184
	v_fma_f32 v210, v34, v202, v172
	v_fma_f32 v211, v34, v203, v188
	v_fma_f32 v212, v36, v204, v176
	v_fma_f32 v213, v36, v205, v192
	v_fma_f32 v214, v38, v206, v180
	v_fma_f32 v215, v38, v207, v196
	v_fma_f32 v208, -v33, v201, v208
	v_fma_f32 v209, v33, v200, v209
	v_fma_f32 v210, -v35, v203, v210
	v_fma_f32 v211, v35, v202, v211
	v_fma_f32 v212, -v37, v205, v212
	v_fma_f32 v213, v37, v204, v213
	v_fma_f32 v214, -v39, v207, v214
	v_fma_f32 v215, v39, v206, v215
	v_cvt_pk_bf16_f32 v124, v208, v209
	v_cvt_pk_bf16_f32 v125, v210, v211
	v_cvt_pk_bf16_f32 v126, v212, v213
	v_cvt_pk_bf16_f32 v127, v214, v215
	ds_write_b128 v241, v[124:127] offset:0
	v_fma_f32 v200, v32, v208, v169
	v_fma_f32 v201, v32, v209, v185
	v_fma_f32 v202, v34, v210, v173
	v_fma_f32 v203, v34, v211, v189
	v_fma_f32 v204, v36, v212, v177
	v_fma_f32 v205, v36, v213, v193
	v_fma_f32 v206, v38, v214, v181
	v_fma_f32 v207, v38, v215, v197
	v_fma_f32 v200, -v33, v209, v200
	v_fma_f32 v201, v33, v208, v201
	v_fma_f32 v202, -v35, v211, v202
	v_fma_f32 v203, v35, v210, v203
	v_fma_f32 v204, -v37, v213, v204
	v_fma_f32 v205, v37, v212, v205
	v_fma_f32 v206, -v39, v215, v206
	v_fma_f32 v207, v39, v214, v207
	v_cvt_pk_bf16_f32 v124, v200, v201
	v_cvt_pk_bf16_f32 v125, v202, v203
	v_cvt_pk_bf16_f32 v126, v204, v205
	v_cvt_pk_bf16_f32 v127, v206, v207
	ds_write_b128 v241, v[124:127] offset:256
	v_fma_f32 v208, v32, v200, v170
	v_fma_f32 v209, v32, v201, v186
	v_fma_f32 v210, v34, v202, v174
	v_fma_f32 v211, v34, v203, v190
	v_fma_f32 v212, v36, v204, v178
	v_fma_f32 v213, v36, v205, v194
	v_fma_f32 v214, v38, v206, v182
	v_fma_f32 v215, v38, v207, v198
	v_fma_f32 v208, -v33, v201, v208
	v_fma_f32 v209, v33, v200, v209
	v_fma_f32 v210, -v35, v203, v210
	v_fma_f32 v211, v35, v202, v211
	v_fma_f32 v212, -v37, v205, v212
	v_fma_f32 v213, v37, v204, v213
	v_fma_f32 v214, -v39, v207, v214
	v_fma_f32 v215, v39, v206, v215
	v_cvt_pk_bf16_f32 v124, v208, v209
	v_cvt_pk_bf16_f32 v125, v210, v211
	v_cvt_pk_bf16_f32 v126, v212, v213
	v_cvt_pk_bf16_f32 v127, v214, v215
	ds_write_b128 v241, v[124:127] offset:512
	v_fma_f32 v200, v32, v208, v171
	v_fma_f32 v201, v32, v209, v187
	v_fma_f32 v202, v34, v210, v175
	v_fma_f32 v203, v34, v211, v191
	v_fma_f32 v204, v36, v212, v179
	v_fma_f32 v205, v36, v213, v195
	v_fma_f32 v206, v38, v214, v183
	v_fma_f32 v207, v38, v215, v199
	v_fma_f32 v200, -v33, v209, v200
	v_fma_f32 v201, v33, v208, v201
	v_fma_f32 v202, -v35, v211, v202
	v_fma_f32 v203, v35, v210, v203
	v_fma_f32 v204, -v37, v213, v204
	v_fma_f32 v205, v37, v212, v205
	v_fma_f32 v206, -v39, v215, v206
	v_fma_f32 v207, v39, v214, v207
	v_cvt_pk_bf16_f32 v124, v200, v201
	v_cvt_pk_bf16_f32 v125, v202, v203
	v_cvt_pk_bf16_f32 v126, v204, v205
	v_cvt_pk_bf16_f32 v127, v206, v207
	ds_write_b128 v241, v[124:127] offset:768
	s_waitcnt lgkmcnt(0)
	ds_read_b128 v[216:219], v242 offset:0
	ds_read_b128 v[220:223], v242 offset:64
	ds_read_b128 v[224:227], v242 offset:128
	ds_read_b128 v[228:231], v242 offset:192
	s_waitcnt lgkmcnt(0)
	v_mfma_f32_16x16x32_bf16 v[120:123], v[40:43], v[216:219], 0
	v_mfma_f32_16x16x32_bf16 v[120:123], v[44:47], v[220:223], v[120:123]
	v_mfma_f32_16x16x32_bf16 v[120:123], v[48:51], v[224:227], v[120:123]
	v_mfma_f32_16x16x32_bf16 v[120:123], v[52:55], v[228:231], v[120:123]
	global_load_dwordx4 v[116:119], v238, s[20:21]
	v_add_u32_e32 v238, v238, v243
	s_nop 7
	v_cvt_pk_bf16_f32 v124, v120, v121
	v_cvt_pk_bf16_f32 v125, v122, v123
	s_nop 0
	global_store_dwordx2 v239, v[124:125], s[24:25]
	v_add_u32_e32 v239, v239, v243
	s_add_i32 s14, s14, 16
	s_add_i32 s19, s19, 1
	s_cmp_lt_u32 s19, s56
	s_cbranch_scc1 .Ls5b_grp
	s_waitcnt vmcnt(0) lgkmcnt(0)
	v_mov_b32_e32 v2, s34
	v_mov_b32_e32 v3, s35
